# v63 + P12 pass loop leaves the unrolled compare body after the last register holding valid keys (test every 8 registers)
# baseline (speedup 1.0000x reference)
; DI size_t sc_row_off(int b, int s) { const int qb = s >> 7; return ((size_t)(b * 2080 + ((qb * (qb + 1)) >> 1))) * 16384 + (size_t)(s & 127) * ((qb + 1) * 128); }
; DI unsigned f2key(float f) { const unsigned u = __float_as_uint(f); return (u & 0x80000000u) ? ~u : (u | 0x80000000u); }
; template <int NV>
; DI void topk_row(const float* row, int s, LAS int* lst, int lane) {
;     ...
;     { const unsigned long long ra = (unsigned long long)row; const unsigned rlo = __builtin_amdgcn_readfirstlane((unsigned)ra), rhi = __builtin_amdgcn_readfirstlane((unsigned)(ra >> 32));
;       row = (const float*)(((unsigned long long)rhi << 32) | rlo); }
; #pragma unroll
;     for (int jo = 0; jo < NV / 16; ++jo) { const float* rb = row + jo * 1024;
; #pragma unroll
;         for (int ji = 0; ji < 16; ++ji) { const int j = jo * 16 + ji; const unsigned u = f2key(rb[ji * 64 + lane]); key[j] = (j * 64 + lane <= s) ? u : 0u; } }
; DI void topk_phase(const float* SC, unsigned short* IDX, LAS unsigned char* lds, int tid, int bid, int G) {
;     ...
;             const float* row = SC + sc_row_off(b, s);
;             if (s < 2048) topk_row<32>(row, s, lst, lane);
;             else if (s < 4096) topk_row<64>(row, s, lst, lane);
;             else if (s < 6144) topk_row<96>(row, s, lst, lane);
;             else topk_row<128>(row, s, lst, lane);
.LBB0_1965:
	s_lshr_b32 s1, s85, 7
	s_add_i32 s2, s1, 1
	s_ashr_i32 s0, s8, 13
	s_mul_i32 s1, s2, s1
	s_mulk_i32 s0, 0x820
	s_lshr_b32 s1, s1, 1
	s_add_i32 s0, s1, s0
	s_ashr_i32 s1, s0, 31
	s_lshl_b32 s3, s8, 7
	s_and_b32 s3, s3, 0x3f80
	s_lshl_b64 s[0:1], s[0:1], 16
	s_mul_i32 s2, s2, s3
	s_add_u32 s0, s14, s0
	s_addc_u32 s1, s15, s1
	s_lshl_b32 s2, s2, 2
	s_add_u32 s12, s0, s2
	s_addc_u32 s13, s1, 0
	s_cmpk_gt_u32 s85, 0x7ff
	v_sub_u32_e32 v161, s85, v2
	s_cbranch_scc0 .LBB0_2481
	s_cmpk_gt_u32 s85, 0xfff
	s_cbranch_scc0 .LBB0_2482
	s_cmpk_gt_u32 s85, 0x17ff
	s_cbranch_scc0 .LBB0_2483
	v_lshlrev_b32_e32 v0, 2, v2
	v_lshl_add_u64 v[40:41], s[12:13], 0, v[0:1]
	flat_load_dword v48, v[40:41]
	flat_load_dword v49, v[40:41] offset:256
	flat_load_dword v50, v[40:41] offset:512
	flat_load_dword v51, v[40:41] offset:768
	flat_load_dword v52, v[40:41] offset:1024
	flat_load_dword v53, v[40:41] offset:1280
	flat_load_dword v54, v[40:41] offset:1536
	flat_load_dword v55, v[40:41] offset:1792
	flat_load_dword v56, v[40:41] offset:2048
	flat_load_dword v57, v[40:41] offset:2304
	flat_load_dword v58, v[40:41] offset:2560
	flat_load_dword v59, v[40:41] offset:2816
	flat_load_dword v60, v[40:41] offset:3072
	flat_load_dword v128, v[40:41] offset:3328
	flat_load_dword v129, v[40:41] offset:3584
	flat_load_dword v130, v[40:41] offset:3840
	s_add_u32 s0, s12, 0x1000
	s_addc_u32 s1, s13, 0
	v_lshlrev_b32_e32 v38, 2, v4
	v_mov_b32_e32 v39, v1
	v_lshlrev_b32_e32 v36, 2, v6
	v_mov_b32_e32 v37, v1
	v_lshlrev_b32_e32 v34, 2, v8
	v_mov_b32_e32 v35, v1
	v_lshl_add_u64 v[40:41], s[0:1], 0, v[0:1]
	v_lshl_add_u64 v[42:43], s[0:1], 0, v[38:39]
	v_lshl_add_u64 v[44:45], s[0:1], 0, v[36:37]
	v_lshl_add_u64 v[46:47], s[0:1], 0, v[34:35]
	flat_load_dword v131, v[40:41]
	flat_load_dword v162, v[42:43]
	flat_load_dword v164, v[44:45]
	flat_load_dword v165, v[46:47]
	s_movk_i32 s2, 0x17ff
	s_waitcnt vmcnt(0) lgkmcnt(0)
	v_not_b32_e32 v40, v48
	v_or_b32_e32 v41, 0x80000000, v48
	v_cmp_gt_i32_e32 vcc, 0, v48
	v_not_b32_e32 v42, v49
	v_or_b32_e32 v43, 0x80000000, v49
	v_cndmask_b32_e32 v141, v41, v40, vcc
	v_cmp_gt_i32_e32 vcc, 0, v49
	v_not_b32_e32 v44, v50
	v_or_b32_e32 v45, 0x80000000, v50
	v_cndmask_b32_e32 v140, v43, v42, vcc
	v_cmp_gt_i32_e32 vcc, 0, v50
	v_not_b32_e32 v46, v51
	v_or_b32_e32 v47, 0x80000000, v51
	v_cndmask_b32_e32 v139, v45, v44, vcc
	v_cmp_gt_i32_e32 vcc, 0, v51
	v_not_b32_e32 v61, v52
	v_or_b32_e32 v62, 0x80000000, v52
	v_cndmask_b32_e32 v138, v47, v46, vcc
	v_cmp_gt_i32_e32 vcc, 0, v52
	v_not_b32_e32 v63, v53
	v_or_b32_e32 v132, 0x80000000, v53
	v_cndmask_b32_e32 v137, v62, v61, vcc
	v_cmp_gt_i32_e32 vcc, 0, v53
	v_not_b32_e32 v133, v54
	v_or_b32_e32 v134, 0x80000000, v54
	v_cndmask_b32_e32 v136, v132, v63, vcc
	v_cmp_gt_i32_e32 vcc, 0, v54
	v_not_b32_e32 v163, v55
	v_or_b32_e32 v166, 0x80000000, v55
	v_cndmask_b32_e32 v135, v134, v133, vcc
	v_cmp_gt_i32_e32 vcc, 0, v55
	v_not_b32_e32 v167, v56
	v_or_b32_e32 v168, 0x80000000, v56
	v_cndmask_b32_e32 v134, v166, v163, vcc
	v_cmp_gt_i32_e32 vcc, 0, v56
	v_not_b32_e32 v169, v57
	v_or_b32_e32 v170, 0x80000000, v57
	v_cndmask_b32_e32 v133, v168, v167, vcc
	v_cmp_gt_i32_e32 vcc, 0, v57
	v_not_b32_e32 v171, v58
	v_or_b32_e32 v172, 0x80000000, v58
	v_cndmask_b32_e32 v132, v170, v169, vcc
	v_cmp_gt_i32_e32 vcc, 0, v58
	v_not_b32_e32 v173, v59
	v_or_b32_e32 v174, 0x80000000, v59
	v_cndmask_b32_e32 v251, v172, v171, vcc
	v_cmp_gt_i32_e32 vcc, 0, v59
	v_lshlrev_b32_e32 v62, 2, v10
	v_mov_b32_e32 v63, v1
	v_not_b32_e32 v175, v60
	v_or_b32_e32 v176, 0x80000000, v60
	v_cndmask_b32_e32 v248, v174, v173, vcc
	v_lshl_add_u64 v[40:41], s[0:1], 0, v[62:63]
	v_cmp_gt_i32_e32 vcc, 0, v60
	v_lshlrev_b32_e32 v60, 2, v12
	v_mov_b32_e32 v61, v1
	flat_load_dword v166, v[40:41]
	v_lshl_add_u64 v[40:41], s[0:1], 0, v[60:61]
	flat_load_dword v167, v[40:41]
	v_lshlrev_b32_e32 v58, 2, v14
	v_mov_b32_e32 v59, v1
	v_lshl_add_u64 v[40:41], s[0:1], 0, v[58:59]
	flat_load_dword v168, v[40:41]
	v_lshlrev_b32_e32 v56, 2, v16
	v_mov_b32_e32 v57, v1
	v_lshl_add_u64 v[40:41], s[0:1], 0, v[56:57]
	flat_load_dword v169, v[40:41]
	v_lshlrev_b32_e32 v52, 2, v18
	v_mov_b32_e32 v53, v1
	v_cndmask_b32_e32 v247, v176, v175, vcc
	v_not_b32_e32 v42, v128
	v_or_b32_e32 v43, 0x80000000, v128
	v_cmp_gt_i32_e32 vcc, 0, v128
	v_lshl_add_u64 v[40:41], s[0:1], 0, v[52:53]
	flat_load_dword v170, v[40:41]
	v_cndmask_b32_e32 v253, v43, v42, vcc
	v_not_b32_e32 v42, v129
	v_or_b32_e32 v40, 0x80000000, v129
	v_cmp_gt_i32_e32 vcc, 0, v129
	v_lshlrev_b32_e32 v54, 2, v20
	v_mov_b32_e32 v55, v1
	v_cndmask_b32_e32 v249, v40, v42, vcc
	v_lshl_add_u64 v[40:41], s[0:1], 0, v[54:55]
	flat_load_dword v171, v[40:41]
	v_lshlrev_b32_e32 v50, 2, v22
	v_mov_b32_e32 v51, v1
	v_lshl_add_u64 v[40:41], s[0:1], 0, v[50:51]
	flat_load_dword v172, v[40:41]
	v_lshlrev_b32_e32 v48, 2, v24
	v_mov_b32_e32 v49, v1
	v_lshl_add_u64 v[40:41], s[0:1], 0, v[48:49]
	flat_load_dword v173, v[40:41]
	v_lshlrev_b32_e32 v46, 2, v26
	v_mov_b32_e32 v47, v1
	v_lshl_add_u64 v[40:41], s[0:1], 0, v[46:47]
	flat_load_dword v174, v[40:41]
	v_lshlrev_b32_e32 v44, 2, v28
	v_mov_b32_e32 v45, v1
	v_lshl_add_u64 v[40:41], s[0:1], 0, v[44:45]
	flat_load_dword v175, v[40:41]
	v_not_b32_e32 v42, v130
	v_or_b32_e32 v43, 0x80000000, v130
	v_cmp_gt_i32_e32 vcc, 0, v130
	v_not_b32_e32 v129, v162
	v_or_b32_e32 v130, 0x80000000, v162
	v_cndmask_b32_e32 v252, v43, v42, vcc
	v_not_b32_e32 v42, v131
	v_or_b32_e32 v43, 0x80000000, v131
	v_cmp_gt_i32_e32 vcc, 0, v131
	v_or_b32_e32 v131, 0x80000000, v164
	s_nop 0
	v_cndmask_b32_e32 v128, v43, v42, vcc
	v_lshlrev_b32_e32 v42, 2, v30
	v_mov_b32_e32 v43, v1
	v_lshl_add_u64 v[40:41], s[0:1], 0, v[42:43]
	flat_load_dword v176, v[40:41]
	v_lshlrev_b32_e32 v40, 2, v32
	v_mov_b32_e32 v41, v1
	v_cmp_gt_i32_e32 vcc, 0, v162
	v_lshl_add_u64 v[162:163], s[0:1], 0, v[40:41]
	s_add_u32 s0, s12, 0x2000
	flat_load_dword v177, v[162:163]
	s_addc_u32 s1, s13, 0
	v_lshl_add_u64 v[162:163], s[0:1], 0, v[0:1]
	v_cndmask_b32_e32 v130, v130, v129, vcc
	v_not_b32_e32 v129, v164
	flat_load_dword v178, v[162:163]
	v_cmp_gt_i32_e32 vcc, 0, v164
	v_or_b32_e32 v164, 0x80000000, v165
	v_lshl_add_u64 v[162:163], s[0:1], 0, v[38:39]
	v_cndmask_b32_e32 v131, v131, v129, vcc
	v_not_b32_e32 v129, v165
	v_cmp_gt_i32_e32 vcc, 0, v165
	flat_load_dword v179, v[162:163]
	v_lshl_add_u64 v[162:163], s[0:1], 0, v[36:37]
	v_cndmask_b32_e32 v129, v164, v129, vcc
	s_waitcnt vmcnt(0) lgkmcnt(0)
; DI unsigned f2key(float f) { const unsigned u = __float_as_uint(f); return (u & 0x80000000u) ? ~u : (u | 0x80000000u); }
; template <int NV>
; DI void topk_row(const float* row, int s, LAS int* lst, int lane) {
;     ...
;     for (int jo = 0; jo < NV / 16; ++jo) { const float* rb = row + jo * 1024;
; #pragma unroll
;         for (int ji = 0; ji < 16; ++ji) { const int j = jo * 16 + ji; const unsigned u = f2key(rb[ji * 64 + lane]); key[j] = (j * 64 + lane <= s) ? u : 0u; } }
	v_not_b32_e32 v164, v166
	v_or_b32_e32 v165, 0x80000000, v166
	v_cmp_gt_i32_e32 vcc, 0, v166
	flat_load_dword v180, v[162:163]
	v_not_b32_e32 v162, v167
	v_cndmask_b32_e32 v250, v165, v164, vcc
	v_or_b32_e32 v163, 0x80000000, v167
	v_cmp_gt_i32_e32 vcc, 0, v167
	v_not_b32_e32 v164, v168
	s_nop 0
	v_cndmask_b32_e32 v246, v163, v162, vcc
	v_lshl_add_u64 v[162:163], s[0:1], 0, v[34:35]
	flat_load_dword v165, v[162:163]
	v_or_b32_e32 v162, 0x80000000, v168
	v_cmp_gt_i32_e32 vcc, 0, v168
	v_or_b32_e32 v168, 0x80000000, v170
	s_nop 0
	v_cndmask_b32_e32 v245, v162, v164, vcc
	v_lshl_add_u64 v[162:163], s[0:1], 0, v[62:63]
	v_not_b32_e32 v164, v169
	flat_load_dword v166, v[162:163]
	v_or_b32_e32 v162, 0x80000000, v169
	v_cmp_gt_i32_e32 vcc, 0, v169
	s_nop 1
	v_cndmask_b32_e32 v244, v162, v164, vcc
	v_lshl_add_u64 v[162:163], s[0:1], 0, v[60:61]
	flat_load_dword v167, v[162:163]
	v_lshl_add_u64 v[162:163], s[0:1], 0, v[58:59]
	flat_load_dword v169, v[162:163]
	v_lshl_add_u64 v[162:163], s[0:1], 0, v[56:57]
	v_not_b32_e32 v164, v170
	v_cmp_gt_i32_e32 vcc, 0, v170
	flat_load_dword v170, v[162:163]
	v_lshl_add_u64 v[162:163], s[0:1], 0, v[52:53]
	v_cndmask_b32_e32 v243, v168, v164, vcc
	v_not_b32_e32 v164, v171
	v_or_b32_e32 v168, 0x80000000, v171
	v_cmp_gt_i32_e32 vcc, 0, v171
	flat_load_dword v171, v[162:163]
	v_lshl_add_u64 v[162:163], s[0:1], 0, v[54:55]
	v_cndmask_b32_e32 v242, v168, v164, vcc
	v_not_b32_e32 v164, v172
	v_or_b32_e32 v168, 0x80000000, v172
	v_cmp_gt_i32_e32 vcc, 0, v172
	flat_load_dword v172, v[162:163]
	v_lshl_add_u64 v[162:163], s[0:1], 0, v[50:51]
	v_cndmask_b32_e32 v241, v168, v164, vcc
	v_not_b32_e32 v164, v173
	v_or_b32_e32 v168, 0x80000000, v173
	v_cmp_gt_i32_e32 vcc, 0, v173
	flat_load_dword v173, v[162:163]
	v_lshl_add_u64 v[162:163], s[0:1], 0, v[48:49]
	v_cndmask_b32_e32 v240, v168, v164, vcc
	v_not_b32_e32 v164, v174
	v_or_b32_e32 v168, 0x80000000, v174
	v_cmp_gt_i32_e32 vcc, 0, v174
	flat_load_dword v174, v[162:163]
	v_lshl_add_u64 v[162:163], s[0:1], 0, v[46:47]
	v_cndmask_b32_e32 v239, v168, v164, vcc
	v_not_b32_e32 v164, v175
	v_or_b32_e32 v168, 0x80000000, v175
	v_cmp_gt_i32_e32 vcc, 0, v175
	flat_load_dword v175, v[162:163]
	v_lshl_add_u64 v[162:163], s[0:1], 0, v[44:45]
	v_cndmask_b32_e32 v238, v168, v164, vcc
	v_not_b32_e32 v164, v176
	v_or_b32_e32 v168, 0x80000000, v176
	v_cmp_gt_i32_e32 vcc, 0, v176
	flat_load_dword v176, v[162:163]
	v_lshl_add_u64 v[162:163], s[0:1], 0, v[42:43]
	v_cndmask_b32_e32 v237, v168, v164, vcc
	v_not_b32_e32 v164, v177
	v_or_b32_e32 v168, 0x80000000, v177
	v_cmp_gt_i32_e32 vcc, 0, v177
	flat_load_dword v177, v[162:163]
	v_lshl_add_u64 v[162:163], s[0:1], 0, v[40:41]
	v_cndmask_b32_e32 v236, v168, v164, vcc
	v_not_b32_e32 v164, v178
	v_or_b32_e32 v168, 0x80000000, v178
	v_cmp_gt_i32_e32 vcc, 0, v178
	flat_load_dword v178, v[162:163]
	s_add_u32 s0, s12, 0x3000
	s_addc_u32 s1, s13, 0
	v_cndmask_b32_e32 v235, v168, v164, vcc
	v_not_b32_e32 v164, v179
	v_or_b32_e32 v168, 0x80000000, v179
	v_cmp_gt_i32_e32 vcc, 0, v179
	v_lshl_add_u64 v[162:163], s[0:1], 0, v[0:1]
	s_waitcnt vmcnt(0) lgkmcnt(0)
	v_or_b32_e32 v179, 0x80000000, v165
	v_cndmask_b32_e32 v234, v168, v164, vcc
	flat_load_dword v168, v[162:163]
	v_not_b32_e32 v164, v180
	v_or_b32_e32 v162, 0x80000000, v180
	v_cmp_gt_i32_e32 vcc, 0, v180
	s_nop 1
	v_cndmask_b32_e32 v233, v162, v164, vcc
	v_not_b32_e32 v164, v165
	v_lshl_add_u64 v[162:163], s[0:1], 0, v[38:39]
	v_cmp_gt_i32_e32 vcc, 0, v165
	flat_load_dword v180, v[162:163]
	v_or_b32_e32 v165, 0x80000000, v166
	v_cndmask_b32_e32 v232, v179, v164, vcc
	v_not_b32_e32 v164, v166
	v_lshl_add_u64 v[162:163], s[0:1], 0, v[36:37]
	v_cmp_gt_i32_e32 vcc, 0, v166
	flat_load_dword v179, v[162:163]
	v_not_b32_e32 v162, v167
	v_cndmask_b32_e32 v231, v165, v164, vcc
	v_or_b32_e32 v163, 0x80000000, v167
	v_cmp_gt_i32_e32 vcc, 0, v167
	v_not_b32_e32 v164, v169
	s_nop 0
	v_cndmask_b32_e32 v230, v163, v162, vcc
	v_lshl_add_u64 v[162:163], s[0:1], 0, v[34:35]
	flat_load_dword v165, v[162:163]
	v_or_b32_e32 v162, 0x80000000, v169
	v_cmp_gt_i32_e32 vcc, 0, v169
	s_nop 1
	v_cndmask_b32_e32 v229, v162, v164, vcc
	v_lshl_add_u64 v[162:163], s[0:1], 0, v[62:63]
	v_not_b32_e32 v164, v170
	flat_load_dword v166, v[162:163]
	v_or_b32_e32 v162, 0x80000000, v170
	v_cmp_gt_i32_e32 vcc, 0, v170
	s_nop 1
	v_cndmask_b32_e32 v228, v162, v164, vcc
	v_lshl_add_u64 v[162:163], s[0:1], 0, v[60:61]
	v_not_b32_e32 v164, v171
	flat_load_dword v167, v[162:163]
	v_or_b32_e32 v162, 0x80000000, v171
	v_cmp_gt_i32_e32 vcc, 0, v171
	s_nop 1
	v_cndmask_b32_e32 v227, v162, v164, vcc
	v_lshl_add_u64 v[162:163], s[0:1], 0, v[58:59]
	v_not_b32_e32 v164, v172
	flat_load_dword v169, v[162:163]
	v_or_b32_e32 v162, 0x80000000, v172
	v_cmp_gt_i32_e32 vcc, 0, v172
	s_nop 1
	v_cndmask_b32_e32 v226, v162, v164, vcc
	v_lshl_add_u64 v[162:163], s[0:1], 0, v[56:57]
	v_not_b32_e32 v164, v173
	flat_load_dword v170, v[162:163]
	v_or_b32_e32 v162, 0x80000000, v173
	v_cmp_gt_i32_e32 vcc, 0, v173
	s_nop 1
	v_cndmask_b32_e32 v225, v162, v164, vcc
	v_lshl_add_u64 v[162:163], s[0:1], 0, v[52:53]
	v_not_b32_e32 v164, v174
	flat_load_dword v171, v[162:163]
	v_or_b32_e32 v162, 0x80000000, v174
	v_cmp_gt_i32_e32 vcc, 0, v174
	s_nop 1
	v_cndmask_b32_e32 v224, v162, v164, vcc
	v_lshl_add_u64 v[162:163], s[0:1], 0, v[54:55]
	v_not_b32_e32 v164, v175
	flat_load_dword v172, v[162:163]
	v_or_b32_e32 v162, 0x80000000, v175
	v_cmp_gt_i32_e32 vcc, 0, v175
	s_nop 1
	v_cndmask_b32_e32 v223, v162, v164, vcc
	v_lshl_add_u64 v[162:163], s[0:1], 0, v[50:51]
	flat_load_dword v173, v[162:163]
	v_not_b32_e32 v164, v176
	v_or_b32_e32 v162, 0x80000000, v176
	v_cmp_gt_i32_e32 vcc, 0, v176
	s_nop 1
	v_cndmask_b32_e32 v222, v162, v164, vcc
	v_lshl_add_u64 v[162:163], s[0:1], 0, v[48:49]
	v_not_b32_e32 v164, v177
	flat_load_dword v174, v[162:163]
	v_or_b32_e32 v162, 0x80000000, v177
	v_cmp_gt_i32_e32 vcc, 0, v177
	s_waitcnt vmcnt(0) lgkmcnt(0)
; DI unsigned f2key(float f) { const unsigned u = __float_as_uint(f); return (u & 0x80000000u) ? ~u : (u | 0x80000000u); }
; template <int NV>
; DI void topk_row(const float* row, int s, LAS int* lst, int lane) {
;     ...
;     for (int jo = 0; jo < NV / 16; ++jo) { const float* rb = row + jo * 1024;
; #pragma unroll
;         for (int ji = 0; ji < 16; ++ji) { const int j = jo * 16 + ji; const unsigned u = f2key(rb[ji * 64 + lane]); key[j] = (j * 64 + lane <= s) ? u : 0u; } }
	v_or_b32_e32 v177, 0x80000000, v168
	v_cndmask_b32_e32 v221, v162, v164, vcc
	v_lshl_add_u64 v[162:163], s[0:1], 0, v[46:47]
	v_not_b32_e32 v164, v178
	flat_load_dword v175, v[162:163]
	v_or_b32_e32 v162, 0x80000000, v178
	v_cmp_gt_i32_e32 vcc, 0, v178
	s_nop 1
	v_cndmask_b32_e32 v220, v162, v164, vcc
	v_lshl_add_u64 v[162:163], s[0:1], 0, v[44:45]
	flat_load_dword v176, v[162:163]
	v_lshl_add_u64 v[162:163], s[0:1], 0, v[42:43]
	flat_load_dword v178, v[162:163]
	v_not_b32_e32 v164, v168
	v_cmp_gt_i32_e32 vcc, 0, v168
	v_lshl_add_u64 v[162:163], s[0:1], 0, v[40:41]
	s_add_u32 s0, s12, 0x4000
	v_cndmask_b32_e32 v219, v177, v164, vcc
	flat_load_dword v177, v[162:163]
	s_addc_u32 s1, s13, 0
	v_not_b32_e32 v164, v180
	v_or_b32_e32 v168, 0x80000000, v180
	v_cmp_gt_i32_e32 vcc, 0, v180
	v_lshl_add_u64 v[162:163], s[0:1], 0, v[0:1]
	s_nop 0
	v_cndmask_b32_e32 v218, v168, v164, vcc
	v_not_b32_e32 v164, v179
	flat_load_dword v168, v[162:163]
	v_or_b32_e32 v162, 0x80000000, v179
	v_cmp_gt_i32_e32 vcc, 0, v179
	s_nop 1
	v_cndmask_b32_e32 v217, v162, v164, vcc
	v_lshl_add_u64 v[162:163], s[0:1], 0, v[38:39]
	v_not_b32_e32 v164, v165
	flat_load_dword v179, v[162:163]
	v_or_b32_e32 v162, 0x80000000, v165
	v_cmp_gt_i32_e32 vcc, 0, v165
	s_nop 1
	v_cndmask_b32_e32 v216, v162, v164, vcc
	v_lshl_add_u64 v[162:163], s[0:1], 0, v[36:37]
	v_not_b32_e32 v164, v166
	flat_load_dword v165, v[162:163]
	v_or_b32_e32 v162, 0x80000000, v166
	v_cmp_gt_i32_e32 vcc, 0, v166
	s_nop 1
	v_cndmask_b32_e32 v215, v162, v164, vcc
	v_lshl_add_u64 v[162:163], s[0:1], 0, v[34:35]
	v_not_b32_e32 v164, v167
	flat_load_dword v166, v[162:163]
	v_or_b32_e32 v162, 0x80000000, v167
	v_cmp_gt_i32_e32 vcc, 0, v167
	v_or_b32_e32 v167, 0x80000000, v169
	s_nop 0
	v_cndmask_b32_e32 v214, v162, v164, vcc
	v_lshl_add_u64 v[162:163], s[0:1], 0, v[62:63]
	flat_load_dword v180, v[162:163]
	v_not_b32_e32 v164, v169
	v_cmp_gt_i32_e32 vcc, 0, v169
	v_lshl_add_u64 v[162:163], s[0:1], 0, v[60:61]
	v_or_b32_e32 v169, 0x80000000, v171
	v_cndmask_b32_e32 v213, v167, v164, vcc
	v_not_b32_e32 v164, v170
	flat_load_dword v167, v[162:163]
	v_or_b32_e32 v162, 0x80000000, v170
	v_cmp_gt_i32_e32 vcc, 0, v170
	s_nop 1
	v_cndmask_b32_e32 v212, v162, v164, vcc
	v_lshl_add_u64 v[162:163], s[0:1], 0, v[58:59]
	flat_load_dword v170, v[162:163]
	v_lshl_add_u64 v[162:163], s[0:1], 0, v[56:57]
	v_not_b32_e32 v164, v171
	v_cmp_gt_i32_e32 vcc, 0, v171
	flat_load_dword v171, v[162:163]
	v_lshl_add_u64 v[162:163], s[0:1], 0, v[52:53]
	v_cndmask_b32_e32 v211, v169, v164, vcc
	v_not_b32_e32 v164, v172
	v_or_b32_e32 v169, 0x80000000, v172
	v_cmp_gt_i32_e32 vcc, 0, v172
	flat_load_dword v172, v[162:163]
	v_lshl_add_u64 v[162:163], s[0:1], 0, v[54:55]
	v_cndmask_b32_e32 v210, v169, v164, vcc
	v_not_b32_e32 v164, v173
	v_or_b32_e32 v169, 0x80000000, v173
	v_cmp_gt_i32_e32 vcc, 0, v173
	flat_load_dword v173, v[162:163]
	v_lshl_add_u64 v[162:163], s[0:1], 0, v[50:51]
	v_cndmask_b32_e32 v209, v169, v164, vcc
	v_not_b32_e32 v164, v174
	v_or_b32_e32 v169, 0x80000000, v174
	v_cmp_gt_i32_e32 vcc, 0, v174
	flat_load_dword v174, v[162:163]
	s_waitcnt vmcnt(0) lgkmcnt(0)
	v_not_b32_e32 v162, v176
	v_cndmask_b32_e32 v208, v169, v164, vcc
	v_not_b32_e32 v164, v175
	v_or_b32_e32 v169, 0x80000000, v175
	v_cmp_gt_i32_e32 vcc, 0, v175
	v_or_b32_e32 v163, 0x80000000, v176
	s_nop 0
	v_cndmask_b32_e32 v207, v169, v164, vcc
	v_cmp_gt_i32_e32 vcc, 0, v176
	v_not_b32_e32 v164, v178
	s_nop 0
	v_cndmask_b32_e32 v206, v163, v162, vcc
	v_lshl_add_u64 v[162:163], s[0:1], 0, v[48:49]
	flat_load_dword v169, v[162:163]
	v_or_b32_e32 v162, 0x80000000, v178
	v_cmp_gt_i32_e32 vcc, 0, v178
	s_nop 1
	v_cndmask_b32_e32 v205, v162, v164, vcc
	v_lshl_add_u64 v[162:163], s[0:1], 0, v[46:47]
	v_not_b32_e32 v164, v177
	flat_load_dword v175, v[162:163]
	v_or_b32_e32 v162, 0x80000000, v177
	v_cmp_gt_i32_e32 vcc, 0, v177
	v_or_b32_e32 v177, 0x80000000, v165
	s_nop 0
	v_cndmask_b32_e32 v204, v162, v164, vcc
	v_lshl_add_u64 v[162:163], s[0:1], 0, v[44:45]
	flat_load_dword v176, v[162:163]
	v_not_b32_e32 v164, v168
	v_or_b32_e32 v162, 0x80000000, v168
	v_cmp_gt_i32_e32 vcc, 0, v168
	s_nop 1
	v_cndmask_b32_e32 v203, v162, v164, vcc
	v_lshl_add_u64 v[162:163], s[0:1], 0, v[42:43]
	v_not_b32_e32 v164, v179
	flat_load_dword v168, v[162:163]
	v_or_b32_e32 v162, 0x80000000, v179
	v_cmp_gt_i32_e32 vcc, 0, v179
	s_nop 1
	v_cndmask_b32_e32 v202, v162, v164, vcc
	v_lshl_add_u64 v[162:163], s[0:1], 0, v[40:41]
	s_add_u32 s0, s12, 0x5000
	s_addc_u32 s1, s13, 0
	v_not_b32_e32 v164, v165
	flat_load_dword v178, v[162:163]
	v_cmp_gt_i32_e32 vcc, 0, v165
	v_lshl_add_u64 v[162:163], s[0:1], 0, v[0:1]
	flat_load_dword v165, v[162:163]
	v_cndmask_b32_e32 v201, v177, v164, vcc
	v_not_b32_e32 v164, v166
	v_or_b32_e32 v162, 0x80000000, v166
	v_cmp_gt_i32_e32 vcc, 0, v166
	v_or_b32_e32 v163, 0x80000000, v180
	v_or_b32_e32 v177, 0x80000000, v167
	v_cndmask_b32_e32 v200, v162, v164, vcc
	v_not_b32_e32 v162, v180
	v_cmp_gt_i32_e32 vcc, 0, v180
	v_not_b32_e32 v164, v167
	s_nop 0
	v_cndmask_b32_e32 v199, v163, v162, vcc
	v_lshl_add_u64 v[162:163], s[0:1], 0, v[38:39]
	flat_load_dword v166, v[162:163]
	v_lshl_add_u64 v[162:163], s[0:1], 0, v[36:37]
	flat_load_dword v179, v[162:163]
	v_cmp_gt_i32_e32 vcc, 0, v167
	v_lshl_add_u64 v[162:163], s[0:1], 0, v[34:35]
	v_or_b32_e32 v167, 0x80000000, v170
	v_cndmask_b32_e32 v198, v177, v164, vcc
	v_not_b32_e32 v164, v170
	flat_load_dword v177, v[162:163]
	v_cmp_gt_i32_e32 vcc, 0, v170
	v_lshl_add_u64 v[162:163], s[0:1], 0, v[62:63]
	flat_load_dword v170, v[162:163]
	v_cndmask_b32_e32 v197, v167, v164, vcc
	v_not_b32_e32 v164, v171
	v_or_b32_e32 v167, 0x80000000, v171
	v_cmp_gt_i32_e32 vcc, 0, v171
	v_lshl_add_u64 v[162:163], s[0:1], 0, v[60:61]
	s_nop 0
	v_cndmask_b32_e32 v196, v167, v164, vcc
	v_not_b32_e32 v164, v172
	flat_load_dword v167, v[162:163]
	v_or_b32_e32 v162, 0x80000000, v172
	v_cmp_gt_i32_e32 vcc, 0, v172
	s_nop 1
	v_cndmask_b32_e32 v195, v162, v164, vcc
	v_lshl_add_u64 v[162:163], s[0:1], 0, v[58:59]
	v_not_b32_e32 v164, v173
	flat_load_dword v171, v[162:163]
	v_or_b32_e32 v162, 0x80000000, v173
	v_cmp_gt_i32_e32 vcc, 0, v173
	v_or_b32_e32 v173, 0x80000000, v174
	s_nop 0
	v_cndmask_b32_e32 v194, v162, v164, vcc
	v_lshl_add_u64 v[162:163], s[0:1], 0, v[56:57]
	flat_load_dword v172, v[162:163]
	v_lshl_add_u64 v[162:163], s[0:1], 0, v[52:53]
	flat_load_dword v142, v[162:163]
	v_not_b32_e32 v164, v174
	v_cmp_gt_i32_e32 vcc, 0, v174
	v_lshl_add_u64 v[162:163], s[0:1], 0, v[54:55]
	flat_load_dword v174, v[162:163]
	v_cndmask_b32_e32 v193, v173, v164, vcc
	s_waitcnt vmcnt(0) lgkmcnt(0)
; DI unsigned f2key(float f) { const unsigned u = __float_as_uint(f); return (u & 0x80000000u) ? ~u : (u | 0x80000000u); }
; template <int NV>
; DI void topk_row(const float* row, int s, LAS int* lst, int lane) {
;     ...
;     for (int jo = 0; jo < NV / 16; ++jo) { const float* rb = row + jo * 1024;
; #pragma unroll
;         for (int ji = 0; ji < 16; ++ji) { const int j = jo * 16 + ji; const unsigned u = f2key(rb[ji * 64 + lane]); key[j] = (j * 64 + lane <= s) ? u : 0u; } }
	v_not_b32_e32 v164, v169
	v_or_b32_e32 v173, 0x80000000, v169
	v_cmp_gt_i32_e32 vcc, 0, v169
	v_lshl_add_u64 v[162:163], s[0:1], 0, v[50:51]
	v_or_b32_e32 v169, 0x80000000, v175
	v_cndmask_b32_e32 v192, v173, v164, vcc
	v_not_b32_e32 v164, v175
	flat_load_dword v173, v[162:163]
	v_cmp_gt_i32_e32 vcc, 0, v175
	v_lshl_add_u64 v[162:163], s[0:1], 0, v[48:49]
	s_nop 0
	v_cndmask_b32_e32 v191, v169, v164, vcc
	v_not_b32_e32 v164, v176
	flat_load_dword v169, v[162:163]
	v_or_b32_e32 v162, 0x80000000, v176
	v_cmp_gt_i32_e32 vcc, 0, v176
	v_or_b32_e32 v176, 0x80000000, v168
	s_nop 0
	v_cndmask_b32_e32 v190, v162, v164, vcc
	v_lshl_add_u64 v[162:163], s[0:1], 0, v[46:47]
	flat_load_dword v175, v[162:163]
	v_lshl_add_u64 v[162:163], s[0:1], 0, v[44:45]
	flat_load_dword v143, v[162:163]
	v_lshl_add_u64 v[162:163], s[0:1], 0, v[42:43]
	flat_load_dword v144, v[162:163]
	v_lshl_add_u64 v[162:163], s[0:1], 0, v[40:41]
	flat_load_dword v145, v[162:163]
	s_add_u32 s0, s12, 0x6000
	v_not_b32_e32 v164, v168
	v_cmp_gt_i32_e32 vcc, 0, v168
	s_addc_u32 s1, s13, 0
	v_or_b32_e32 v168, 0x80000000, v178
	v_cndmask_b32_e32 v189, v176, v164, vcc
	v_not_b32_e32 v164, v178
	v_cmp_gt_i32_e32 vcc, 0, v178
	v_lshl_add_u64 v[162:163], s[0:1], 0, v[0:1]
	flat_load_dword v146, v[162:163]
	v_cndmask_b32_e32 v187, v168, v164, vcc
	v_not_b32_e32 v164, v165
	v_or_b32_e32 v168, 0x80000000, v165
	v_cmp_gt_i32_e32 vcc, 0, v165
	v_not_b32_e32 v162, v166
	v_or_b32_e32 v163, 0x80000000, v166
	v_cndmask_b32_e32 v188, v168, v164, vcc
	v_cmp_gt_i32_e32 vcc, 0, v166
	v_not_b32_e32 v164, v179
	v_or_b32_e32 v166, 0x80000000, v177
	v_cndmask_b32_e32 v186, v163, v162, vcc
	v_lshl_add_u64 v[162:163], s[0:1], 0, v[38:39]
	flat_load_dword v165, v[162:163]
	v_or_b32_e32 v162, 0x80000000, v179
	v_cmp_gt_i32_e32 vcc, 0, v179
	s_nop 1
	v_cndmask_b32_e32 v185, v162, v164, vcc
	v_not_b32_e32 v164, v177
	v_lshl_add_u64 v[162:163], s[0:1], 0, v[36:37]
	v_cmp_gt_i32_e32 vcc, 0, v177
	flat_load_dword v168, v[162:163]
	v_not_b32_e32 v162, v170
	v_cndmask_b32_e32 v184, v166, v164, vcc
	v_or_b32_e32 v163, 0x80000000, v170
	v_cmp_gt_i32_e32 vcc, 0, v170
	v_not_b32_e32 v164, v167
	s_nop 0
	v_cndmask_b32_e32 v183, v163, v162, vcc
	v_lshl_add_u64 v[162:163], s[0:1], 0, v[34:35]
	flat_load_dword v166, v[162:163]
	v_or_b32_e32 v162, 0x80000000, v167
	v_cmp_gt_i32_e32 vcc, 0, v167
	v_or_b32_e32 v167, 0x80000000, v171
	s_nop 0
	v_cndmask_b32_e32 v182, v162, v164, vcc
	v_not_b32_e32 v164, v171
	v_lshl_add_u64 v[162:163], s[0:1], 0, v[62:63]
	v_cmp_gt_i32_e32 vcc, 0, v171
	flat_load_dword v147, v[162:163]
	v_not_b32_e32 v162, v172
	v_cndmask_b32_e32 v181, v167, v164, vcc
	v_or_b32_e32 v163, 0x80000000, v172
	v_cmp_gt_i32_e32 vcc, 0, v172
	v_not_b32_e32 v164, v142
	s_nop 0
	v_cndmask_b32_e32 v180, v163, v162, vcc
	v_lshl_add_u64 v[162:163], s[0:1], 0, v[60:61]
	flat_load_dword v167, v[162:163]
	v_or_b32_e32 v162, 0x80000000, v142
	v_cmp_gt_i32_e32 vcc, 0, v142
	v_not_b32_e32 v142, v174
	s_nop 0
	v_cndmask_b32_e32 v179, v162, v164, vcc
	v_lshl_add_u64 v[162:163], s[0:1], 0, v[58:59]
	flat_load_dword v148, v[162:163]
	v_or_b32_e32 v164, 0x80000000, v174
	v_cmp_gt_i32_e32 vcc, 0, v174
	s_waitcnt vmcnt(0) lgkmcnt(0)
	v_or_b32_e32 v162, 0x80000000, v173
	v_cndmask_b32_e32 v178, v164, v142, vcc
	v_not_b32_e32 v142, v173
	v_cmp_gt_i32_e32 vcc, 0, v173
	v_or_b32_e32 v164, 0x80000000, v169
	s_nop 0
	v_cndmask_b32_e32 v177, v162, v142, vcc
	v_not_b32_e32 v142, v169
	v_lshl_add_u64 v[162:163], s[0:1], 0, v[56:57]
	v_cmp_gt_i32_e32 vcc, 0, v169
	flat_load_dword v149, v[162:163]
	v_or_b32_e32 v162, 0x80000000, v175
	v_cndmask_b32_e32 v176, v164, v142, vcc
	v_not_b32_e32 v142, v175
	v_cmp_gt_i32_e32 vcc, 0, v175
	s_nop 1
	v_cndmask_b32_e32 v175, v162, v142, vcc
	v_lshl_add_u64 v[162:163], s[0:1], 0, v[52:53]
	v_not_b32_e32 v142, v143
	flat_load_dword v150, v[162:163]
	v_or_b32_e32 v162, 0x80000000, v143
	v_cmp_gt_i32_e32 vcc, 0, v143
	s_nop 1
	v_cndmask_b32_e32 v174, v162, v142, vcc
	v_lshl_add_u64 v[162:163], s[0:1], 0, v[54:55]
	v_not_b32_e32 v142, v144
	flat_load_dword v143, v[162:163]
	v_or_b32_e32 v162, 0x80000000, v144
	v_cmp_gt_i32_e32 vcc, 0, v144
	v_or_b32_e32 v144, 0x80000000, v145
	s_nop 0
	v_cndmask_b32_e32 v173, v162, v142, vcc
	v_not_b32_e32 v142, v145
	v_cmp_gt_i32_e32 vcc, 0, v145
	v_lshl_add_u64 v[162:163], s[0:1], 0, v[50:51]
	v_or_b32_e32 v145, 0x80000000, v146
	v_cndmask_b32_e32 v172, v144, v142, vcc
	flat_load_dword v144, v[162:163]
	v_not_b32_e32 v142, v146
	v_cmp_gt_i32_e32 vcc, 0, v146
	v_lshl_add_u64 v[162:163], s[0:1], 0, v[48:49]
	v_or_b32_e32 v146, 0x80000000, v165
	v_cndmask_b32_e32 v142, v145, v142, vcc
	flat_load_dword v145, v[162:163]
	v_cmp_lt_u32_e32 vcc, s2, v161
	s_movk_i32 s2, 0x183f
	v_lshl_add_u64 v[162:163], s[0:1], 0, v[46:47]
	v_cndmask_b32_e32 v171, 0, v142, vcc
	v_not_b32_e32 v142, v165
	v_cmp_gt_i32_e32 vcc, 0, v165
	flat_load_dword v151, v[162:163]
	v_lshl_add_u64 v[162:163], s[0:1], 0, v[44:45]
	v_cndmask_b32_e32 v142, v146, v142, vcc
	v_cmp_lt_u32_e32 vcc, s2, v161
	v_or_b32_e32 v146, 0x80000000, v168
	s_movk_i32 s2, 0x187f
	v_cndmask_b32_e32 v170, 0, v142, vcc
	v_not_b32_e32 v142, v168
	v_cmp_gt_i32_e32 vcc, 0, v168
	flat_load_dword v152, v[162:163]
	v_lshl_add_u64 v[162:163], s[0:1], 0, v[42:43]
	v_cndmask_b32_e32 v142, v146, v142, vcc
	v_cmp_lt_u32_e32 vcc, s2, v161
	v_or_b32_e32 v146, 0x80000000, v166
	s_movk_i32 s2, 0x18bf
	v_cndmask_b32_e32 v169, 0, v142, vcc
	v_not_b32_e32 v142, v166
	v_cmp_gt_i32_e32 vcc, 0, v166
	s_nop 1
	v_cndmask_b32_e32 v142, v146, v142, vcc
	v_cmp_lt_u32_e32 vcc, s2, v161
	v_or_b32_e32 v146, 0x80000000, v147
	s_movk_i32 s2, 0x18ff
	v_cndmask_b32_e32 v168, 0, v142, vcc
	v_not_b32_e32 v142, v147
	v_cmp_gt_i32_e32 vcc, 0, v147
	v_or_b32_e32 v147, 0x80000000, v167
	s_nop 0
	v_cndmask_b32_e32 v142, v146, v142, vcc
	flat_load_dword v146, v[162:163]
	v_cmp_lt_u32_e32 vcc, s2, v161
	v_lshl_add_u64 v[162:163], s[0:1], 0, v[40:41]
	s_movk_i32 s0, 0x193f
	v_cndmask_b32_e32 v166, 0, v142, vcc
	v_not_b32_e32 v142, v167
	v_cmp_gt_i32_e32 vcc, 0, v167
	s_movk_i32 s2, 0x197f
	s_nop 0
	v_cndmask_b32_e32 v142, v147, v142, vcc
	v_cmp_lt_u32_e32 vcc, s0, v161
	s_add_u32 s0, s12, 0x7000
	flat_load_dword v147, v[162:163]
	s_addc_u32 s1, s13, 0
	v_lshl_add_u64 v[38:39], s[0:1], 0, v[38:39]
	v_cndmask_b32_e32 v164, 0, v142, vcc
	v_not_b32_e32 v142, v148
	v_cmp_gt_i32_e32 vcc, 0, v148
	flat_load_dword v38, v[38:39]
	v_or_b32_e32 v162, 0x80000000, v148
	v_cndmask_b32_e32 v142, v162, v142, vcc
	v_lshl_add_u64 v[162:163], s[0:1], 0, v[0:1]
	flat_load_dword v0, v[162:163]
	v_cmp_lt_u32_e32 vcc, s2, v161
	s_waitcnt vmcnt(0) lgkmcnt(0)
; DI unsigned f2key(float f) { const unsigned u = __float_as_uint(f); return (u & 0x80000000u) ? ~u : (u | 0x80000000u); }
; template <int NV>
; DI void topk_row(const float* row, int s, LAS int* lst, int lane) {
;     ...
;     for (int jo = 0; jo < NV / 16; ++jo) { const float* rb = row + jo * 1024;
; #pragma unroll
;         for (int ji = 0; ji < 16; ++ji) { const int j = jo * 16 + ji; const unsigned u = f2key(rb[ji * 64 + lane]); key[j] = (j * 64 + lane <= s) ? u : 0u; } }
;     unsigned T = 0u;
; #pragma unroll 1
	v_or_b32_e32 v148, 0x80000000, v149
	s_movk_i32 s2, 0x19bf
	v_cndmask_b32_e32 v167, 0, v142, vcc
	v_not_b32_e32 v142, v149
	v_cmp_gt_i32_e32 vcc, 0, v149
	v_lshl_add_u64 v[36:37], s[0:1], 0, v[36:37]
	flat_load_dword v36, v[36:37]
	v_cndmask_b32_e32 v142, v148, v142, vcc
	v_cmp_lt_u32_e32 vcc, s2, v161
	v_not_b32_e32 v39, v150
	s_movk_i32 s2, 0x19ff
	v_cndmask_b32_e32 v165, 0, v142, vcc
	v_or_b32_e32 v142, 0x80000000, v150
	v_cmp_gt_i32_e32 vcc, 0, v150
	v_or_b32_e32 v37, 0x80000000, v143
	v_lshl_add_u64 v[34:35], s[0:1], 0, v[34:35]
	v_cndmask_b32_e32 v39, v142, v39, vcc
	v_cmp_lt_u32_e32 vcc, s2, v161
	s_movk_i32 s2, 0x1a3f
	v_or_b32_e32 v142, 0x80000000, v144
	v_cndmask_b32_e32 v162, 0, v39, vcc
	v_not_b32_e32 v39, v143
	v_cmp_gt_i32_e32 vcc, 0, v143
	s_nop 1
	v_cndmask_b32_e32 v37, v37, v39, vcc
	flat_load_dword v39, v[34:35]
	v_cmp_lt_u32_e32 vcc, s2, v161
	v_lshl_add_u64 v[34:35], s[0:1], 0, v[62:63]
	s_movk_i32 s2, 0x1a7f
	v_cndmask_b32_e32 v163, 0, v37, vcc
	v_not_b32_e32 v37, v144
	v_cmp_gt_i32_e32 vcc, 0, v144
	flat_load_dword v63, v[34:35]
	s_nop 0
	v_cndmask_b32_e32 v34, v142, v37, vcc
	v_cmp_lt_u32_e32 vcc, s2, v161
	v_not_b32_e32 v37, v145
	s_movk_i32 s2, 0x1abf
	v_cndmask_b32_e32 v62, 0, v34, vcc
	v_lshl_add_u64 v[34:35], s[0:1], 0, v[60:61]
	flat_load_dword v60, v[34:35]
	v_or_b32_e32 v34, 0x80000000, v145
	v_cmp_gt_i32_e32 vcc, 0, v145
	v_or_b32_e32 v61, 0x80000000, v151
	s_nop 0
	v_cndmask_b32_e32 v37, v34, v37, vcc
	v_lshl_add_u64 v[34:35], s[0:1], 0, v[58:59]
	flat_load_dword v59, v[34:35]
	v_cmp_lt_u32_e32 vcc, s2, v161
	v_lshl_add_u64 v[34:35], s[0:1], 0, v[56:57]
	s_movk_i32 s2, 0x1aff
	v_cndmask_b32_e32 v58, 0, v37, vcc
	v_not_b32_e32 v37, v151
	v_cmp_gt_i32_e32 vcc, 0, v151
	flat_load_dword v57, v[34:35]
	s_nop 0
	v_cndmask_b32_e32 v34, v61, v37, vcc
	v_cmp_lt_u32_e32 vcc, s2, v161
	v_not_b32_e32 v37, v152
	s_movk_i32 s2, 0x1b3f
	v_cndmask_b32_e32 v56, 0, v34, vcc
	v_lshl_add_u64 v[34:35], s[0:1], 0, v[52:53]
	flat_load_dword v53, v[34:35]
	v_or_b32_e32 v34, 0x80000000, v152
	v_cmp_gt_i32_e32 vcc, 0, v152
	s_nop 1
	v_cndmask_b32_e32 v37, v34, v37, vcc
	v_lshl_add_u64 v[34:35], s[0:1], 0, v[54:55]
	flat_load_dword v54, v[34:35]
	v_cmp_lt_u32_e32 vcc, s2, v161
	v_or_b32_e32 v55, 0x80000000, v146
	v_lshl_add_u64 v[34:35], s[0:1], 0, v[50:51]
	v_cndmask_b32_e32 v52, 0, v37, vcc
	v_not_b32_e32 v37, v146
	v_cmp_gt_i32_e32 vcc, 0, v146
	s_movk_i32 s2, 0x1b7f
	flat_load_dword v61, v[34:35]
	v_cndmask_b32_e32 v34, v55, v37, vcc
	v_cmp_lt_u32_e32 vcc, s2, v161
	v_not_b32_e32 v37, v147
	s_movk_i32 s2, 0x1bbf
	v_cndmask_b32_e32 v50, 0, v34, vcc
	v_lshl_add_u64 v[34:35], s[0:1], 0, v[48:49]
	flat_load_dword v55, v[34:35]
	v_or_b32_e32 v34, 0x80000000, v147
	v_cmp_gt_i32_e32 vcc, 0, v147
	s_nop 1
	v_cndmask_b32_e32 v37, v34, v37, vcc
	v_lshl_add_u64 v[34:35], s[0:1], 0, v[46:47]
	flat_load_dword v142, v[34:35]
	v_cmp_lt_u32_e32 vcc, s2, v161
	v_lshl_add_u64 v[34:35], s[0:1], 0, v[44:45]
	v_or_b32_e32 v46, 0x80000000, v0
	v_cndmask_b32_e32 v49, 0, v37, vcc
	v_not_b32_e32 v37, v0
	flat_load_dword v143, v[34:35]
	v_cmp_gt_i32_e32 vcc, 0, v0
	s_movk_i32 s2, 0x1bff
	v_lshl_add_u64 v[34:35], s[0:1], 0, v[42:43]
	v_cndmask_b32_e32 v0, v46, v37, vcc
	v_cmp_lt_u32_e32 vcc, s2, v161
	flat_load_dword v144, v[34:35]
	v_or_b32_e32 v34, 0x80000000, v38
	v_cndmask_b32_e32 v48, 0, v0, vcc
	v_not_b32_e32 v0, v38
	v_cmp_gt_i32_e32 vcc, 0, v38
	s_nop 1
	v_cndmask_b32_e32 v0, v34, v0, vcc
	v_lshl_add_u64 v[34:35], s[0:1], 0, v[40:41]
	flat_load_dword v34, v[34:35]
	s_movk_i32 s0, 0x1c3f
	v_cmp_lt_u32_e32 vcc, s0, v161
	s_waitcnt vmcnt(0) lgkmcnt(0)
	v_or_b32_e32 v35, 0x80000000, v36
	s_movk_i32 s0, 0x1c7f
	v_cndmask_b32_e32 v51, 0, v0, vcc
	v_not_b32_e32 v0, v36
	v_cmp_gt_i32_e32 vcc, 0, v36
	s_nop 1
	v_cndmask_b32_e32 v0, v35, v0, vcc
	v_cmp_lt_u32_e32 vcc, s0, v161
	v_or_b32_e32 v35, 0x80000000, v39
	s_movk_i32 s0, 0x1cbf
	v_cndmask_b32_e32 v47, 0, v0, vcc
	v_not_b32_e32 v0, v39
	v_cmp_gt_i32_e32 vcc, 0, v39
	s_nop 1
	v_cndmask_b32_e32 v0, v35, v0, vcc
	v_cmp_lt_u32_e32 vcc, s0, v161
	v_or_b32_e32 v35, 0x80000000, v63
	s_movk_i32 s0, 0x1cff
	v_cndmask_b32_e32 v46, 0, v0, vcc
	v_not_b32_e32 v0, v63
	v_cmp_gt_i32_e32 vcc, 0, v63
	s_nop 1
	v_cndmask_b32_e32 v0, v35, v0, vcc
	v_cmp_lt_u32_e32 vcc, s0, v161
	v_or_b32_e32 v35, 0x80000000, v60
	s_movk_i32 s0, 0x1d3f
	v_cndmask_b32_e32 v45, 0, v0, vcc
	v_not_b32_e32 v0, v60
	v_cmp_gt_i32_e32 vcc, 0, v60
	s_nop 1
	v_cndmask_b32_e32 v0, v35, v0, vcc
	v_cmp_lt_u32_e32 vcc, s0, v161
	v_or_b32_e32 v35, 0x80000000, v59
	s_movk_i32 s0, 0x1d7f
	v_cndmask_b32_e32 v44, 0, v0, vcc
	v_not_b32_e32 v0, v59
	v_cmp_gt_i32_e32 vcc, 0, v59
	s_nop 1
	v_cndmask_b32_e32 v0, v35, v0, vcc
	v_cmp_lt_u32_e32 vcc, s0, v161
	v_or_b32_e32 v35, 0x80000000, v57
	s_movk_i32 s0, 0x1dbf
	v_cndmask_b32_e32 v43, 0, v0, vcc
	v_not_b32_e32 v0, v57
	v_cmp_gt_i32_e32 vcc, 0, v57
	s_nop 1
	v_cndmask_b32_e32 v0, v35, v0, vcc
	v_cmp_lt_u32_e32 vcc, s0, v161
	v_or_b32_e32 v35, 0x80000000, v53
	s_movk_i32 s0, 0x1dff
	v_cndmask_b32_e32 v42, 0, v0, vcc
	v_not_b32_e32 v0, v53
	v_cmp_gt_i32_e32 vcc, 0, v53
	v_or_b32_e32 v53, 0x80000000, v34
	s_nop 0
	v_cndmask_b32_e32 v0, v35, v0, vcc
	v_cmp_lt_u32_e32 vcc, s0, v161
	v_or_b32_e32 v35, 0x80000000, v54
	s_movk_i32 s0, 0x1e3f
	v_cndmask_b32_e32 v41, 0, v0, vcc
	v_not_b32_e32 v0, v54
	v_cmp_gt_i32_e32 vcc, 0, v54
	s_nop 1
	v_cndmask_b32_e32 v0, v35, v0, vcc
	v_cmp_lt_u32_e32 vcc, s0, v161
	v_or_b32_e32 v35, 0x80000000, v61
	s_movk_i32 s0, 0x1e7f
	v_cndmask_b32_e32 v40, 0, v0, vcc
	v_not_b32_e32 v0, v61
	v_cmp_gt_i32_e32 vcc, 0, v61
	s_nop 1
	v_cndmask_b32_e32 v0, v35, v0, vcc
	v_cmp_lt_u32_e32 vcc, s0, v161
	v_or_b32_e32 v35, 0x80000000, v55
	s_movk_i32 s0, 0x1ebf
	v_cndmask_b32_e32 v39, 0, v0, vcc
	v_not_b32_e32 v0, v55
	v_cmp_gt_i32_e32 vcc, 0, v55
	s_nop 1
	v_cndmask_b32_e32 v0, v35, v0, vcc
	v_cmp_lt_u32_e32 vcc, s0, v161
	v_or_b32_e32 v35, 0x80000000, v142
	s_movk_i32 s0, 0x1eff
	v_cndmask_b32_e32 v38, 0, v0, vcc
	v_not_b32_e32 v0, v142
	v_cmp_gt_i32_e32 vcc, 0, v142
	s_nop 1
	v_cndmask_b32_e32 v0, v35, v0, vcc
	v_cmp_lt_u32_e32 vcc, s0, v161
	v_or_b32_e32 v35, 0x80000000, v143
	s_movk_i32 s0, 0x1f3f
	v_cndmask_b32_e32 v37, 0, v0, vcc
	v_not_b32_e32 v0, v143
	v_cmp_gt_i32_e32 vcc, 0, v143
	s_nop 1
	v_cndmask_b32_e32 v0, v35, v0, vcc
	v_cmp_lt_u32_e32 vcc, s0, v161
	v_or_b32_e32 v35, 0x80000000, v144
	s_movk_i32 s0, 0x1f7f
	v_cndmask_b32_e32 v36, 0, v0, vcc
	v_not_b32_e32 v0, v144
	v_cmp_gt_i32_e32 vcc, 0, v144
	s_nop 1
	v_cndmask_b32_e32 v0, v35, v0, vcc
	v_cmp_lt_u32_e32 vcc, s0, v161
	s_movk_i32 s0, 0x1fbf
	s_nop 0
	v_cndmask_b32_e32 v35, 0, v0, vcc
	v_not_b32_e32 v0, v34
	v_cmp_gt_i32_e32 vcc, 0, v34
	v_mov_b32_e32 v34, 0
	s_nop 0
	v_cndmask_b32_e32 v0, v53, v0, vcc
	v_cmp_lt_u32_e32 vcc, s0, v161
	v_mov_b32_e32 v53, 31
	s_nop 0
	v_cndmask_b32_e32 v0, 0, v0, vcc
	v_readlane_b32 s100, v161, 0
	s_lshr_b32 s100, s100, 6
	s_add_u32 s100, s100, 1
; DI unsigned mbcnt64(unsigned long long m) { return __builtin_amdgcn_mbcnt_hi((unsigned)(m >> 32), __builtin_amdgcn_mbcnt_lo((unsigned)m, 0u)); }
; template <int NV>
; DI void topk_row(const float* row, int s, LAS int* lst, int lane) {
;     ...
;         const unsigned cand = T | (1u << bit); int c = 0;
; #pragma unroll
;         for (int j = 0; j < NV; ++j) asm volatile("v_cmp_le_u32 vcc, %2, %1\n\tv_addc_co_u32 %0, vcc, 0, %0, vcc" : "+v"(c) : "v"(key[j]), "s"(cand) : "vcc");
;         const int tot = wave_sum_i(c);
;         if (tot >= 256) T = cand;
;         if (tot == 256) break;
;     }
;     int bgt = 0;
; #pragma unroll
;     for (int j = 0; j < NV; ++j) { const bool sg = key[j] > T; const unsigned long long mg = __ballot(sg); if (sg) lst[bgt + (int)mbcnt64(mg)] = j * 64 + lane; bgt += __builtin_popcountll(mg); }
.LBB0_1969:
	v_lshlrev_b32_e64 v54, v53, 1
	v_mov_b32_e32 v55, 0
	v_or_b32_e32 v54, v54, v34
	v_cmp_le_u32 vcc, v54, v141
	v_addc_co_u32 v55, vcc, 0, v55, vcc
	s_nop 0
	v_cmp_le_u32 vcc, v54, v140
	v_addc_co_u32 v55, vcc, 0, v55, vcc
	s_nop 0
	v_cmp_le_u32 vcc, v54, v139
	v_addc_co_u32 v55, vcc, 0, v55, vcc
	s_nop 0
	v_cmp_le_u32 vcc, v54, v138
	v_addc_co_u32 v55, vcc, 0, v55, vcc
	s_nop 0
	v_cmp_le_u32 vcc, v54, v137
	v_addc_co_u32 v55, vcc, 0, v55, vcc
	s_nop 0
	v_cmp_le_u32 vcc, v54, v136
	v_addc_co_u32 v55, vcc, 0, v55, vcc
	s_nop 0
	v_cmp_le_u32 vcc, v54, v135
	v_addc_co_u32 v55, vcc, 0, v55, vcc
	s_nop 0
	v_cmp_le_u32 vcc, v54, v134
	v_addc_co_u32 v55, vcc, 0, v55, vcc
	s_nop 0
	s_cmp_le_u32 s100, 8
	s_cbranch_scc1 .Lp12_pe_0
	v_cmp_le_u32 vcc, v54, v133
	v_addc_co_u32 v55, vcc, 0, v55, vcc
	s_nop 0
	v_cmp_le_u32 vcc, v54, v132
	v_addc_co_u32 v55, vcc, 0, v55, vcc
	s_nop 0
	v_cmp_le_u32 vcc, v54, v251
	v_addc_co_u32 v55, vcc, 0, v55, vcc
	s_nop 0
	v_cmp_le_u32 vcc, v54, v248
	v_addc_co_u32 v55, vcc, 0, v55, vcc
	s_nop 0
	v_cmp_le_u32 vcc, v54, v247
	v_addc_co_u32 v55, vcc, 0, v55, vcc
	s_nop 0
	v_cmp_le_u32 vcc, v54, v253
	v_addc_co_u32 v55, vcc, 0, v55, vcc
	s_nop 0
	v_cmp_le_u32 vcc, v54, v249
	v_addc_co_u32 v55, vcc, 0, v55, vcc
	s_nop 0
	v_cmp_le_u32 vcc, v54, v252
	v_addc_co_u32 v55, vcc, 0, v55, vcc
	s_nop 0
	s_cmp_le_u32 s100, 16
	s_cbranch_scc1 .Lp12_pe_0
	v_cmp_le_u32 vcc, v54, v128
	v_addc_co_u32 v55, vcc, 0, v55, vcc
	s_nop 0
	v_cmp_le_u32 vcc, v54, v130
	v_addc_co_u32 v55, vcc, 0, v55, vcc
	s_nop 0
	v_cmp_le_u32 vcc, v54, v131
	v_addc_co_u32 v55, vcc, 0, v55, vcc
	s_nop 0
	v_cmp_le_u32 vcc, v54, v129
	v_addc_co_u32 v55, vcc, 0, v55, vcc
	s_nop 0
	v_cmp_le_u32 vcc, v54, v250
	v_addc_co_u32 v55, vcc, 0, v55, vcc
	s_nop 0
	v_cmp_le_u32 vcc, v54, v246
	v_addc_co_u32 v55, vcc, 0, v55, vcc
	s_nop 0
	v_cmp_le_u32 vcc, v54, v245
	v_addc_co_u32 v55, vcc, 0, v55, vcc
	s_nop 0
	v_cmp_le_u32 vcc, v54, v244
	v_addc_co_u32 v55, vcc, 0, v55, vcc
	s_nop 0
	s_cmp_le_u32 s100, 24
	s_cbranch_scc1 .Lp12_pe_0
	v_cmp_le_u32 vcc, v54, v243
	v_addc_co_u32 v55, vcc, 0, v55, vcc
	s_nop 0
	v_cmp_le_u32 vcc, v54, v242
	v_addc_co_u32 v55, vcc, 0, v55, vcc
	s_nop 0
	v_cmp_le_u32 vcc, v54, v241
	v_addc_co_u32 v55, vcc, 0, v55, vcc
	s_nop 0
	v_cmp_le_u32 vcc, v54, v240
	v_addc_co_u32 v55, vcc, 0, v55, vcc
	s_nop 0
	v_cmp_le_u32 vcc, v54, v239
	v_addc_co_u32 v55, vcc, 0, v55, vcc
	s_nop 0
	v_cmp_le_u32 vcc, v54, v238
	v_addc_co_u32 v55, vcc, 0, v55, vcc
	s_nop 0
	v_cmp_le_u32 vcc, v54, v237
	v_addc_co_u32 v55, vcc, 0, v55, vcc
	s_nop 0
	v_cmp_le_u32 vcc, v54, v236
	v_addc_co_u32 v55, vcc, 0, v55, vcc
	s_nop 0
	s_cmp_le_u32 s100, 32
	s_cbranch_scc1 .Lp12_pe_0
	v_cmp_le_u32 vcc, v54, v235
	v_addc_co_u32 v55, vcc, 0, v55, vcc
	s_nop 0
	v_cmp_le_u32 vcc, v54, v234
	v_addc_co_u32 v55, vcc, 0, v55, vcc
	s_nop 0
	v_cmp_le_u32 vcc, v54, v233
	v_addc_co_u32 v55, vcc, 0, v55, vcc
	s_nop 0
	v_cmp_le_u32 vcc, v54, v232
	v_addc_co_u32 v55, vcc, 0, v55, vcc
	s_nop 0
	v_cmp_le_u32 vcc, v54, v231
	v_addc_co_u32 v55, vcc, 0, v55, vcc
	s_nop 0
	v_cmp_le_u32 vcc, v54, v230
	v_addc_co_u32 v55, vcc, 0, v55, vcc
	s_nop 0
	v_cmp_le_u32 vcc, v54, v229
	v_addc_co_u32 v55, vcc, 0, v55, vcc
	s_nop 0
	v_cmp_le_u32 vcc, v54, v228
	v_addc_co_u32 v55, vcc, 0, v55, vcc
	s_nop 0
	s_cmp_le_u32 s100, 40
	s_cbranch_scc1 .Lp12_pe_0
	v_cmp_le_u32 vcc, v54, v227
	v_addc_co_u32 v55, vcc, 0, v55, vcc
	s_nop 0
	v_cmp_le_u32 vcc, v54, v226
	v_addc_co_u32 v55, vcc, 0, v55, vcc
	s_nop 0
	v_cmp_le_u32 vcc, v54, v225
	v_addc_co_u32 v55, vcc, 0, v55, vcc
	s_nop 0
	v_cmp_le_u32 vcc, v54, v224
	v_addc_co_u32 v55, vcc, 0, v55, vcc
	s_nop 0
	v_cmp_le_u32 vcc, v54, v223
	v_addc_co_u32 v55, vcc, 0, v55, vcc
	s_nop 0
	v_cmp_le_u32 vcc, v54, v222
	v_addc_co_u32 v55, vcc, 0, v55, vcc
	s_nop 0
	v_cmp_le_u32 vcc, v54, v221
	v_addc_co_u32 v55, vcc, 0, v55, vcc
	s_nop 0
	v_cmp_le_u32 vcc, v54, v220
	v_addc_co_u32 v55, vcc, 0, v55, vcc
	s_nop 0
	s_cmp_le_u32 s100, 48
	s_cbranch_scc1 .Lp12_pe_0
	v_cmp_le_u32 vcc, v54, v219
	v_addc_co_u32 v55, vcc, 0, v55, vcc
	s_nop 0
	v_cmp_le_u32 vcc, v54, v218
	v_addc_co_u32 v55, vcc, 0, v55, vcc
	s_nop 0
	v_cmp_le_u32 vcc, v54, v217
	v_addc_co_u32 v55, vcc, 0, v55, vcc
	s_nop 0
	v_cmp_le_u32 vcc, v54, v216
	v_addc_co_u32 v55, vcc, 0, v55, vcc
	s_nop 0
	v_cmp_le_u32 vcc, v54, v215
	v_addc_co_u32 v55, vcc, 0, v55, vcc
	s_nop 0
	v_cmp_le_u32 vcc, v54, v214
	v_addc_co_u32 v55, vcc, 0, v55, vcc
	s_nop 0
	v_cmp_le_u32 vcc, v54, v213
	v_addc_co_u32 v55, vcc, 0, v55, vcc
	s_nop 0
	v_cmp_le_u32 vcc, v54, v212
	v_addc_co_u32 v55, vcc, 0, v55, vcc
	s_nop 0
	s_cmp_le_u32 s100, 56
	s_cbranch_scc1 .Lp12_pe_0
	v_cmp_le_u32 vcc, v54, v211
	v_addc_co_u32 v55, vcc, 0, v55, vcc
	s_nop 0
	v_cmp_le_u32 vcc, v54, v210
	v_addc_co_u32 v55, vcc, 0, v55, vcc
	s_nop 0
	v_cmp_le_u32 vcc, v54, v209
	v_addc_co_u32 v55, vcc, 0, v55, vcc
	s_nop 0
	v_cmp_le_u32 vcc, v54, v208
	v_addc_co_u32 v55, vcc, 0, v55, vcc
	s_nop 0
	v_cmp_le_u32 vcc, v54, v207
	v_addc_co_u32 v55, vcc, 0, v55, vcc
	s_nop 0
	v_cmp_le_u32 vcc, v54, v206
	v_addc_co_u32 v55, vcc, 0, v55, vcc
	s_nop 0
	v_cmp_le_u32 vcc, v54, v205
	v_addc_co_u32 v55, vcc, 0, v55, vcc
	s_nop 0
	v_cmp_le_u32 vcc, v54, v204
	v_addc_co_u32 v55, vcc, 0, v55, vcc
	s_nop 0
	s_cmp_le_u32 s100, 64
	s_cbranch_scc1 .Lp12_pe_0
	v_cmp_le_u32 vcc, v54, v203
	v_addc_co_u32 v55, vcc, 0, v55, vcc
	s_nop 0
	v_cmp_le_u32 vcc, v54, v202
	v_addc_co_u32 v55, vcc, 0, v55, vcc
	s_nop 0
	v_cmp_le_u32 vcc, v54, v201
	v_addc_co_u32 v55, vcc, 0, v55, vcc
	s_nop 0
	v_cmp_le_u32 vcc, v54, v200
	v_addc_co_u32 v55, vcc, 0, v55, vcc
	s_nop 0
	v_cmp_le_u32 vcc, v54, v199
	v_addc_co_u32 v55, vcc, 0, v55, vcc
	s_nop 0
	v_cmp_le_u32 vcc, v54, v198
	v_addc_co_u32 v55, vcc, 0, v55, vcc
	s_nop 0
	v_cmp_le_u32 vcc, v54, v197
	v_addc_co_u32 v55, vcc, 0, v55, vcc
	s_nop 0
	v_cmp_le_u32 vcc, v54, v196
	v_addc_co_u32 v55, vcc, 0, v55, vcc
	s_nop 0
	s_cmp_le_u32 s100, 72
	s_cbranch_scc1 .Lp12_pe_0
; DI unsigned mbcnt64(unsigned long long m) { return __builtin_amdgcn_mbcnt_hi((unsigned)(m >> 32), __builtin_amdgcn_mbcnt_lo((unsigned)m, 0u)); }
; template <int NV>
; DI void topk_row(const float* row, int s, LAS int* lst, int lane) {
;     ...
;         const unsigned cand = T | (1u << bit); int c = 0;
; #pragma unroll
;         for (int j = 0; j < NV; ++j) asm volatile("v_cmp_le_u32 vcc, %2, %1\n\tv_addc_co_u32 %0, vcc, 0, %0, vcc" : "+v"(c) : "v"(key[j]), "s"(cand) : "vcc");
;         const int tot = wave_sum_i(c);
;         if (tot >= 256) T = cand;
;         if (tot == 256) break;
;     }
;     int bgt = 0;
; #pragma unroll
;     for (int j = 0; j < NV; ++j) { const bool sg = key[j] > T; const unsigned long long mg = __ballot(sg); if (sg) lst[bgt + (int)mbcnt64(mg)] = j * 64 + lane; bgt += __builtin_popcountll(mg); }
	v_cmp_le_u32 vcc, v54, v195
	v_addc_co_u32 v55, vcc, 0, v55, vcc
	s_nop 0
	v_cmp_le_u32 vcc, v54, v194
	v_addc_co_u32 v55, vcc, 0, v55, vcc
	s_nop 0
	v_cmp_le_u32 vcc, v54, v193
	v_addc_co_u32 v55, vcc, 0, v55, vcc
	s_nop 0
	v_cmp_le_u32 vcc, v54, v192
	v_addc_co_u32 v55, vcc, 0, v55, vcc
	s_nop 0
	v_cmp_le_u32 vcc, v54, v191
	v_addc_co_u32 v55, vcc, 0, v55, vcc
	s_nop 0
	v_cmp_le_u32 vcc, v54, v190
	v_addc_co_u32 v55, vcc, 0, v55, vcc
	s_nop 0
	v_cmp_le_u32 vcc, v54, v189
	v_addc_co_u32 v55, vcc, 0, v55, vcc
	s_nop 0
	v_cmp_le_u32 vcc, v54, v187
	v_addc_co_u32 v55, vcc, 0, v55, vcc
	s_nop 0
	s_cmp_le_u32 s100, 80
	s_cbranch_scc1 .Lp12_pe_0
	v_cmp_le_u32 vcc, v54, v188
	v_addc_co_u32 v55, vcc, 0, v55, vcc
	s_nop 0
	v_cmp_le_u32 vcc, v54, v186
	v_addc_co_u32 v55, vcc, 0, v55, vcc
	s_nop 0
	v_cmp_le_u32 vcc, v54, v185
	v_addc_co_u32 v55, vcc, 0, v55, vcc
	s_nop 0
	v_cmp_le_u32 vcc, v54, v184
	v_addc_co_u32 v55, vcc, 0, v55, vcc
	s_nop 0
	v_cmp_le_u32 vcc, v54, v183
	v_addc_co_u32 v55, vcc, 0, v55, vcc
	s_nop 0
	v_cmp_le_u32 vcc, v54, v182
	v_addc_co_u32 v55, vcc, 0, v55, vcc
	s_nop 0
	v_cmp_le_u32 vcc, v54, v181
	v_addc_co_u32 v55, vcc, 0, v55, vcc
	s_nop 0
	v_cmp_le_u32 vcc, v54, v180
	v_addc_co_u32 v55, vcc, 0, v55, vcc
	s_nop 0
	s_cmp_le_u32 s100, 88
	s_cbranch_scc1 .Lp12_pe_0
	v_cmp_le_u32 vcc, v54, v179
	v_addc_co_u32 v55, vcc, 0, v55, vcc
	s_nop 0
	v_cmp_le_u32 vcc, v54, v178
	v_addc_co_u32 v55, vcc, 0, v55, vcc
	s_nop 0
	v_cmp_le_u32 vcc, v54, v177
	v_addc_co_u32 v55, vcc, 0, v55, vcc
	s_nop 0
	v_cmp_le_u32 vcc, v54, v176
	v_addc_co_u32 v55, vcc, 0, v55, vcc
	s_nop 0
	v_cmp_le_u32 vcc, v54, v175
	v_addc_co_u32 v55, vcc, 0, v55, vcc
	s_nop 0
	v_cmp_le_u32 vcc, v54, v174
	v_addc_co_u32 v55, vcc, 0, v55, vcc
	s_nop 0
	v_cmp_le_u32 vcc, v54, v173
	v_addc_co_u32 v55, vcc, 0, v55, vcc
	s_nop 0
	v_cmp_le_u32 vcc, v54, v172
	v_addc_co_u32 v55, vcc, 0, v55, vcc
	s_nop 0
	s_cmp_le_u32 s100, 96
	s_cbranch_scc1 .Lp12_pe_0
	v_cmp_le_u32 vcc, v54, v171
	v_addc_co_u32 v55, vcc, 0, v55, vcc
	s_nop 0
	v_cmp_le_u32 vcc, v54, v170
	v_addc_co_u32 v55, vcc, 0, v55, vcc
	s_nop 0
	v_cmp_le_u32 vcc, v54, v169
	v_addc_co_u32 v55, vcc, 0, v55, vcc
	s_nop 0
	v_cmp_le_u32 vcc, v54, v168
	v_addc_co_u32 v55, vcc, 0, v55, vcc
	s_nop 0
	v_cmp_le_u32 vcc, v54, v166
	v_addc_co_u32 v55, vcc, 0, v55, vcc
	s_nop 0
	v_cmp_le_u32 vcc, v54, v164
	v_addc_co_u32 v55, vcc, 0, v55, vcc
	s_nop 0
	v_cmp_le_u32 vcc, v54, v167
	v_addc_co_u32 v55, vcc, 0, v55, vcc
	s_nop 0
	v_cmp_le_u32 vcc, v54, v165
	v_addc_co_u32 v55, vcc, 0, v55, vcc
	s_nop 0
	s_cmp_le_u32 s100, 104
	s_cbranch_scc1 .Lp12_pe_0
	v_cmp_le_u32 vcc, v54, v162
	v_addc_co_u32 v55, vcc, 0, v55, vcc
	s_nop 0
	v_cmp_le_u32 vcc, v54, v163
	v_addc_co_u32 v55, vcc, 0, v55, vcc
	s_nop 0
	v_cmp_le_u32 vcc, v54, v62
	v_addc_co_u32 v55, vcc, 0, v55, vcc
	s_nop 0
	v_cmp_le_u32 vcc, v54, v58
	v_addc_co_u32 v55, vcc, 0, v55, vcc
	s_nop 0
	v_cmp_le_u32 vcc, v54, v56
	v_addc_co_u32 v55, vcc, 0, v55, vcc
	s_nop 0
	v_cmp_le_u32 vcc, v54, v52
	v_addc_co_u32 v55, vcc, 0, v55, vcc
	s_nop 0
	v_cmp_le_u32 vcc, v54, v50
	v_addc_co_u32 v55, vcc, 0, v55, vcc
	s_nop 0
	v_cmp_le_u32 vcc, v54, v49
	v_addc_co_u32 v55, vcc, 0, v55, vcc
	s_nop 0
	s_cmp_le_u32 s100, 112
	s_cbranch_scc1 .Lp12_pe_0
	v_cmp_le_u32 vcc, v54, v48
	v_addc_co_u32 v55, vcc, 0, v55, vcc
	s_nop 0
	v_cmp_le_u32 vcc, v54, v51
	v_addc_co_u32 v55, vcc, 0, v55, vcc
	s_nop 0
	v_cmp_le_u32 vcc, v54, v47
	v_addc_co_u32 v55, vcc, 0, v55, vcc
	s_nop 0
	v_cmp_le_u32 vcc, v54, v46
	v_addc_co_u32 v55, vcc, 0, v55, vcc
	s_nop 0
	v_cmp_le_u32 vcc, v54, v45
	v_addc_co_u32 v55, vcc, 0, v55, vcc
	s_nop 0
	v_cmp_le_u32 vcc, v54, v44
	v_addc_co_u32 v55, vcc, 0, v55, vcc
	s_nop 0
	v_cmp_le_u32 vcc, v54, v43
	v_addc_co_u32 v55, vcc, 0, v55, vcc
	s_nop 0
	v_cmp_le_u32 vcc, v54, v42
	v_addc_co_u32 v55, vcc, 0, v55, vcc
	s_nop 0
	s_cmp_le_u32 s100, 120
	s_cbranch_scc1 .Lp12_pe_0
	v_cmp_le_u32 vcc, v54, v41
	v_addc_co_u32 v55, vcc, 0, v55, vcc
	s_nop 0
	v_cmp_le_u32 vcc, v54, v40
	v_addc_co_u32 v55, vcc, 0, v55, vcc
	s_nop 0
	v_cmp_le_u32 vcc, v54, v39
	v_addc_co_u32 v55, vcc, 0, v55, vcc
	s_nop 0
	v_cmp_le_u32 vcc, v54, v38
	v_addc_co_u32 v55, vcc, 0, v55, vcc
	s_nop 0
	v_cmp_le_u32 vcc, v54, v37
	v_addc_co_u32 v55, vcc, 0, v55, vcc
	s_nop 0
	v_cmp_le_u32 vcc, v54, v36
	v_addc_co_u32 v55, vcc, 0, v55, vcc
	s_nop 0
	v_cmp_le_u32 vcc, v54, v35
	v_addc_co_u32 v55, vcc, 0, v55, vcc
	s_nop 0
	v_cmp_le_u32 vcc, v54, v0
	v_addc_co_u32 v55, vcc, 0, v55, vcc
.Lp12_pe_0:
	s_nop 1
	v_add_u32_dpp v55, v55, v55 quad_perm:[1,0,3,2] row_mask:0xf bank_mask:0xf bound_ctrl:1
	s_nop 1
	v_add_u32_dpp v55, v55, v55 quad_perm:[2,3,0,1] row_mask:0xf bank_mask:0xf bound_ctrl:1
	s_nop 1
	v_add_u32_dpp v55, v55, v55 row_half_mirror row_mask:0xf bank_mask:0xf bound_ctrl:1
	s_nop 1
	v_add_u32_dpp v55, v55, v55 row_mirror row_mask:0xf bank_mask:0xf bound_ctrl:1
	s_nop 0
	v_readlane_b32 s0, v55, 0
	v_readlane_b32 s1, v55, 16
	s_add_i32 s0, s1, s0
	v_readlane_b32 s1, v55, 32
	s_add_i32 s0, s0, s1
	v_readlane_b32 s1, v55, 48
	s_add_i32 s0, s0, s1
	s_cmpk_gt_i32 s0, 0xff
	s_cselect_b64 vcc, -1, 0
	s_cmpk_eq_i32 s0, 0x100
	v_cndmask_b32_e32 v34, v34, v54, vcc
	s_cselect_b64 s[0:1], -1, 0
	v_subrev_co_u32_e32 v53, vcc, 1, v53
	s_or_b64 s[0:1], s[0:1], vcc
	s_andn2_b64 vcc, exec, s[0:1]
	s_cbranch_vccnz .LBB0_1969
	v_cmp_gt_u32_e32 vcc, v141, v34
	s_and_saveexec_b64 s[0:1], vcc
	s_nop 0
	v_mbcnt_lo_u32_b32 v53, vcc_lo, 0
	v_mbcnt_hi_u32_b32 v53, vcc_hi, v53
	v_lshl_add_u32 v53, v53, 2, s20
	ds_write_b32 v53, v2
	s_or_b64 exec, exec, s[0:1]
	s_bcnt1_i32_b64 s2, vcc
	v_cmp_gt_u32_e32 vcc, v140, v34
	s_and_saveexec_b64 s[0:1], vcc
	s_cbranch_execz .LBB0_1974
	s_lshl_b32 s3, s2, 2
	v_mbcnt_lo_u32_b32 v53, vcc_lo, 0
	s_add_i32 s3, s20, s3
	v_mbcnt_hi_u32_b32 v53, vcc_hi, v53
	v_lshl_add_u32 v53, v53, 2, s3
	ds_write_b32 v53, v4

; DI unsigned f2key(float f) { const unsigned u = __float_as_uint(f); return (u & 0x80000000u) ? ~u : (u | 0x80000000u); }
; template <int NV>
; DI void topk_row(const float* row, int s, LAS int* lst, int lane) {
;     ...
;     for (int jo = 0; jo < NV / 16; ++jo) { const float* rb = row + jo * 1024;
; #pragma unroll
;         for (int ji = 0; ji < 16; ++ji) { const int j = jo * 16 + ji; const unsigned u = f2key(rb[ji * 64 + lane]); key[j] = (j * 64 + lane <= s) ? u : 0u; } }
.LBB0_2483:
	s_mov_b64 s[0:1], 0
	v_mov_b32_e32 v34, v159
	s_cbranch_execz .LBB0_2869
	v_lshlrev_b32_e32 v0, 2, v2
	v_lshl_add_u64 v[40:41], s[12:13], 0, v[0:1]
	flat_load_dword v48, v[40:41]
	flat_load_dword v49, v[40:41] offset:256
	flat_load_dword v50, v[40:41] offset:512
	flat_load_dword v51, v[40:41] offset:768
	flat_load_dword v52, v[40:41] offset:1024
	flat_load_dword v53, v[40:41] offset:1280
	flat_load_dword v54, v[40:41] offset:1536
	flat_load_dword v55, v[40:41] offset:1792
	flat_load_dword v56, v[40:41] offset:2048
	flat_load_dword v57, v[40:41] offset:2304
	flat_load_dword v58, v[40:41] offset:2560
	flat_load_dword v59, v[40:41] offset:2816
	flat_load_dword v60, v[40:41] offset:3072
	flat_load_dword v128, v[40:41] offset:3328
	s_add_u32 s0, s12, 0x1000
	s_addc_u32 s1, s13, 0
	v_lshlrev_b32_e32 v38, 2, v4
	v_mov_b32_e32 v39, v1
	v_lshlrev_b32_e32 v36, 2, v6
	v_mov_b32_e32 v37, v1
	v_lshlrev_b32_e32 v34, 2, v8
	flat_load_dword v129, v[40:41] offset:3584
	flat_load_dword v130, v[40:41] offset:3840
	v_mov_b32_e32 v35, v1
	v_lshl_add_u64 v[40:41], s[0:1], 0, v[0:1]
	v_lshl_add_u64 v[42:43], s[0:1], 0, v[38:39]
	v_lshl_add_u64 v[44:45], s[0:1], 0, v[36:37]
	v_lshl_add_u64 v[46:47], s[0:1], 0, v[34:35]
	flat_load_dword v131, v[40:41]
	flat_load_dword v132, v[42:43]
	flat_load_dword v133, v[44:45]
	flat_load_dword v134, v[46:47]
	s_movk_i32 s2, 0xfff
	s_waitcnt vmcnt(0) lgkmcnt(0)
	v_not_b32_e32 v40, v48
	v_or_b32_e32 v41, 0x80000000, v48
	v_cmp_gt_i32_e32 vcc, 0, v48
	v_not_b32_e32 v42, v49
	v_or_b32_e32 v43, 0x80000000, v49
	v_cndmask_b32_e32 v221, v41, v40, vcc
	v_cmp_gt_i32_e32 vcc, 0, v49
	v_not_b32_e32 v44, v50
	v_or_b32_e32 v45, 0x80000000, v50
	v_cndmask_b32_e32 v220, v43, v42, vcc
	v_cmp_gt_i32_e32 vcc, 0, v50
	v_not_b32_e32 v46, v51
	v_or_b32_e32 v47, 0x80000000, v51
	v_cndmask_b32_e32 v219, v45, v44, vcc
	v_cmp_gt_i32_e32 vcc, 0, v51
	v_not_b32_e32 v61, v52
	v_or_b32_e32 v62, 0x80000000, v52
	v_cndmask_b32_e32 v218, v47, v46, vcc
	v_cmp_gt_i32_e32 vcc, 0, v52
	v_not_b32_e32 v63, v53
	v_or_b32_e32 v135, 0x80000000, v53
	v_cndmask_b32_e32 v217, v62, v61, vcc
	v_cmp_gt_i32_e32 vcc, 0, v53
	v_not_b32_e32 v136, v54
	v_or_b32_e32 v137, 0x80000000, v54
	v_cndmask_b32_e32 v216, v135, v63, vcc
	v_cmp_gt_i32_e32 vcc, 0, v54
	v_not_b32_e32 v138, v55
	v_or_b32_e32 v139, 0x80000000, v55
	v_cndmask_b32_e32 v215, v137, v136, vcc
	v_cmp_gt_i32_e32 vcc, 0, v55
	v_not_b32_e32 v140, v56
	v_or_b32_e32 v141, 0x80000000, v56
	v_cndmask_b32_e32 v214, v139, v138, vcc
	v_cmp_gt_i32_e32 vcc, 0, v56
	v_not_b32_e32 v162, v57
	v_or_b32_e32 v163, 0x80000000, v57
	v_cndmask_b32_e32 v213, v141, v140, vcc
	v_cmp_gt_i32_e32 vcc, 0, v57
	v_not_b32_e32 v164, v58
	v_or_b32_e32 v165, 0x80000000, v58
	v_cndmask_b32_e32 v211, v163, v162, vcc
	v_cmp_gt_i32_e32 vcc, 0, v58
	v_lshlrev_b32_e32 v62, 2, v10
	v_mov_b32_e32 v63, v1
	v_not_b32_e32 v166, v59
	v_or_b32_e32 v167, 0x80000000, v59
	v_cndmask_b32_e32 v206, v165, v164, vcc
	v_cmp_gt_i32_e32 vcc, 0, v59
	v_lshl_add_u64 v[40:41], s[0:1], 0, v[62:63]
	v_not_b32_e32 v168, v60
	v_or_b32_e32 v169, 0x80000000, v60
	v_cndmask_b32_e32 v203, v167, v166, vcc
	flat_load_dword v135, v[40:41]
	v_cmp_gt_i32_e32 vcc, 0, v60
	v_lshlrev_b32_e32 v60, 2, v12
	v_mov_b32_e32 v61, v1
	v_lshl_add_u64 v[40:41], s[0:1], 0, v[60:61]
	flat_load_dword v136, v[40:41]
	v_lshlrev_b32_e32 v58, 2, v14
	v_mov_b32_e32 v59, v1
	v_lshl_add_u64 v[40:41], s[0:1], 0, v[58:59]
	v_lshlrev_b32_e32 v56, 2, v16
	v_mov_b32_e32 v57, v1
	flat_load_dword v137, v[40:41]
	v_lshl_add_u64 v[40:41], s[0:1], 0, v[56:57]
	flat_load_dword v138, v[40:41]
	v_lshlrev_b32_e32 v54, 2, v18
	v_mov_b32_e32 v55, v1
	v_lshl_add_u64 v[40:41], s[0:1], 0, v[54:55]
	v_lshlrev_b32_e32 v52, 2, v20
	v_mov_b32_e32 v53, v1
	flat_load_dword v139, v[40:41]
	v_lshl_add_u64 v[40:41], s[0:1], 0, v[52:53]
	flat_load_dword v140, v[40:41]
	v_lshlrev_b32_e32 v50, 2, v22
	v_mov_b32_e32 v51, v1
	v_lshl_add_u64 v[40:41], s[0:1], 0, v[50:51]
	flat_load_dword v141, v[40:41]
	v_cndmask_b32_e32 v200, v169, v168, vcc
	v_not_b32_e32 v42, v128
	v_or_b32_e32 v43, 0x80000000, v128
	v_cmp_gt_i32_e32 vcc, 0, v128
	v_lshlrev_b32_e32 v48, 2, v24
	v_mov_b32_e32 v49, v1
	v_cndmask_b32_e32 v202, v43, v42, vcc
	v_not_b32_e32 v42, v129
	v_or_b32_e32 v43, 0x80000000, v129
	v_cmp_gt_i32_e32 vcc, 0, v129
	v_lshl_add_u64 v[40:41], s[0:1], 0, v[48:49]
	v_lshlrev_b32_e32 v46, 2, v26
	v_mov_b32_e32 v47, v1
	v_cndmask_b32_e32 v204, v43, v42, vcc
	v_not_b32_e32 v42, v130
	v_or_b32_e32 v43, 0x80000000, v130
	v_cmp_gt_i32_e32 vcc, 0, v130
	flat_load_dword v130, v[40:41]
	v_lshl_add_u64 v[40:41], s[0:1], 0, v[46:47]
	v_lshlrev_b32_e32 v44, 2, v28
	v_mov_b32_e32 v45, v1
	v_cndmask_b32_e32 v207, v43, v42, vcc
	v_not_b32_e32 v42, v131
	v_or_b32_e32 v43, 0x80000000, v131
	flat_load_dword v162, v[40:41]
	v_cmp_gt_i32_e32 vcc, 0, v131
	v_lshl_add_u64 v[40:41], s[0:1], 0, v[44:45]
	flat_load_dword v163, v[40:41]
	v_cndmask_b32_e32 v208, v43, v42, vcc
	v_lshlrev_b32_e32 v42, 2, v30
	v_mov_b32_e32 v43, v1
	v_lshl_add_u64 v[40:41], s[0:1], 0, v[42:43]
	flat_load_dword v164, v[40:41]
	v_lshlrev_b32_e32 v40, 2, v32
	v_mov_b32_e32 v41, v1
	v_lshl_add_u64 v[128:129], s[0:1], 0, v[40:41]
	s_add_u32 s0, s12, 0x2000
	flat_load_dword v166, v[128:129]
	s_addc_u32 s1, s13, 0
	v_not_b32_e32 v131, v132
	v_or_b32_e32 v165, 0x80000000, v132
	v_cmp_gt_i32_e32 vcc, 0, v132
	v_lshl_add_u64 v[128:129], s[0:1], 0, v[0:1]
	flat_load_dword v132, v[128:129]
	v_cndmask_b32_e32 v212, v165, v131, vcc
	v_not_b32_e32 v131, v133
	v_or_b32_e32 v128, 0x80000000, v133
	v_cmp_gt_i32_e32 vcc, 0, v133
	s_nop 1
	v_cndmask_b32_e32 v210, v128, v131, vcc
	v_lshl_add_u64 v[128:129], s[0:1], 0, v[38:39]
	v_not_b32_e32 v131, v134
	flat_load_dword v133, v[128:129]
	v_or_b32_e32 v128, 0x80000000, v134
	v_cmp_gt_i32_e32 vcc, 0, v134
	s_nop 1
	v_cndmask_b32_e32 v209, v128, v131, vcc
	v_lshl_add_u64 v[128:129], s[0:1], 0, v[36:37]
	s_waitcnt vmcnt(0) lgkmcnt(0)
; DI unsigned f2key(float f) { const unsigned u = __float_as_uint(f); return (u & 0x80000000u) ? ~u : (u | 0x80000000u); }
; template <int NV>
; DI void topk_row(const float* row, int s, LAS int* lst, int lane) {
;     ...
;     for (int jo = 0; jo < NV / 16; ++jo) { const float* rb = row + jo * 1024;
; #pragma unroll
;         for (int ji = 0; ji < 16; ++ji) { const int j = jo * 16 + ji; const unsigned u = f2key(rb[ji * 64 + lane]); key[j] = (j * 64 + lane <= s) ? u : 0u; } }
	v_not_b32_e32 v131, v135
	flat_load_dword v134, v[128:129]
	v_or_b32_e32 v128, 0x80000000, v135
	v_cmp_gt_i32_e32 vcc, 0, v135
	s_nop 1
	v_cndmask_b32_e32 v205, v128, v131, vcc
	v_lshl_add_u64 v[128:129], s[0:1], 0, v[34:35]
	v_not_b32_e32 v131, v136
	flat_load_dword v135, v[128:129]
	v_or_b32_e32 v128, 0x80000000, v136
	v_cmp_gt_i32_e32 vcc, 0, v136
	v_or_b32_e32 v136, 0x80000000, v137
	s_nop 0
	v_cndmask_b32_e32 v201, v128, v131, vcc
	v_lshl_add_u64 v[128:129], s[0:1], 0, v[62:63]
	flat_load_dword v165, v[128:129]
	v_not_b32_e32 v131, v137
	v_cmp_gt_i32_e32 vcc, 0, v137
	v_lshl_add_u64 v[128:129], s[0:1], 0, v[60:61]
	v_or_b32_e32 v137, 0x80000000, v139
	v_cndmask_b32_e32 v199, v136, v131, vcc
	v_not_b32_e32 v131, v138
	flat_load_dword v136, v[128:129]
	v_or_b32_e32 v128, 0x80000000, v138
	v_cmp_gt_i32_e32 vcc, 0, v138
	s_nop 1
	v_cndmask_b32_e32 v198, v128, v131, vcc
	v_lshl_add_u64 v[128:129], s[0:1], 0, v[58:59]
	flat_load_dword v138, v[128:129]
	v_lshl_add_u64 v[128:129], s[0:1], 0, v[56:57]
	v_not_b32_e32 v131, v139
	v_cmp_gt_i32_e32 vcc, 0, v139
	flat_load_dword v139, v[128:129]
	v_lshl_add_u64 v[128:129], s[0:1], 0, v[54:55]
	v_cndmask_b32_e32 v197, v137, v131, vcc
	v_not_b32_e32 v131, v140
	v_or_b32_e32 v137, 0x80000000, v140
	v_cmp_gt_i32_e32 vcc, 0, v140
	flat_load_dword v140, v[128:129]
	v_lshl_add_u64 v[128:129], s[0:1], 0, v[52:53]
	v_cndmask_b32_e32 v196, v137, v131, vcc
	v_not_b32_e32 v131, v141
	v_or_b32_e32 v137, 0x80000000, v141
	v_cmp_gt_i32_e32 vcc, 0, v141
	flat_load_dword v141, v[128:129]
	v_lshl_add_u64 v[128:129], s[0:1], 0, v[50:51]
	v_cndmask_b32_e32 v195, v137, v131, vcc
	v_not_b32_e32 v131, v130
	v_or_b32_e32 v137, 0x80000000, v130
	v_cmp_gt_i32_e32 vcc, 0, v130
	v_not_b32_e32 v130, v162
	s_nop 0
	v_cndmask_b32_e32 v194, v137, v131, vcc
	v_or_b32_e32 v131, 0x80000000, v162
	v_cmp_gt_i32_e32 vcc, 0, v162
	flat_load_dword v137, v[128:129]
	v_not_b32_e32 v128, v163
	v_cndmask_b32_e32 v193, v131, v130, vcc
	v_or_b32_e32 v129, 0x80000000, v163
	v_cmp_gt_i32_e32 vcc, 0, v163
	v_not_b32_e32 v130, v164
	s_nop 0
	v_cndmask_b32_e32 v192, v129, v128, vcc
	v_lshl_add_u64 v[128:129], s[0:1], 0, v[48:49]
	flat_load_dword v131, v[128:129]
	v_or_b32_e32 v128, 0x80000000, v164
	v_cmp_gt_i32_e32 vcc, 0, v164
	s_nop 1
	v_cndmask_b32_e32 v191, v128, v130, vcc
	v_lshl_add_u64 v[128:129], s[0:1], 0, v[46:47]
	v_not_b32_e32 v130, v166
	flat_load_dword v162, v[128:129]
	v_or_b32_e32 v128, 0x80000000, v166
	v_cmp_gt_i32_e32 vcc, 0, v166
	s_nop 1
	v_cndmask_b32_e32 v190, v128, v130, vcc
	v_lshl_add_u64 v[128:129], s[0:1], 0, v[44:45]
	flat_load_dword v163, v[128:129]
	v_not_b32_e32 v130, v132
	v_or_b32_e32 v128, 0x80000000, v132
	v_cmp_gt_i32_e32 vcc, 0, v132
	s_nop 1
	v_cndmask_b32_e32 v189, v128, v130, vcc
	v_lshl_add_u64 v[128:129], s[0:1], 0, v[42:43]
	v_not_b32_e32 v130, v133
	flat_load_dword v132, v[128:129]
	v_or_b32_e32 v128, 0x80000000, v133
	v_cmp_gt_i32_e32 vcc, 0, v133
	s_waitcnt vmcnt(0) lgkmcnt(0)
	v_or_b32_e32 v133, 0x80000000, v134
	v_cndmask_b32_e32 v188, v128, v130, vcc
	v_lshl_add_u64 v[128:129], s[0:1], 0, v[40:41]
	s_add_u32 s0, s12, 0x3000
	s_addc_u32 s1, s13, 0
	v_not_b32_e32 v130, v134
	flat_load_dword v164, v[128:129]
	v_cmp_gt_i32_e32 vcc, 0, v134
	v_lshl_add_u64 v[128:129], s[0:1], 0, v[0:1]
	s_nop 0
	v_cndmask_b32_e32 v187, v133, v130, vcc
	v_not_b32_e32 v130, v135
	flat_load_dword v133, v[128:129]
	v_or_b32_e32 v128, 0x80000000, v135
	v_cmp_gt_i32_e32 vcc, 0, v135
	v_or_b32_e32 v129, 0x80000000, v165
	v_or_b32_e32 v135, 0x80000000, v136
	v_cndmask_b32_e32 v186, v128, v130, vcc
	v_not_b32_e32 v128, v165
	v_cmp_gt_i32_e32 vcc, 0, v165
	v_not_b32_e32 v130, v136
	s_nop 0
	v_cndmask_b32_e32 v185, v129, v128, vcc
	v_lshl_add_u64 v[128:129], s[0:1], 0, v[38:39]
	flat_load_dword v134, v[128:129]
	v_lshl_add_u64 v[128:129], s[0:1], 0, v[36:37]
	flat_load_dword v165, v[128:129]
	v_cmp_gt_i32_e32 vcc, 0, v136
	v_lshl_add_u64 v[128:129], s[0:1], 0, v[34:35]
	flat_load_dword v136, v[128:129]
	v_cndmask_b32_e32 v184, v135, v130, vcc
	v_not_b32_e32 v130, v138
	v_or_b32_e32 v135, 0x80000000, v138
	v_cmp_gt_i32_e32 vcc, 0, v138
	v_lshl_add_u64 v[128:129], s[0:1], 0, v[62:63]
	flat_load_dword v138, v[128:129]
	v_cndmask_b32_e32 v183, v135, v130, vcc
	v_not_b32_e32 v130, v139
	v_or_b32_e32 v135, 0x80000000, v139
	v_cmp_gt_i32_e32 vcc, 0, v139
	v_lshl_add_u64 v[128:129], s[0:1], 0, v[60:61]
	s_nop 0
	v_cndmask_b32_e32 v182, v135, v130, vcc
	v_not_b32_e32 v130, v140
	flat_load_dword v135, v[128:129]
	v_or_b32_e32 v128, 0x80000000, v140
	v_cmp_gt_i32_e32 vcc, 0, v140
	s_nop 1
	v_cndmask_b32_e32 v181, v128, v130, vcc
	v_lshl_add_u64 v[128:129], s[0:1], 0, v[58:59]
	v_not_b32_e32 v130, v141
	flat_load_dword v139, v[128:129]
	v_or_b32_e32 v128, 0x80000000, v141
	v_cmp_gt_i32_e32 vcc, 0, v141
	v_or_b32_e32 v141, 0x80000000, v137
	s_nop 0
	v_cndmask_b32_e32 v180, v128, v130, vcc
	v_lshl_add_u64 v[128:129], s[0:1], 0, v[56:57]
	flat_load_dword v140, v[128:129]
	v_lshl_add_u64 v[128:129], s[0:1], 0, v[54:55]
	flat_load_dword v222, v[128:129]
	v_not_b32_e32 v130, v137
	v_cmp_gt_i32_e32 vcc, 0, v137
	v_lshl_add_u64 v[128:129], s[0:1], 0, v[52:53]
	v_or_b32_e32 v137, 0x80000000, v131
	v_cndmask_b32_e32 v179, v141, v130, vcc
	v_not_b32_e32 v130, v131
	flat_load_dword v141, v[128:129]
	v_cmp_gt_i32_e32 vcc, 0, v131
	v_lshl_add_u64 v[128:129], s[0:1], 0, v[50:51]
	v_or_b32_e32 v131, 0x80000000, v162
	v_cndmask_b32_e32 v178, v137, v130, vcc
	v_not_b32_e32 v130, v162
	flat_load_dword v137, v[128:129]
	v_cmp_gt_i32_e32 vcc, 0, v162
	v_lshl_add_u64 v[128:129], s[0:1], 0, v[48:49]
	v_or_b32_e32 v162, 0x80000000, v132
	v_cndmask_b32_e32 v177, v131, v130, vcc
	v_not_b32_e32 v130, v163
	flat_load_dword v131, v[128:129]
	v_or_b32_e32 v128, 0x80000000, v163
	v_cmp_gt_i32_e32 vcc, 0, v163
	s_nop 1
	v_cndmask_b32_e32 v176, v128, v130, vcc
	v_lshl_add_u64 v[128:129], s[0:1], 0, v[46:47]
	flat_load_dword v223, v[128:129]
	v_lshl_add_u64 v[128:129], s[0:1], 0, v[44:45]
	flat_load_dword v224, v[128:129]
	v_lshl_add_u64 v[128:129], s[0:1], 0, v[42:43]
	flat_load_dword v225, v[128:129]
	v_lshl_add_u64 v[128:129], s[0:1], 0, v[40:41]
	s_add_u32 s0, s12, 0x4000
	v_not_b32_e32 v130, v132
	v_cmp_gt_i32_e32 vcc, 0, v132
	flat_load_dword v226, v[128:129]
	s_addc_u32 s1, s13, 0
	v_cndmask_b32_e32 v175, v162, v130, vcc
	s_waitcnt vmcnt(0) lgkmcnt(0)
; DI unsigned f2key(float f) { const unsigned u = __float_as_uint(f); return (u & 0x80000000u) ? ~u : (u | 0x80000000u); }
; template <int NV>
; DI void topk_row(const float* row, int s, LAS int* lst, int lane) {
;     ...
;     for (int jo = 0; jo < NV / 16; ++jo) { const float* rb = row + jo * 1024;
; #pragma unroll
;         for (int ji = 0; ji < 16; ++ji) { const int j = jo * 16 + ji; const unsigned u = f2key(rb[ji * 64 + lane]); key[j] = (j * 64 + lane <= s) ? u : 0u; } }
	v_not_b32_e32 v130, v164
	v_or_b32_e32 v132, 0x80000000, v164
	v_cmp_gt_i32_e32 vcc, 0, v164
	v_lshl_add_u64 v[128:129], s[0:1], 0, v[0:1]
	flat_load_dword v227, v[128:129]
	v_cndmask_b32_e32 v173, v132, v130, vcc
	v_not_b32_e32 v130, v133
	v_or_b32_e32 v132, 0x80000000, v133
	v_cmp_gt_i32_e32 vcc, 0, v133
	v_not_b32_e32 v128, v134
	v_or_b32_e32 v129, 0x80000000, v134
	v_cndmask_b32_e32 v174, v132, v130, vcc
	v_cmp_gt_i32_e32 vcc, 0, v134
	v_not_b32_e32 v130, v165
	v_or_b32_e32 v133, 0x80000000, v136
	v_cndmask_b32_e32 v172, v129, v128, vcc
	v_lshl_add_u64 v[128:129], s[0:1], 0, v[38:39]
	flat_load_dword v132, v[128:129]
	v_or_b32_e32 v128, 0x80000000, v165
	v_cmp_gt_i32_e32 vcc, 0, v165
	s_nop 1
	v_cndmask_b32_e32 v171, v128, v130, vcc
	v_not_b32_e32 v130, v136
	v_lshl_add_u64 v[128:129], s[0:1], 0, v[36:37]
	v_cmp_gt_i32_e32 vcc, 0, v136
	flat_load_dword v134, v[128:129]
	v_not_b32_e32 v128, v138
	v_cndmask_b32_e32 v170, v133, v130, vcc
	v_or_b32_e32 v129, 0x80000000, v138
	v_cmp_gt_i32_e32 vcc, 0, v138
	v_not_b32_e32 v130, v135
	s_nop 0
	v_cndmask_b32_e32 v169, v129, v128, vcc
	v_lshl_add_u64 v[128:129], s[0:1], 0, v[34:35]
	flat_load_dword v133, v[128:129]
	v_or_b32_e32 v128, 0x80000000, v135
	v_cmp_gt_i32_e32 vcc, 0, v135
	v_or_b32_e32 v135, 0x80000000, v139
	s_nop 0
	v_cndmask_b32_e32 v168, v128, v130, vcc
	v_not_b32_e32 v130, v139
	v_lshl_add_u64 v[128:129], s[0:1], 0, v[62:63]
	v_cmp_gt_i32_e32 vcc, 0, v139
	flat_load_dword v228, v[128:129]
	v_not_b32_e32 v128, v140
	v_cndmask_b32_e32 v167, v135, v130, vcc
	v_or_b32_e32 v129, 0x80000000, v140
	v_cmp_gt_i32_e32 vcc, 0, v140
	v_not_b32_e32 v130, v222
	v_or_b32_e32 v135, 0x80000000, v141
	v_cndmask_b32_e32 v166, v129, v128, vcc
	v_lshl_add_u64 v[128:129], s[0:1], 0, v[60:61]
	flat_load_dword v229, v[128:129]
	v_or_b32_e32 v128, 0x80000000, v222
	v_cmp_gt_i32_e32 vcc, 0, v222
	s_nop 1
	v_cndmask_b32_e32 v165, v128, v130, vcc
	v_lshl_add_u64 v[128:129], s[0:1], 0, v[58:59]
	flat_load_dword v222, v[128:129]
	v_not_b32_e32 v130, v141
	v_cmp_gt_i32_e32 vcc, 0, v141
	v_not_b32_e32 v128, v137
	v_or_b32_e32 v129, 0x80000000, v137
	v_cndmask_b32_e32 v164, v135, v130, vcc
	v_cmp_gt_i32_e32 vcc, 0, v137
	v_not_b32_e32 v130, v131
	v_or_b32_e32 v135, 0x80000000, v131
	v_cndmask_b32_e32 v163, v129, v128, vcc
	v_lshl_add_u64 v[128:129], s[0:1], 0, v[56:57]
	v_cmp_gt_i32_e32 vcc, 0, v131
	flat_load_dword v230, v[128:129]
	v_not_b32_e32 v128, v223
	v_cndmask_b32_e32 v162, v135, v130, vcc
	v_or_b32_e32 v129, 0x80000000, v223
	v_cmp_gt_i32_e32 vcc, 0, v223
	v_not_b32_e32 v130, v224
	s_waitcnt vmcnt(0) lgkmcnt(0)
	v_or_b32_e32 v131, 0x80000000, v134
	v_cndmask_b32_e32 v141, v129, v128, vcc
	v_lshl_add_u64 v[128:129], s[0:1], 0, v[54:55]
	flat_load_dword v223, v[128:129]
	v_or_b32_e32 v128, 0x80000000, v224
	v_cmp_gt_i32_e32 vcc, 0, v224
	s_nop 1
	v_cndmask_b32_e32 v140, v128, v130, vcc
	v_lshl_add_u64 v[128:129], s[0:1], 0, v[52:53]
	v_not_b32_e32 v130, v225
	flat_load_dword v224, v[128:129]
	v_or_b32_e32 v128, 0x80000000, v225
	v_cmp_gt_i32_e32 vcc, 0, v225
	v_or_b32_e32 v129, 0x80000000, v226
	s_nop 0
	v_cndmask_b32_e32 v139, v128, v130, vcc
	v_not_b32_e32 v128, v226
	v_cmp_gt_i32_e32 vcc, 0, v226
	v_not_b32_e32 v130, v227
	s_nop 0
	v_cndmask_b32_e32 v138, v129, v128, vcc
	v_lshl_add_u64 v[128:129], s[0:1], 0, v[50:51]
	flat_load_dword v225, v[128:129]
	v_or_b32_e32 v128, 0x80000000, v227
	v_cmp_gt_i32_e32 vcc, 0, v227
	s_nop 1
	v_cndmask_b32_e32 v128, v128, v130, vcc
	v_cmp_lt_u32_e32 vcc, s2, v161
	v_not_b32_e32 v130, v132
	s_movk_i32 s2, 0x103f
	v_cndmask_b32_e32 v137, 0, v128, vcc
	v_lshl_add_u64 v[128:129], s[0:1], 0, v[48:49]
	flat_load_dword v226, v[128:129]
	v_or_b32_e32 v128, 0x80000000, v132
	v_cmp_gt_i32_e32 vcc, 0, v132
	s_nop 1
	v_cndmask_b32_e32 v128, v128, v130, vcc
	v_cmp_lt_u32_e32 vcc, s2, v161
	v_not_b32_e32 v130, v134
	s_movk_i32 s2, 0x107f
	v_cndmask_b32_e32 v136, 0, v128, vcc
	v_lshl_add_u64 v[128:129], s[0:1], 0, v[46:47]
	flat_load_dword v227, v[128:129]
	v_cmp_gt_i32_e32 vcc, 0, v134
	s_nop 1
	v_cndmask_b32_e32 v128, v131, v130, vcc
	v_cmp_lt_u32_e32 vcc, s2, v161
	v_not_b32_e32 v130, v133
	v_or_b32_e32 v131, 0x80000000, v133
	v_cndmask_b32_e32 v135, 0, v128, vcc
	v_lshl_add_u64 v[128:129], s[0:1], 0, v[44:45]
	v_cmp_gt_i32_e32 vcc, 0, v133
	s_movk_i32 s2, 0x10bf
	flat_load_dword v231, v[128:129]
	v_cndmask_b32_e32 v128, v131, v130, vcc
	v_cmp_lt_u32_e32 vcc, s2, v161
	v_or_b32_e32 v129, 0x80000000, v228
	s_movk_i32 s2, 0x10ff
	v_cndmask_b32_e32 v134, 0, v128, vcc
	v_not_b32_e32 v128, v228
	v_cmp_gt_i32_e32 vcc, 0, v228
	s_nop 1
	v_cndmask_b32_e32 v130, v129, v128, vcc
	v_lshl_add_u64 v[128:129], s[0:1], 0, v[42:43]
	v_cmp_lt_u32_e32 vcc, s2, v161
	flat_load_dword v228, v[128:129]
	v_not_b32_e32 v128, v229
	v_cndmask_b32_e32 v132, 0, v130, vcc
	v_or_b32_e32 v129, 0x80000000, v229
	v_cmp_gt_i32_e32 vcc, 0, v229
	s_movk_i32 s2, 0x117f
	s_nop 0
	v_cndmask_b32_e32 v130, v129, v128, vcc
	v_lshl_add_u64 v[128:129], s[0:1], 0, v[40:41]
	s_movk_i32 s0, 0x113f
	v_cmp_lt_u32_e32 vcc, s0, v161
	s_add_u32 s0, s12, 0x5000
	flat_load_dword v229, v[128:129]
	s_addc_u32 s1, s13, 0
	v_lshl_add_u64 v[38:39], s[0:1], 0, v[38:39]
	v_cndmask_b32_e32 v130, 0, v130, vcc
	v_cmp_gt_i32_e32 vcc, 0, v222
	flat_load_dword v38, v[38:39]
	v_not_b32_e32 v128, v222
	v_or_b32_e32 v129, 0x80000000, v222
	v_cndmask_b32_e32 v131, v129, v128, vcc
	v_lshl_add_u64 v[128:129], s[0:1], 0, v[0:1]
	flat_load_dword v0, v[128:129]
	v_cmp_lt_u32_e32 vcc, s2, v161
	v_not_b32_e32 v128, v230
	v_or_b32_e32 v129, 0x80000000, v230
	v_cndmask_b32_e32 v133, 0, v131, vcc
	v_cmp_gt_i32_e32 vcc, 0, v230
	s_movk_i32 s2, 0x11bf
	v_lshl_add_u64 v[36:37], s[0:1], 0, v[36:37]
	v_cndmask_b32_e32 v128, v129, v128, vcc
	v_cmp_lt_u32_e32 vcc, s2, v161
	s_movk_i32 s2, 0x11ff
	flat_load_dword v36, v[36:37]
	v_cndmask_b32_e32 v131, 0, v128, vcc
	s_waitcnt vmcnt(0) lgkmcnt(0)
; DI unsigned f2key(float f) { const unsigned u = __float_as_uint(f); return (u & 0x80000000u) ? ~u : (u | 0x80000000u); }
; template <int NV>
; DI void topk_row(const float* row, int s, LAS int* lst, int lane) {
;     ...
;     for (int jo = 0; jo < NV / 16; ++jo) { const float* rb = row + jo * 1024;
; #pragma unroll
;         for (int ji = 0; ji < 16; ++ji) { const int j = jo * 16 + ji; const unsigned u = f2key(rb[ji * 64 + lane]); key[j] = (j * 64 + lane <= s) ? u : 0u; } }
;     unsigned T = 0u;
; #pragma unroll 1
	v_not_b32_e32 v39, v223
	v_or_b32_e32 v128, 0x80000000, v223
	v_cmp_gt_i32_e32 vcc, 0, v223
	v_or_b32_e32 v37, 0x80000000, v224
	v_lshl_add_u64 v[34:35], s[0:1], 0, v[34:35]
	v_cndmask_b32_e32 v39, v128, v39, vcc
	v_cmp_lt_u32_e32 vcc, s2, v161
	s_movk_i32 s2, 0x123f
	v_or_b32_e32 v222, 0x80000000, v225
	v_cndmask_b32_e32 v128, 0, v39, vcc
	v_not_b32_e32 v39, v224
	v_cmp_gt_i32_e32 vcc, 0, v224
	s_nop 1
	v_cndmask_b32_e32 v37, v37, v39, vcc
	flat_load_dword v39, v[34:35]
	v_cmp_lt_u32_e32 vcc, s2, v161
	v_lshl_add_u64 v[34:35], s[0:1], 0, v[62:63]
	s_movk_i32 s2, 0x127f
	v_cndmask_b32_e32 v129, 0, v37, vcc
	v_not_b32_e32 v37, v225
	v_cmp_gt_i32_e32 vcc, 0, v225
	flat_load_dword v63, v[34:35]
	s_nop 0
	v_cndmask_b32_e32 v34, v222, v37, vcc
	v_cmp_lt_u32_e32 vcc, s2, v161
	v_not_b32_e32 v37, v226
	s_movk_i32 s2, 0x12bf
	v_cndmask_b32_e32 v62, 0, v34, vcc
	v_lshl_add_u64 v[34:35], s[0:1], 0, v[60:61]
	flat_load_dword v60, v[34:35]
	v_or_b32_e32 v34, 0x80000000, v226
	v_cmp_gt_i32_e32 vcc, 0, v226
	v_or_b32_e32 v61, 0x80000000, v227
	s_nop 0
	v_cndmask_b32_e32 v37, v34, v37, vcc
	v_lshl_add_u64 v[34:35], s[0:1], 0, v[58:59]
	flat_load_dword v59, v[34:35]
	v_cmp_lt_u32_e32 vcc, s2, v161
	v_lshl_add_u64 v[34:35], s[0:1], 0, v[56:57]
	s_movk_i32 s2, 0x12ff
	v_cndmask_b32_e32 v58, 0, v37, vcc
	v_not_b32_e32 v37, v227
	v_cmp_gt_i32_e32 vcc, 0, v227
	flat_load_dword v57, v[34:35]
	s_nop 0
	v_cndmask_b32_e32 v34, v61, v37, vcc
	v_cmp_lt_u32_e32 vcc, s2, v161
	v_not_b32_e32 v37, v231
	s_movk_i32 s2, 0x133f
	v_cndmask_b32_e32 v56, 0, v34, vcc
	v_lshl_add_u64 v[34:35], s[0:1], 0, v[54:55]
	flat_load_dword v54, v[34:35]
	v_or_b32_e32 v34, 0x80000000, v231
	v_cmp_gt_i32_e32 vcc, 0, v231
	v_or_b32_e32 v55, 0x80000000, v228
	s_nop 0
	v_cndmask_b32_e32 v37, v34, v37, vcc
	v_lshl_add_u64 v[34:35], s[0:1], 0, v[52:53]
	flat_load_dword v53, v[34:35]
	v_cmp_lt_u32_e32 vcc, s2, v161
	v_lshl_add_u64 v[34:35], s[0:1], 0, v[50:51]
	s_movk_i32 s2, 0x137f
	v_cndmask_b32_e32 v52, 0, v37, vcc
	v_not_b32_e32 v37, v228
	v_cmp_gt_i32_e32 vcc, 0, v228
	flat_load_dword v61, v[34:35]
	s_nop 0
	v_cndmask_b32_e32 v34, v55, v37, vcc
	v_cmp_lt_u32_e32 vcc, s2, v161
	v_not_b32_e32 v37, v229
	s_movk_i32 s2, 0x13bf
	v_cndmask_b32_e32 v50, 0, v34, vcc
	v_lshl_add_u64 v[34:35], s[0:1], 0, v[48:49]
	flat_load_dword v55, v[34:35]
	v_or_b32_e32 v34, 0x80000000, v229
	v_cmp_gt_i32_e32 vcc, 0, v229
	s_nop 1
	v_cndmask_b32_e32 v37, v34, v37, vcc
	v_lshl_add_u64 v[34:35], s[0:1], 0, v[46:47]
	flat_load_dword v222, v[34:35]
	v_cmp_lt_u32_e32 vcc, s2, v161
	v_lshl_add_u64 v[34:35], s[0:1], 0, v[44:45]
	v_or_b32_e32 v46, 0x80000000, v0
	v_cndmask_b32_e32 v49, 0, v37, vcc
	v_not_b32_e32 v37, v0
	flat_load_dword v223, v[34:35]
	v_cmp_gt_i32_e32 vcc, 0, v0
	s_movk_i32 s2, 0x13ff
	v_lshl_add_u64 v[34:35], s[0:1], 0, v[42:43]
	v_cndmask_b32_e32 v0, v46, v37, vcc
	v_cmp_lt_u32_e32 vcc, s2, v161
	flat_load_dword v224, v[34:35]
	v_or_b32_e32 v34, 0x80000000, v38
	v_cndmask_b32_e32 v48, 0, v0, vcc
	v_not_b32_e32 v0, v38
	v_cmp_gt_i32_e32 vcc, 0, v38
	s_nop 1
	v_cndmask_b32_e32 v0, v34, v0, vcc
	v_lshl_add_u64 v[34:35], s[0:1], 0, v[40:41]
	flat_load_dword v34, v[34:35]
	s_movk_i32 s0, 0x143f
	v_cmp_lt_u32_e32 vcc, s0, v161
	v_or_b32_e32 v35, 0x80000000, v36
	s_movk_i32 s0, 0x147f
	v_cndmask_b32_e32 v51, 0, v0, vcc
	v_not_b32_e32 v0, v36
	v_cmp_gt_i32_e32 vcc, 0, v36
	s_nop 1
	v_cndmask_b32_e32 v0, v35, v0, vcc
	v_cmp_lt_u32_e32 vcc, s0, v161
	s_waitcnt vmcnt(0) lgkmcnt(0)
	v_or_b32_e32 v35, 0x80000000, v39
	s_movk_i32 s0, 0x14bf
	v_cndmask_b32_e32 v47, 0, v0, vcc
	v_not_b32_e32 v0, v39
	v_cmp_gt_i32_e32 vcc, 0, v39
	s_nop 1
	v_cndmask_b32_e32 v0, v35, v0, vcc
	v_cmp_lt_u32_e32 vcc, s0, v161
	v_or_b32_e32 v35, 0x80000000, v63
	s_movk_i32 s0, 0x14ff
	v_cndmask_b32_e32 v46, 0, v0, vcc
	v_not_b32_e32 v0, v63
	v_cmp_gt_i32_e32 vcc, 0, v63
	s_nop 1
	v_cndmask_b32_e32 v0, v35, v0, vcc
	v_cmp_lt_u32_e32 vcc, s0, v161
	v_or_b32_e32 v35, 0x80000000, v60
	s_movk_i32 s0, 0x153f
	v_cndmask_b32_e32 v45, 0, v0, vcc
	v_not_b32_e32 v0, v60
	v_cmp_gt_i32_e32 vcc, 0, v60
	s_nop 1
	v_cndmask_b32_e32 v0, v35, v0, vcc
	v_cmp_lt_u32_e32 vcc, s0, v161
	v_or_b32_e32 v35, 0x80000000, v59
	s_movk_i32 s0, 0x157f
	v_cndmask_b32_e32 v44, 0, v0, vcc
	v_not_b32_e32 v0, v59
	v_cmp_gt_i32_e32 vcc, 0, v59
	s_nop 1
	v_cndmask_b32_e32 v0, v35, v0, vcc
	v_cmp_lt_u32_e32 vcc, s0, v161
	v_or_b32_e32 v35, 0x80000000, v57
	s_movk_i32 s0, 0x15bf
	v_cndmask_b32_e32 v43, 0, v0, vcc
	v_not_b32_e32 v0, v57
	v_cmp_gt_i32_e32 vcc, 0, v57
	s_nop 1
	v_cndmask_b32_e32 v0, v35, v0, vcc
	v_cmp_lt_u32_e32 vcc, s0, v161
	v_or_b32_e32 v35, 0x80000000, v54
	s_movk_i32 s0, 0x15ff
	v_cndmask_b32_e32 v42, 0, v0, vcc
	v_not_b32_e32 v0, v54
	v_cmp_gt_i32_e32 vcc, 0, v54
	s_nop 1
	v_cndmask_b32_e32 v0, v35, v0, vcc
	v_cmp_lt_u32_e32 vcc, s0, v161
	v_or_b32_e32 v35, 0x80000000, v53
	s_movk_i32 s0, 0x163f
	v_cndmask_b32_e32 v41, 0, v0, vcc
	v_not_b32_e32 v0, v53
	v_cmp_gt_i32_e32 vcc, 0, v53
	v_or_b32_e32 v53, 0x80000000, v34
	s_nop 0
	v_cndmask_b32_e32 v0, v35, v0, vcc
	v_cmp_lt_u32_e32 vcc, s0, v161
	v_or_b32_e32 v35, 0x80000000, v61
	s_movk_i32 s0, 0x167f
	v_cndmask_b32_e32 v40, 0, v0, vcc
	v_not_b32_e32 v0, v61
	v_cmp_gt_i32_e32 vcc, 0, v61
	s_nop 1
	v_cndmask_b32_e32 v0, v35, v0, vcc
	v_cmp_lt_u32_e32 vcc, s0, v161
	v_or_b32_e32 v35, 0x80000000, v55
	s_movk_i32 s0, 0x16bf
	v_cndmask_b32_e32 v39, 0, v0, vcc
	v_not_b32_e32 v0, v55
	v_cmp_gt_i32_e32 vcc, 0, v55
	s_nop 1
	v_cndmask_b32_e32 v0, v35, v0, vcc
	v_cmp_lt_u32_e32 vcc, s0, v161
	v_or_b32_e32 v35, 0x80000000, v222
	s_movk_i32 s0, 0x16ff
	v_cndmask_b32_e32 v38, 0, v0, vcc
	v_not_b32_e32 v0, v222
	v_cmp_gt_i32_e32 vcc, 0, v222
	s_nop 1
	v_cndmask_b32_e32 v0, v35, v0, vcc
	v_cmp_lt_u32_e32 vcc, s0, v161
	v_or_b32_e32 v35, 0x80000000, v223
	s_movk_i32 s0, 0x173f
	v_cndmask_b32_e32 v37, 0, v0, vcc
	v_not_b32_e32 v0, v223
	v_cmp_gt_i32_e32 vcc, 0, v223
	s_nop 1
	v_cndmask_b32_e32 v0, v35, v0, vcc
	v_cmp_lt_u32_e32 vcc, s0, v161
	v_or_b32_e32 v35, 0x80000000, v224
	s_movk_i32 s0, 0x177f
	v_cndmask_b32_e32 v36, 0, v0, vcc
	v_not_b32_e32 v0, v224
	v_cmp_gt_i32_e32 vcc, 0, v224
	s_nop 1
	v_cndmask_b32_e32 v0, v35, v0, vcc
	v_cmp_lt_u32_e32 vcc, s0, v161
	s_movk_i32 s0, 0x17bf
	s_nop 0
	v_cndmask_b32_e32 v35, 0, v0, vcc
	v_not_b32_e32 v0, v34
	v_cmp_gt_i32_e32 vcc, 0, v34
	v_mov_b32_e32 v34, 0
	s_nop 0
	v_cndmask_b32_e32 v0, v53, v0, vcc
	v_cmp_lt_u32_e32 vcc, s0, v161
	v_mov_b32_e32 v53, 31
	s_nop 0
	v_cndmask_b32_e32 v0, 0, v0, vcc
	v_readlane_b32 s100, v161, 0
	s_lshr_b32 s100, s100, 6
	s_add_u32 s100, s100, 1
; DI unsigned mbcnt64(unsigned long long m) { return __builtin_amdgcn_mbcnt_hi((unsigned)(m >> 32), __builtin_amdgcn_mbcnt_lo((unsigned)m, 0u)); }
; template <int NV>
; DI void topk_row(const float* row, int s, LAS int* lst, int lane) {
;     ...
;         const unsigned cand = T | (1u << bit); int c = 0;
; #pragma unroll
;         for (int j = 0; j < NV; ++j) asm volatile("v_cmp_le_u32 vcc, %2, %1\n\tv_addc_co_u32 %0, vcc, 0, %0, vcc" : "+v"(c) : "v"(key[j]), "s"(cand) : "vcc");
;         const int tot = wave_sum_i(c);
;         if (tot >= 256) T = cand;
;         if (tot == 256) break;
;     }
;     int bgt = 0;
; #pragma unroll
;     for (int j = 0; j < NV; ++j) { const bool sg = key[j] > T; const unsigned long long mg = __ballot(sg); if (sg) lst[bgt + (int)mbcnt64(mg)] = j * 64 + lane; bgt += __builtin_popcountll(mg); }
.LBB0_2485:
	v_lshlrev_b32_e64 v54, v53, 1
	v_mov_b32_e32 v55, 0
	v_or_b32_e32 v54, v54, v34
	v_cmp_le_u32 vcc, v54, v221
	v_addc_co_u32 v55, vcc, 0, v55, vcc
	s_nop 0
	v_cmp_le_u32 vcc, v54, v220
	v_addc_co_u32 v55, vcc, 0, v55, vcc
	s_nop 0
	v_cmp_le_u32 vcc, v54, v219
	v_addc_co_u32 v55, vcc, 0, v55, vcc
	s_nop 0
	v_cmp_le_u32 vcc, v54, v218
	v_addc_co_u32 v55, vcc, 0, v55, vcc
	s_nop 0
	v_cmp_le_u32 vcc, v54, v217
	v_addc_co_u32 v55, vcc, 0, v55, vcc
	s_nop 0
	v_cmp_le_u32 vcc, v54, v216
	v_addc_co_u32 v55, vcc, 0, v55, vcc
	s_nop 0
	v_cmp_le_u32 vcc, v54, v215
	v_addc_co_u32 v55, vcc, 0, v55, vcc
	s_nop 0
	v_cmp_le_u32 vcc, v54, v214
	v_addc_co_u32 v55, vcc, 0, v55, vcc
	s_nop 0
	s_cmp_le_u32 s100, 8
	s_cbranch_scc1 .Lp12_pe_1
	v_cmp_le_u32 vcc, v54, v213
	v_addc_co_u32 v55, vcc, 0, v55, vcc
	s_nop 0
	v_cmp_le_u32 vcc, v54, v211
	v_addc_co_u32 v55, vcc, 0, v55, vcc
	s_nop 0
	v_cmp_le_u32 vcc, v54, v206
	v_addc_co_u32 v55, vcc, 0, v55, vcc
	s_nop 0
	v_cmp_le_u32 vcc, v54, v203
	v_addc_co_u32 v55, vcc, 0, v55, vcc
	s_nop 0
	v_cmp_le_u32 vcc, v54, v200
	v_addc_co_u32 v55, vcc, 0, v55, vcc
	s_nop 0
	v_cmp_le_u32 vcc, v54, v202
	v_addc_co_u32 v55, vcc, 0, v55, vcc
	s_nop 0
	v_cmp_le_u32 vcc, v54, v204
	v_addc_co_u32 v55, vcc, 0, v55, vcc
	s_nop 0
	v_cmp_le_u32 vcc, v54, v207
	v_addc_co_u32 v55, vcc, 0, v55, vcc
	s_nop 0
	s_cmp_le_u32 s100, 16
	s_cbranch_scc1 .Lp12_pe_1
	v_cmp_le_u32 vcc, v54, v208
	v_addc_co_u32 v55, vcc, 0, v55, vcc
	s_nop 0
	v_cmp_le_u32 vcc, v54, v212
	v_addc_co_u32 v55, vcc, 0, v55, vcc
	s_nop 0
	v_cmp_le_u32 vcc, v54, v210
	v_addc_co_u32 v55, vcc, 0, v55, vcc
	s_nop 0
	v_cmp_le_u32 vcc, v54, v209
	v_addc_co_u32 v55, vcc, 0, v55, vcc
	s_nop 0
	v_cmp_le_u32 vcc, v54, v205
	v_addc_co_u32 v55, vcc, 0, v55, vcc
	s_nop 0
	v_cmp_le_u32 vcc, v54, v201
	v_addc_co_u32 v55, vcc, 0, v55, vcc
	s_nop 0
	v_cmp_le_u32 vcc, v54, v199
	v_addc_co_u32 v55, vcc, 0, v55, vcc
	s_nop 0
	v_cmp_le_u32 vcc, v54, v198
	v_addc_co_u32 v55, vcc, 0, v55, vcc
	s_nop 0
	s_cmp_le_u32 s100, 24
	s_cbranch_scc1 .Lp12_pe_1
	v_cmp_le_u32 vcc, v54, v197
	v_addc_co_u32 v55, vcc, 0, v55, vcc
	s_nop 0
	v_cmp_le_u32 vcc, v54, v196
	v_addc_co_u32 v55, vcc, 0, v55, vcc
	s_nop 0
	v_cmp_le_u32 vcc, v54, v195
	v_addc_co_u32 v55, vcc, 0, v55, vcc
	s_nop 0
	v_cmp_le_u32 vcc, v54, v194
	v_addc_co_u32 v55, vcc, 0, v55, vcc
	s_nop 0
	v_cmp_le_u32 vcc, v54, v193
	v_addc_co_u32 v55, vcc, 0, v55, vcc
	s_nop 0
	v_cmp_le_u32 vcc, v54, v192
	v_addc_co_u32 v55, vcc, 0, v55, vcc
	s_nop 0
	v_cmp_le_u32 vcc, v54, v191
	v_addc_co_u32 v55, vcc, 0, v55, vcc
	s_nop 0
	v_cmp_le_u32 vcc, v54, v190
	v_addc_co_u32 v55, vcc, 0, v55, vcc
	s_nop 0
	s_cmp_le_u32 s100, 32
	s_cbranch_scc1 .Lp12_pe_1
	v_cmp_le_u32 vcc, v54, v189
	v_addc_co_u32 v55, vcc, 0, v55, vcc
	s_nop 0
	v_cmp_le_u32 vcc, v54, v188
	v_addc_co_u32 v55, vcc, 0, v55, vcc
	s_nop 0
	v_cmp_le_u32 vcc, v54, v187
	v_addc_co_u32 v55, vcc, 0, v55, vcc
	s_nop 0
	v_cmp_le_u32 vcc, v54, v186
	v_addc_co_u32 v55, vcc, 0, v55, vcc
	s_nop 0
	v_cmp_le_u32 vcc, v54, v185
	v_addc_co_u32 v55, vcc, 0, v55, vcc
	s_nop 0
	v_cmp_le_u32 vcc, v54, v184
	v_addc_co_u32 v55, vcc, 0, v55, vcc
	s_nop 0
	v_cmp_le_u32 vcc, v54, v183
	v_addc_co_u32 v55, vcc, 0, v55, vcc
	s_nop 0
	v_cmp_le_u32 vcc, v54, v182
	v_addc_co_u32 v55, vcc, 0, v55, vcc
	s_nop 0
	s_cmp_le_u32 s100, 40
	s_cbranch_scc1 .Lp12_pe_1
	v_cmp_le_u32 vcc, v54, v181
	v_addc_co_u32 v55, vcc, 0, v55, vcc
	s_nop 0
	v_cmp_le_u32 vcc, v54, v180
	v_addc_co_u32 v55, vcc, 0, v55, vcc
	s_nop 0
	v_cmp_le_u32 vcc, v54, v179
	v_addc_co_u32 v55, vcc, 0, v55, vcc
	s_nop 0
	v_cmp_le_u32 vcc, v54, v178
	v_addc_co_u32 v55, vcc, 0, v55, vcc
	s_nop 0
	v_cmp_le_u32 vcc, v54, v177
	v_addc_co_u32 v55, vcc, 0, v55, vcc
	s_nop 0
	v_cmp_le_u32 vcc, v54, v176
	v_addc_co_u32 v55, vcc, 0, v55, vcc
	s_nop 0
	v_cmp_le_u32 vcc, v54, v175
	v_addc_co_u32 v55, vcc, 0, v55, vcc
	s_nop 0
	v_cmp_le_u32 vcc, v54, v173
	v_addc_co_u32 v55, vcc, 0, v55, vcc
	s_nop 0
	s_cmp_le_u32 s100, 48
	s_cbranch_scc1 .Lp12_pe_1
	v_cmp_le_u32 vcc, v54, v174
	v_addc_co_u32 v55, vcc, 0, v55, vcc
	s_nop 0
	v_cmp_le_u32 vcc, v54, v172
	v_addc_co_u32 v55, vcc, 0, v55, vcc
	s_nop 0
	v_cmp_le_u32 vcc, v54, v171
	v_addc_co_u32 v55, vcc, 0, v55, vcc
	s_nop 0
	v_cmp_le_u32 vcc, v54, v170
	v_addc_co_u32 v55, vcc, 0, v55, vcc
	s_nop 0
	v_cmp_le_u32 vcc, v54, v169
	v_addc_co_u32 v55, vcc, 0, v55, vcc
	s_nop 0
	v_cmp_le_u32 vcc, v54, v168
	v_addc_co_u32 v55, vcc, 0, v55, vcc
	s_nop 0
	v_cmp_le_u32 vcc, v54, v167
	v_addc_co_u32 v55, vcc, 0, v55, vcc
	s_nop 0
	v_cmp_le_u32 vcc, v54, v166
	v_addc_co_u32 v55, vcc, 0, v55, vcc
	s_nop 0
	s_cmp_le_u32 s100, 56
	s_cbranch_scc1 .Lp12_pe_1
; DI unsigned mbcnt64(unsigned long long m) { return __builtin_amdgcn_mbcnt_hi((unsigned)(m >> 32), __builtin_amdgcn_mbcnt_lo((unsigned)m, 0u)); }
; template <int NV>
; DI void topk_row(const float* row, int s, LAS int* lst, int lane) {
;     ...
;         const unsigned cand = T | (1u << bit); int c = 0;
; #pragma unroll
;         for (int j = 0; j < NV; ++j) asm volatile("v_cmp_le_u32 vcc, %2, %1\n\tv_addc_co_u32 %0, vcc, 0, %0, vcc" : "+v"(c) : "v"(key[j]), "s"(cand) : "vcc");
;         const int tot = wave_sum_i(c);
;         if (tot >= 256) T = cand;
;         if (tot == 256) break;
;     }
;     int bgt = 0;
; #pragma unroll
;     for (int j = 0; j < NV; ++j) { const bool sg = key[j] > T; const unsigned long long mg = __ballot(sg); if (sg) lst[bgt + (int)mbcnt64(mg)] = j * 64 + lane; bgt += __builtin_popcountll(mg); }
	v_cmp_le_u32 vcc, v54, v165
	v_addc_co_u32 v55, vcc, 0, v55, vcc
	s_nop 0
	v_cmp_le_u32 vcc, v54, v164
	v_addc_co_u32 v55, vcc, 0, v55, vcc
	s_nop 0
	v_cmp_le_u32 vcc, v54, v163
	v_addc_co_u32 v55, vcc, 0, v55, vcc
	s_nop 0
	v_cmp_le_u32 vcc, v54, v162
	v_addc_co_u32 v55, vcc, 0, v55, vcc
	s_nop 0
	v_cmp_le_u32 vcc, v54, v141
	v_addc_co_u32 v55, vcc, 0, v55, vcc
	s_nop 0
	v_cmp_le_u32 vcc, v54, v140
	v_addc_co_u32 v55, vcc, 0, v55, vcc
	s_nop 0
	v_cmp_le_u32 vcc, v54, v139
	v_addc_co_u32 v55, vcc, 0, v55, vcc
	s_nop 0
	v_cmp_le_u32 vcc, v54, v138
	v_addc_co_u32 v55, vcc, 0, v55, vcc
	s_nop 0
	s_cmp_le_u32 s100, 64
	s_cbranch_scc1 .Lp12_pe_1
	v_cmp_le_u32 vcc, v54, v137
	v_addc_co_u32 v55, vcc, 0, v55, vcc
	s_nop 0
	v_cmp_le_u32 vcc, v54, v136
	v_addc_co_u32 v55, vcc, 0, v55, vcc
	s_nop 0
	v_cmp_le_u32 vcc, v54, v135
	v_addc_co_u32 v55, vcc, 0, v55, vcc
	s_nop 0
	v_cmp_le_u32 vcc, v54, v134
	v_addc_co_u32 v55, vcc, 0, v55, vcc
	s_nop 0
	v_cmp_le_u32 vcc, v54, v132
	v_addc_co_u32 v55, vcc, 0, v55, vcc
	s_nop 0
	v_cmp_le_u32 vcc, v54, v130
	v_addc_co_u32 v55, vcc, 0, v55, vcc
	s_nop 0
	v_cmp_le_u32 vcc, v54, v133
	v_addc_co_u32 v55, vcc, 0, v55, vcc
	s_nop 0
	v_cmp_le_u32 vcc, v54, v131
	v_addc_co_u32 v55, vcc, 0, v55, vcc
	s_nop 0
	s_cmp_le_u32 s100, 72
	s_cbranch_scc1 .Lp12_pe_1
	v_cmp_le_u32 vcc, v54, v128
	v_addc_co_u32 v55, vcc, 0, v55, vcc
	s_nop 0
	v_cmp_le_u32 vcc, v54, v129
	v_addc_co_u32 v55, vcc, 0, v55, vcc
	s_nop 0
	v_cmp_le_u32 vcc, v54, v62
	v_addc_co_u32 v55, vcc, 0, v55, vcc
	s_nop 0
	v_cmp_le_u32 vcc, v54, v58
	v_addc_co_u32 v55, vcc, 0, v55, vcc
	s_nop 0
	v_cmp_le_u32 vcc, v54, v56
	v_addc_co_u32 v55, vcc, 0, v55, vcc
	s_nop 0
	v_cmp_le_u32 vcc, v54, v52
	v_addc_co_u32 v55, vcc, 0, v55, vcc
	s_nop 0
	v_cmp_le_u32 vcc, v54, v50
	v_addc_co_u32 v55, vcc, 0, v55, vcc
	s_nop 0
	v_cmp_le_u32 vcc, v54, v49
	v_addc_co_u32 v55, vcc, 0, v55, vcc
	s_nop 0
	s_cmp_le_u32 s100, 80
	s_cbranch_scc1 .Lp12_pe_1
	v_cmp_le_u32 vcc, v54, v48
	v_addc_co_u32 v55, vcc, 0, v55, vcc
	s_nop 0
	v_cmp_le_u32 vcc, v54, v51
	v_addc_co_u32 v55, vcc, 0, v55, vcc
	s_nop 0
	v_cmp_le_u32 vcc, v54, v47
	v_addc_co_u32 v55, vcc, 0, v55, vcc
	s_nop 0
	v_cmp_le_u32 vcc, v54, v46
	v_addc_co_u32 v55, vcc, 0, v55, vcc
	s_nop 0
	v_cmp_le_u32 vcc, v54, v45
	v_addc_co_u32 v55, vcc, 0, v55, vcc
	s_nop 0
	v_cmp_le_u32 vcc, v54, v44
	v_addc_co_u32 v55, vcc, 0, v55, vcc
	s_nop 0
	v_cmp_le_u32 vcc, v54, v43
	v_addc_co_u32 v55, vcc, 0, v55, vcc
	s_nop 0
	v_cmp_le_u32 vcc, v54, v42
	v_addc_co_u32 v55, vcc, 0, v55, vcc
	s_nop 0
	s_cmp_le_u32 s100, 88
	s_cbranch_scc1 .Lp12_pe_1
	v_cmp_le_u32 vcc, v54, v41
	v_addc_co_u32 v55, vcc, 0, v55, vcc
	s_nop 0
	v_cmp_le_u32 vcc, v54, v40
	v_addc_co_u32 v55, vcc, 0, v55, vcc
	s_nop 0
	v_cmp_le_u32 vcc, v54, v39
	v_addc_co_u32 v55, vcc, 0, v55, vcc
	s_nop 0
	v_cmp_le_u32 vcc, v54, v38
	v_addc_co_u32 v55, vcc, 0, v55, vcc
	s_nop 0
	v_cmp_le_u32 vcc, v54, v37
	v_addc_co_u32 v55, vcc, 0, v55, vcc
	s_nop 0
	v_cmp_le_u32 vcc, v54, v36
	v_addc_co_u32 v55, vcc, 0, v55, vcc
	s_nop 0
	v_cmp_le_u32 vcc, v54, v35
	v_addc_co_u32 v55, vcc, 0, v55, vcc
	s_nop 0
	v_cmp_le_u32 vcc, v54, v0
	v_addc_co_u32 v55, vcc, 0, v55, vcc
.Lp12_pe_1:
	s_nop 1
	v_add_u32_dpp v55, v55, v55 quad_perm:[1,0,3,2] row_mask:0xf bank_mask:0xf bound_ctrl:1
	s_nop 1
	v_add_u32_dpp v55, v55, v55 quad_perm:[2,3,0,1] row_mask:0xf bank_mask:0xf bound_ctrl:1
	s_nop 1
	v_add_u32_dpp v55, v55, v55 row_half_mirror row_mask:0xf bank_mask:0xf bound_ctrl:1
	s_nop 1
	v_add_u32_dpp v55, v55, v55 row_mirror row_mask:0xf bank_mask:0xf bound_ctrl:1
	s_nop 0
	v_readlane_b32 s0, v55, 0
	v_readlane_b32 s1, v55, 16
	s_add_i32 s0, s1, s0
	v_readlane_b32 s1, v55, 32
	s_add_i32 s0, s0, s1
	v_readlane_b32 s1, v55, 48
	s_add_i32 s0, s0, s1
	s_cmpk_gt_i32 s0, 0xff
	s_cselect_b64 vcc, -1, 0
	s_cmpk_eq_i32 s0, 0x100
	v_cndmask_b32_e32 v34, v34, v54, vcc
	s_cselect_b64 s[0:1], -1, 0
	v_subrev_co_u32_e32 v53, vcc, 1, v53
	s_or_b64 s[0:1], s[0:1], vcc
	s_andn2_b64 vcc, exec, s[0:1]
	s_cbranch_vccnz .LBB0_2485
	v_cmp_gt_u32_e32 vcc, v221, v34
	s_and_saveexec_b64 s[0:1], vcc
	s_nop 0
	v_mbcnt_lo_u32_b32 v53, vcc_lo, 0
	v_mbcnt_hi_u32_b32 v53, vcc_hi, v53
	v_lshl_add_u32 v53, v53, 2, s20
	ds_write_b32 v53, v2
	s_or_b64 exec, exec, s[0:1]
	s_bcnt1_i32_b64 s2, vcc
	v_cmp_gt_u32_e32 vcc, v220, v34
	s_and_saveexec_b64 s[0:1], vcc
	s_cbranch_execz .LBB0_2490
	s_lshl_b32 s3, s2, 2
	v_mbcnt_lo_u32_b32 v53, vcc_lo, 0
	s_add_i32 s3, s20, s3
	v_mbcnt_hi_u32_b32 v53, vcc_hi, v53
	v_lshl_add_u32 v53, v53, 2, s3
	ds_write_b32 v53, v4

; DI unsigned f2key(float f) { const unsigned u = __float_as_uint(f); return (u & 0x80000000u) ? ~u : (u | 0x80000000u); }
; template <int NV>
; DI void topk_row(const float* row, int s, LAS int* lst, int lane) {
;     ...
;     for (int jo = 0; jo < NV / 16; ++jo) { const float* rb = row + jo * 1024;
; #pragma unroll
;         for (int ji = 0; ji < 16; ++ji) { const int j = jo * 16 + ji; const unsigned u = f2key(rb[ji * 64 + lane]); key[j] = (j * 64 + lane <= s) ? u : 0u; } }
.LBB0_2870:
	v_lshlrev_b32_e32 v0, 2, v2
	v_lshl_add_u64 v[40:41], s[12:13], 0, v[0:1]
	flat_load_dword v48, v[40:41]
	flat_load_dword v49, v[40:41] offset:256
	flat_load_dword v50, v[40:41] offset:512
	flat_load_dword v51, v[40:41] offset:768
	flat_load_dword v52, v[40:41] offset:1024
	flat_load_dword v53, v[40:41] offset:1280
	flat_load_dword v54, v[40:41] offset:1536
	flat_load_dword v55, v[40:41] offset:1792
	flat_load_dword v56, v[40:41] offset:2048
	flat_load_dword v57, v[40:41] offset:2304
	flat_load_dword v58, v[40:41] offset:2560
	flat_load_dword v59, v[40:41] offset:2816
	flat_load_dword v60, v[40:41] offset:3072
	flat_load_dword v128, v[40:41] offset:3328
	s_add_u32 s0, s12, 0x1000
	flat_load_dword v129, v[40:41] offset:3584
	flat_load_dword v130, v[40:41] offset:3840
	s_addc_u32 s1, s13, 0
	v_lshlrev_b32_e32 v38, 2, v4
	v_mov_b32_e32 v39, v1
	v_lshlrev_b32_e32 v36, 2, v6
	v_mov_b32_e32 v37, v1
	v_lshlrev_b32_e32 v34, 2, v8
	v_mov_b32_e32 v35, v1
	v_lshl_add_u64 v[40:41], s[0:1], 0, v[0:1]
	v_lshl_add_u64 v[42:43], s[0:1], 0, v[38:39]
	v_lshl_add_u64 v[44:45], s[0:1], 0, v[36:37]
	v_lshl_add_u64 v[46:47], s[0:1], 0, v[34:35]
	flat_load_dword v131, v[40:41]
	flat_load_dword v132, v[42:43]
	flat_load_dword v133, v[44:45]
	flat_load_dword v134, v[46:47]
	s_movk_i32 s2, 0x7ff
	s_waitcnt vmcnt(0) lgkmcnt(0)
	v_not_b32_e32 v40, v48
	v_or_b32_e32 v41, 0x80000000, v48
	v_cmp_gt_i32_e32 vcc, 0, v48
	v_not_b32_e32 v42, v49
	v_or_b32_e32 v43, 0x80000000, v49
	v_cndmask_b32_e32 v189, v41, v40, vcc
	v_cmp_gt_i32_e32 vcc, 0, v49
	v_not_b32_e32 v44, v50
	v_or_b32_e32 v45, 0x80000000, v50
	v_cndmask_b32_e32 v188, v43, v42, vcc
	v_cmp_gt_i32_e32 vcc, 0, v50
	v_not_b32_e32 v46, v51
	v_or_b32_e32 v47, 0x80000000, v51
	v_cndmask_b32_e32 v187, v45, v44, vcc
	v_cmp_gt_i32_e32 vcc, 0, v51
	v_not_b32_e32 v61, v52
	v_or_b32_e32 v62, 0x80000000, v52
	v_cndmask_b32_e32 v186, v47, v46, vcc
	v_cmp_gt_i32_e32 vcc, 0, v52
	v_not_b32_e32 v63, v53
	v_or_b32_e32 v135, 0x80000000, v53
	v_cndmask_b32_e32 v185, v62, v61, vcc
	v_cmp_gt_i32_e32 vcc, 0, v53
	v_not_b32_e32 v136, v54
	v_or_b32_e32 v137, 0x80000000, v54
	v_cndmask_b32_e32 v184, v135, v63, vcc
	v_cmp_gt_i32_e32 vcc, 0, v54
	v_not_b32_e32 v138, v55
	v_or_b32_e32 v139, 0x80000000, v55
	v_cndmask_b32_e32 v183, v137, v136, vcc
	v_cmp_gt_i32_e32 vcc, 0, v55
	v_not_b32_e32 v140, v56
	v_or_b32_e32 v141, 0x80000000, v56
	v_cndmask_b32_e32 v182, v139, v138, vcc
	v_cmp_gt_i32_e32 vcc, 0, v56
	v_not_b32_e32 v162, v57
	v_or_b32_e32 v163, 0x80000000, v57
	v_cndmask_b32_e32 v179, v141, v140, vcc
	v_cmp_gt_i32_e32 vcc, 0, v57
	v_not_b32_e32 v164, v58
	v_or_b32_e32 v165, 0x80000000, v58
	v_cndmask_b32_e32 v175, v163, v162, vcc
	v_cmp_gt_i32_e32 vcc, 0, v58
	v_lshlrev_b32_e32 v62, 2, v10
	v_mov_b32_e32 v63, v1
	v_not_b32_e32 v166, v59
	v_or_b32_e32 v167, 0x80000000, v59
	v_cndmask_b32_e32 v172, v165, v164, vcc
	v_cmp_gt_i32_e32 vcc, 0, v59
	v_lshl_add_u64 v[40:41], s[0:1], 0, v[62:63]
	v_not_b32_e32 v168, v60
	v_or_b32_e32 v169, 0x80000000, v60
	v_cndmask_b32_e32 v170, v167, v166, vcc
	v_cmp_gt_i32_e32 vcc, 0, v60
	flat_load_dword v135, v[40:41]
	v_lshlrev_b32_e32 v60, 2, v12
	v_mov_b32_e32 v61, v1
	v_lshl_add_u64 v[40:41], s[0:1], 0, v[60:61]
	v_lshlrev_b32_e32 v58, 2, v14
	v_mov_b32_e32 v59, v1
	flat_load_dword v136, v[40:41]
	v_lshl_add_u64 v[40:41], s[0:1], 0, v[58:59]
	v_lshlrev_b32_e32 v56, 2, v16
	v_mov_b32_e32 v57, v1
	flat_load_dword v137, v[40:41]
	v_lshl_add_u64 v[40:41], s[0:1], 0, v[56:57]
	flat_load_dword v138, v[40:41]
	v_lshlrev_b32_e32 v54, 2, v18
	v_mov_b32_e32 v55, v1
	v_lshl_add_u64 v[40:41], s[0:1], 0, v[54:55]
	flat_load_dword v139, v[40:41]
	v_lshlrev_b32_e32 v52, 2, v20
	v_mov_b32_e32 v53, v1
	v_lshl_add_u64 v[40:41], s[0:1], 0, v[52:53]
	v_lshlrev_b32_e32 v50, 2, v22
	v_mov_b32_e32 v51, v1
	flat_load_dword v140, v[40:41]
	v_lshl_add_u64 v[40:41], s[0:1], 0, v[50:51]
	v_lshlrev_b32_e32 v48, 2, v24
	v_mov_b32_e32 v49, v1
	v_cndmask_b32_e32 v167, v169, v168, vcc
	v_not_b32_e32 v42, v128
	v_or_b32_e32 v43, 0x80000000, v128
	v_cmp_gt_i32_e32 vcc, 0, v128
	flat_load_dword v141, v[40:41]
	v_lshl_add_u64 v[40:41], s[0:1], 0, v[48:49]
	v_lshlrev_b32_e32 v46, 2, v26
	v_mov_b32_e32 v47, v1
	v_cndmask_b32_e32 v169, v43, v42, vcc
	v_not_b32_e32 v42, v129
	v_or_b32_e32 v43, 0x80000000, v129
	v_cmp_gt_i32_e32 vcc, 0, v129
	flat_load_dword v162, v[40:41]
	v_lshl_add_u64 v[40:41], s[0:1], 0, v[46:47]
	v_cndmask_b32_e32 v174, v43, v42, vcc
	v_not_b32_e32 v42, v130
	v_or_b32_e32 v43, 0x80000000, v130
	flat_load_dword v190, v[40:41]
	v_lshlrev_b32_e32 v44, 2, v28
	v_mov_b32_e32 v45, v1
	v_cmp_gt_i32_e32 vcc, 0, v130
	v_lshl_add_u64 v[40:41], s[0:1], 0, v[44:45]
	flat_load_dword v191, v[40:41]
	v_cndmask_b32_e32 v178, v43, v42, vcc
	v_lshlrev_b32_e32 v42, 2, v30
	v_mov_b32_e32 v43, v1
	v_lshl_add_u64 v[40:41], s[0:1], 0, v[42:43]
	flat_load_dword v192, v[40:41]
	v_lshlrev_b32_e32 v40, 2, v32
	v_mov_b32_e32 v41, v1
	v_lshl_add_u64 v[128:129], s[0:1], 0, v[40:41]
	s_add_u32 s0, s12, 0x2000
	flat_load_dword v193, v[128:129]
	s_addc_u32 s1, s13, 0
	v_lshl_add_u64 v[128:129], s[0:1], 0, v[0:1]
	v_not_b32_e32 v130, v131
	v_or_b32_e32 v163, 0x80000000, v131
	flat_load_dword v194, v[128:129]
	v_cmp_gt_i32_e32 vcc, 0, v131
	v_not_b32_e32 v128, v132
	v_or_b32_e32 v129, 0x80000000, v132
	v_cndmask_b32_e32 v181, v163, v130, vcc
	v_cmp_gt_i32_e32 vcc, 0, v132
	v_not_b32_e32 v130, v133
	v_or_b32_e32 v132, 0x80000000, v134
	v_cndmask_b32_e32 v180, v129, v128, vcc
	v_lshl_add_u64 v[128:129], s[0:1], 0, v[38:39]
	flat_load_dword v131, v[128:129]
	v_or_b32_e32 v128, 0x80000000, v133
	v_cmp_gt_i32_e32 vcc, 0, v133
	s_nop 1
	v_cndmask_b32_e32 v177, v128, v130, vcc
	v_not_b32_e32 v130, v134
	v_lshl_add_u64 v[128:129], s[0:1], 0, v[36:37]
	v_cmp_gt_i32_e32 vcc, 0, v134
	flat_load_dword v133, v[128:129]
	s_waitcnt vmcnt(0) lgkmcnt(0)
; DI unsigned f2key(float f) { const unsigned u = __float_as_uint(f); return (u & 0x80000000u) ? ~u : (u | 0x80000000u); }
; template <int NV>
; DI void topk_row(const float* row, int s, LAS int* lst, int lane) {
;     ...
;     for (int jo = 0; jo < NV / 16; ++jo) { const float* rb = row + jo * 1024;
; #pragma unroll
;         for (int ji = 0; ji < 16; ++ji) { const int j = jo * 16 + ji; const unsigned u = f2key(rb[ji * 64 + lane]); key[j] = (j * 64 + lane <= s) ? u : 0u; } }
	v_not_b32_e32 v128, v135
	v_cndmask_b32_e32 v176, v132, v130, vcc
	v_or_b32_e32 v129, 0x80000000, v135
	v_cmp_gt_i32_e32 vcc, 0, v135
	v_not_b32_e32 v130, v136
	v_or_b32_e32 v134, 0x80000000, v137
	v_cndmask_b32_e32 v173, v129, v128, vcc
	v_lshl_add_u64 v[128:129], s[0:1], 0, v[34:35]
	flat_load_dword v132, v[128:129]
	v_or_b32_e32 v128, 0x80000000, v136
	v_cmp_gt_i32_e32 vcc, 0, v136
	s_nop 1
	v_cndmask_b32_e32 v171, v128, v130, vcc
	v_not_b32_e32 v130, v137
	v_lshl_add_u64 v[128:129], s[0:1], 0, v[62:63]
	v_cmp_gt_i32_e32 vcc, 0, v137
	flat_load_dword v195, v[128:129]
	v_not_b32_e32 v128, v138
	v_cndmask_b32_e32 v168, v134, v130, vcc
	v_or_b32_e32 v129, 0x80000000, v138
	v_cmp_gt_i32_e32 vcc, 0, v138
	v_not_b32_e32 v130, v139
	v_or_b32_e32 v134, 0x80000000, v140
	v_cndmask_b32_e32 v166, v129, v128, vcc
	v_lshl_add_u64 v[128:129], s[0:1], 0, v[60:61]
	flat_load_dword v196, v[128:129]
	v_or_b32_e32 v128, 0x80000000, v139
	v_cmp_gt_i32_e32 vcc, 0, v139
	s_nop 1
	v_cndmask_b32_e32 v165, v128, v130, vcc
	v_lshl_add_u64 v[128:129], s[0:1], 0, v[58:59]
	flat_load_dword v197, v[128:129]
	v_not_b32_e32 v130, v140
	v_cmp_gt_i32_e32 vcc, 0, v140
	v_not_b32_e32 v128, v141
	v_or_b32_e32 v129, 0x80000000, v141
	v_cndmask_b32_e32 v164, v134, v130, vcc
	v_cmp_gt_i32_e32 vcc, 0, v141
	v_not_b32_e32 v130, v162
	v_or_b32_e32 v134, 0x80000000, v162
	v_cndmask_b32_e32 v163, v129, v128, vcc
	v_lshl_add_u64 v[128:129], s[0:1], 0, v[56:57]
	v_cmp_gt_i32_e32 vcc, 0, v162
	flat_load_dword v198, v[128:129]
	v_not_b32_e32 v128, v190
	v_cndmask_b32_e32 v162, v134, v130, vcc
	v_or_b32_e32 v129, 0x80000000, v190
	v_cmp_gt_i32_e32 vcc, 0, v190
	v_not_b32_e32 v130, v191
	s_nop 0
	v_cndmask_b32_e32 v141, v129, v128, vcc
	v_lshl_add_u64 v[128:129], s[0:1], 0, v[54:55]
	flat_load_dword v190, v[128:129]
	v_or_b32_e32 v128, 0x80000000, v191
	v_cmp_gt_i32_e32 vcc, 0, v191
	s_nop 1
	v_cndmask_b32_e32 v140, v128, v130, vcc
	v_lshl_add_u64 v[128:129], s[0:1], 0, v[52:53]
	v_not_b32_e32 v130, v192
	flat_load_dword v191, v[128:129]
	v_or_b32_e32 v128, 0x80000000, v192
	v_cmp_gt_i32_e32 vcc, 0, v192
	v_or_b32_e32 v129, 0x80000000, v193
	s_nop 0
	v_cndmask_b32_e32 v139, v128, v130, vcc
	v_not_b32_e32 v128, v193
	v_cmp_gt_i32_e32 vcc, 0, v193
	v_not_b32_e32 v130, v194
	s_nop 0
	v_cndmask_b32_e32 v138, v129, v128, vcc
	v_lshl_add_u64 v[128:129], s[0:1], 0, v[50:51]
	flat_load_dword v192, v[128:129]
	v_or_b32_e32 v128, 0x80000000, v194
	v_cmp_gt_i32_e32 vcc, 0, v194
	s_nop 1
	v_cndmask_b32_e32 v128, v128, v130, vcc
	v_cmp_lt_u32_e32 vcc, s2, v161
	v_not_b32_e32 v130, v131
	s_movk_i32 s2, 0x83f
	v_cndmask_b32_e32 v137, 0, v128, vcc
	v_lshl_add_u64 v[128:129], s[0:1], 0, v[48:49]
	flat_load_dword v193, v[128:129]
	v_or_b32_e32 v128, 0x80000000, v131
	v_cmp_gt_i32_e32 vcc, 0, v131
	v_or_b32_e32 v131, 0x80000000, v133
	s_nop 0
	v_cndmask_b32_e32 v128, v128, v130, vcc
	v_cmp_lt_u32_e32 vcc, s2, v161
	v_not_b32_e32 v130, v133
	s_movk_i32 s2, 0x87f
	v_cndmask_b32_e32 v136, 0, v128, vcc
	v_lshl_add_u64 v[128:129], s[0:1], 0, v[46:47]
	flat_load_dword v194, v[128:129]
	v_cmp_gt_i32_e32 vcc, 0, v133
	s_nop 1
	v_cndmask_b32_e32 v128, v131, v130, vcc
	v_cmp_lt_u32_e32 vcc, s2, v161
	s_waitcnt vmcnt(0) lgkmcnt(0)
	v_not_b32_e32 v130, v132
	v_or_b32_e32 v131, 0x80000000, v132
	v_cndmask_b32_e32 v135, 0, v128, vcc
	v_lshl_add_u64 v[128:129], s[0:1], 0, v[44:45]
	v_cmp_gt_i32_e32 vcc, 0, v132
	s_movk_i32 s2, 0x8bf
	flat_load_dword v199, v[128:129]
	v_cndmask_b32_e32 v128, v131, v130, vcc
	v_cmp_lt_u32_e32 vcc, s2, v161
	v_or_b32_e32 v129, 0x80000000, v195
	s_movk_i32 s2, 0x8ff
	v_cndmask_b32_e32 v134, 0, v128, vcc
	v_not_b32_e32 v128, v195
	v_cmp_gt_i32_e32 vcc, 0, v195
	s_nop 1
	v_cndmask_b32_e32 v130, v129, v128, vcc
	v_lshl_add_u64 v[128:129], s[0:1], 0, v[42:43]
	v_cmp_lt_u32_e32 vcc, s2, v161
	flat_load_dword v195, v[128:129]
	v_not_b32_e32 v128, v196
	v_cndmask_b32_e32 v133, 0, v130, vcc
	v_or_b32_e32 v129, 0x80000000, v196
	v_cmp_gt_i32_e32 vcc, 0, v196
	s_nop 1
	v_cndmask_b32_e32 v130, v129, v128, vcc
	v_lshl_add_u64 v[128:129], s[0:1], 0, v[40:41]
	s_movk_i32 s0, 0x93f
	v_cmp_lt_u32_e32 vcc, s0, v161
	s_add_u32 s0, s12, 0x3000
	flat_load_dword v196, v[128:129]
	s_addc_u32 s1, s13, 0
	v_lshl_add_u64 v[38:39], s[0:1], 0, v[38:39]
	v_cndmask_b32_e32 v131, 0, v130, vcc
	v_cmp_gt_i32_e32 vcc, 0, v197
	flat_load_dword v38, v[38:39]
	v_not_b32_e32 v128, v197
	v_or_b32_e32 v129, 0x80000000, v197
	v_cndmask_b32_e32 v130, v129, v128, vcc
	v_lshl_add_u64 v[128:129], s[0:1], 0, v[0:1]
	flat_load_dword v0, v[128:129]
	v_cmp_lt_u32_e32 vcc, s22, v161
	v_not_b32_e32 v128, v198
	v_or_b32_e32 v129, 0x80000000, v198
	v_cndmask_b32_e32 v132, 0, v130, vcc
	v_cmp_gt_i32_e32 vcc, 0, v198
	v_lshl_add_u64 v[36:37], s[0:1], 0, v[36:37]
	flat_load_dword v36, v[36:37]
	v_cndmask_b32_e32 v128, v129, v128, vcc
	v_cmp_lt_u32_e32 vcc, s23, v161
	v_not_b32_e32 v39, v190
	v_or_b32_e32 v37, 0x80000000, v191
	v_cndmask_b32_e32 v130, 0, v128, vcc
	v_or_b32_e32 v128, 0x80000000, v190
	v_cmp_gt_i32_e32 vcc, 0, v190
	v_lshl_add_u64 v[34:35], s[0:1], 0, v[34:35]
	v_or_b32_e32 v190, 0x80000000, v192
	v_cndmask_b32_e32 v39, v128, v39, vcc
	v_cmp_lt_u32_e32 vcc, s24, v161
	s_nop 1
	v_cndmask_b32_e32 v128, 0, v39, vcc
	v_not_b32_e32 v39, v191
	v_cmp_gt_i32_e32 vcc, 0, v191
	s_nop 1
	v_cndmask_b32_e32 v37, v37, v39, vcc
	flat_load_dword v39, v[34:35]
	v_cmp_lt_u32_e32 vcc, s25, v161
	v_lshl_add_u64 v[34:35], s[0:1], 0, v[62:63]
	flat_load_dword v63, v[34:35]
	v_cndmask_b32_e32 v129, 0, v37, vcc
	v_not_b32_e32 v37, v192
	v_cmp_gt_i32_e32 vcc, 0, v192
	s_nop 1
	v_cndmask_b32_e32 v34, v190, v37, vcc
	v_cmp_lt_u32_e32 vcc, s26, v161
	v_not_b32_e32 v37, v193
	s_nop 0
	v_cndmask_b32_e32 v62, 0, v34, vcc
	v_lshl_add_u64 v[34:35], s[0:1], 0, v[60:61]
	flat_load_dword v60, v[34:35]
	v_or_b32_e32 v34, 0x80000000, v193
	v_cmp_gt_i32_e32 vcc, 0, v193
	v_or_b32_e32 v61, 0x80000000, v194
	s_nop 0
	v_cndmask_b32_e32 v37, v34, v37, vcc
	v_lshl_add_u64 v[34:35], s[0:1], 0, v[58:59]
	flat_load_dword v59, v[34:35]
	v_cmp_lt_u32_e32 vcc, s27, v161
	v_lshl_add_u64 v[34:35], s[0:1], 0, v[56:57]
	flat_load_dword v57, v[34:35]
	v_cndmask_b32_e32 v58, 0, v37, vcc
	v_not_b32_e32 v37, v194
	v_cmp_gt_i32_e32 vcc, 0, v194
	s_nop 1
	v_cndmask_b32_e32 v34, v61, v37, vcc
	v_cmp_lt_u32_e32 vcc, s28, v161
	s_waitcnt vmcnt(0) lgkmcnt(0)
; DI unsigned f2key(float f) { const unsigned u = __float_as_uint(f); return (u & 0x80000000u) ? ~u : (u | 0x80000000u); }
; template <int NV>
; DI void topk_row(const float* row, int s, LAS int* lst, int lane) {
;     ...
;     for (int jo = 0; jo < NV / 16; ++jo) { const float* rb = row + jo * 1024;
; #pragma unroll
;         for (int ji = 0; ji < 16; ++ji) { const int j = jo * 16 + ji; const unsigned u = f2key(rb[ji * 64 + lane]); key[j] = (j * 64 + lane <= s) ? u : 0u; } }
;     unsigned T = 0u;
; #pragma unroll 1
	v_not_b32_e32 v37, v199
	v_cndmask_b32_e32 v56, 0, v34, vcc
	v_lshl_add_u64 v[34:35], s[0:1], 0, v[54:55]
	flat_load_dword v54, v[34:35]
	v_or_b32_e32 v34, 0x80000000, v199
	v_cmp_gt_i32_e32 vcc, 0, v199
	v_or_b32_e32 v55, 0x80000000, v195
	s_nop 0
	v_cndmask_b32_e32 v37, v34, v37, vcc
	v_lshl_add_u64 v[34:35], s[0:1], 0, v[52:53]
	flat_load_dword v53, v[34:35]
	v_cmp_lt_u32_e32 vcc, s29, v161
	v_lshl_add_u64 v[34:35], s[0:1], 0, v[50:51]
	flat_load_dword v61, v[34:35]
	v_cndmask_b32_e32 v52, 0, v37, vcc
	v_not_b32_e32 v37, v195
	v_cmp_gt_i32_e32 vcc, 0, v195
	s_nop 1
	v_cndmask_b32_e32 v34, v55, v37, vcc
	v_cmp_lt_u32_e32 vcc, s30, v161
	v_not_b32_e32 v37, v196
	s_nop 0
	v_cndmask_b32_e32 v50, 0, v34, vcc
	v_lshl_add_u64 v[34:35], s[0:1], 0, v[48:49]
	flat_load_dword v55, v[34:35]
	v_or_b32_e32 v34, 0x80000000, v196
	v_cmp_gt_i32_e32 vcc, 0, v196
	s_nop 1
	v_cndmask_b32_e32 v37, v34, v37, vcc
	v_lshl_add_u64 v[34:35], s[0:1], 0, v[46:47]
	flat_load_dword v190, v[34:35]
	v_cmp_lt_u32_e32 vcc, s31, v161
	v_lshl_add_u64 v[34:35], s[0:1], 0, v[44:45]
	v_or_b32_e32 v46, 0x80000000, v0
	v_cndmask_b32_e32 v49, 0, v37, vcc
	v_not_b32_e32 v37, v0
	flat_load_dword v191, v[34:35]
	v_cmp_gt_i32_e32 vcc, 0, v0
	v_lshl_add_u64 v[34:35], s[0:1], 0, v[42:43]
	flat_load_dword v192, v[34:35]
	v_cndmask_b32_e32 v0, v46, v37, vcc
	v_cmp_lt_u32_e32 vcc, s36, v161
	v_or_b32_e32 v34, 0x80000000, v38
	s_nop 0
	v_cndmask_b32_e32 v48, 0, v0, vcc
	v_not_b32_e32 v0, v38
	v_cmp_gt_i32_e32 vcc, 0, v38
	s_nop 1
	v_cndmask_b32_e32 v0, v34, v0, vcc
	v_lshl_add_u64 v[34:35], s[0:1], 0, v[40:41]
	flat_load_dword v34, v[34:35]
	v_cmp_lt_u32_e32 vcc, s37, v161
	v_or_b32_e32 v35, 0x80000000, v36
	s_nop 0
	v_cndmask_b32_e32 v51, 0, v0, vcc
	v_not_b32_e32 v0, v36
	v_cmp_gt_i32_e32 vcc, 0, v36
	s_nop 1
	v_cndmask_b32_e32 v0, v35, v0, vcc
	v_cmp_lt_u32_e32 vcc, s38, v161
	v_or_b32_e32 v35, 0x80000000, v39
	s_nop 0
	v_cndmask_b32_e32 v47, 0, v0, vcc
	v_not_b32_e32 v0, v39
	v_cmp_gt_i32_e32 vcc, 0, v39
	s_nop 1
	v_cndmask_b32_e32 v0, v35, v0, vcc
	v_cmp_lt_u32_e32 vcc, s39, v161
	v_or_b32_e32 v35, 0x80000000, v63
	s_nop 0
	v_cndmask_b32_e32 v46, 0, v0, vcc
	v_not_b32_e32 v0, v63
	v_cmp_gt_i32_e32 vcc, 0, v63
	s_nop 1
	v_cndmask_b32_e32 v0, v35, v0, vcc
	v_cmp_lt_u32_e32 vcc, s40, v161
	v_or_b32_e32 v35, 0x80000000, v60
	s_nop 0
	v_cndmask_b32_e32 v45, 0, v0, vcc
	v_not_b32_e32 v0, v60
	v_cmp_gt_i32_e32 vcc, 0, v60
	s_nop 1
	v_cndmask_b32_e32 v0, v35, v0, vcc
	v_cmp_lt_u32_e32 vcc, s41, v161
	v_or_b32_e32 v35, 0x80000000, v59
	s_nop 0
	v_cndmask_b32_e32 v44, 0, v0, vcc
	v_not_b32_e32 v0, v59
	v_cmp_gt_i32_e32 vcc, 0, v59
	s_nop 1
	v_cndmask_b32_e32 v0, v35, v0, vcc
	v_cmp_lt_u32_e32 vcc, s42, v161
	v_or_b32_e32 v35, 0x80000000, v57
	s_nop 0
	v_cndmask_b32_e32 v43, 0, v0, vcc
	v_not_b32_e32 v0, v57
	v_cmp_gt_i32_e32 vcc, 0, v57
	s_nop 1
	v_cndmask_b32_e32 v0, v35, v0, vcc
	v_cmp_lt_u32_e32 vcc, s43, v161
	s_waitcnt vmcnt(0) lgkmcnt(0)
	v_or_b32_e32 v35, 0x80000000, v54
	v_cndmask_b32_e32 v42, 0, v0, vcc
	v_not_b32_e32 v0, v54
	v_cmp_gt_i32_e32 vcc, 0, v54
	s_nop 1
	v_cndmask_b32_e32 v0, v35, v0, vcc
	v_cmp_lt_u32_e32 vcc, s44, v161
	v_or_b32_e32 v35, 0x80000000, v53
	s_nop 0
	v_cndmask_b32_e32 v41, 0, v0, vcc
	v_not_b32_e32 v0, v53
	v_cmp_gt_i32_e32 vcc, 0, v53
	v_or_b32_e32 v53, 0x80000000, v34
	s_nop 0
	v_cndmask_b32_e32 v0, v35, v0, vcc
	v_cmp_lt_u32_e32 vcc, s45, v161
	v_or_b32_e32 v35, 0x80000000, v61
	s_nop 0
	v_cndmask_b32_e32 v40, 0, v0, vcc
	v_not_b32_e32 v0, v61
	v_cmp_gt_i32_e32 vcc, 0, v61
	s_nop 1
	v_cndmask_b32_e32 v0, v35, v0, vcc
	v_cmp_lt_u32_e32 vcc, s46, v161
	v_or_b32_e32 v35, 0x80000000, v55
	s_nop 0
	v_cndmask_b32_e32 v39, 0, v0, vcc
	v_not_b32_e32 v0, v55
	v_cmp_gt_i32_e32 vcc, 0, v55
	s_nop 1
	v_cndmask_b32_e32 v0, v35, v0, vcc
	v_cmp_lt_u32_e32 vcc, s47, v161
	v_or_b32_e32 v35, 0x80000000, v190
	s_nop 0
	v_cndmask_b32_e32 v38, 0, v0, vcc
	v_not_b32_e32 v0, v190
	v_cmp_gt_i32_e32 vcc, 0, v190
	s_nop 1
	v_cndmask_b32_e32 v0, v35, v0, vcc
	v_cmp_lt_u32_e32 vcc, s48, v161
	v_or_b32_e32 v35, 0x80000000, v191
	s_nop 0
	v_cndmask_b32_e32 v37, 0, v0, vcc
	v_not_b32_e32 v0, v191
	v_cmp_gt_i32_e32 vcc, 0, v191
	s_nop 1
	v_cndmask_b32_e32 v0, v35, v0, vcc
	v_cmp_lt_u32_e32 vcc, s49, v161
	v_or_b32_e32 v35, 0x80000000, v192
	s_nop 0
	v_cndmask_b32_e32 v36, 0, v0, vcc
	v_not_b32_e32 v0, v192
	v_cmp_gt_i32_e32 vcc, 0, v192
	s_nop 1
	v_cndmask_b32_e32 v0, v35, v0, vcc
	v_cmp_lt_u32_e32 vcc, s50, v161
	s_nop 1
	v_cndmask_b32_e32 v35, 0, v0, vcc
	v_not_b32_e32 v0, v34
	v_cmp_gt_i32_e32 vcc, 0, v34
	v_mov_b32_e32 v34, 0
	s_nop 0
	v_cndmask_b32_e32 v0, v53, v0, vcc
	v_cmp_lt_u32_e32 vcc, s51, v161
	v_mov_b32_e32 v53, 31
	s_nop 0
	v_cndmask_b32_e32 v0, 0, v0, vcc
	v_readlane_b32 s100, v161, 0
	s_lshr_b32 s100, s100, 6
	s_add_u32 s100, s100, 1
; DI unsigned mbcnt64(unsigned long long m) { return __builtin_amdgcn_mbcnt_hi((unsigned)(m >> 32), __builtin_amdgcn_mbcnt_lo((unsigned)m, 0u)); }
; template <int NV>
; DI void topk_row(const float* row, int s, LAS int* lst, int lane) {
;     ...
;         const unsigned cand = T | (1u << bit); int c = 0;
; #pragma unroll
;         for (int j = 0; j < NV; ++j) asm volatile("v_cmp_le_u32 vcc, %2, %1\n\tv_addc_co_u32 %0, vcc, 0, %0, vcc" : "+v"(c) : "v"(key[j]), "s"(cand) : "vcc");
;         const int tot = wave_sum_i(c);
;         if (tot >= 256) T = cand;
;         if (tot == 256) break;
;     }
;     int bgt = 0;
; #pragma unroll
;     for (int j = 0; j < NV; ++j) { const bool sg = key[j] > T; const unsigned long long mg = __ballot(sg); if (sg) lst[bgt + (int)mbcnt64(mg)] = j * 64 + lane; bgt += __builtin_popcountll(mg); }
.LBB0_2871:
	v_lshlrev_b32_e64 v54, v53, 1
	v_mov_b32_e32 v55, 0
	v_or_b32_e32 v54, v54, v34
	v_cmp_le_u32 vcc, v54, v189
	v_addc_co_u32 v55, vcc, 0, v55, vcc
	s_nop 0
	v_cmp_le_u32 vcc, v54, v188
	v_addc_co_u32 v55, vcc, 0, v55, vcc
	s_nop 0
	v_cmp_le_u32 vcc, v54, v187
	v_addc_co_u32 v55, vcc, 0, v55, vcc
	s_nop 0
	v_cmp_le_u32 vcc, v54, v186
	v_addc_co_u32 v55, vcc, 0, v55, vcc
	s_nop 0
	v_cmp_le_u32 vcc, v54, v185
	v_addc_co_u32 v55, vcc, 0, v55, vcc
	s_nop 0
	v_cmp_le_u32 vcc, v54, v184
	v_addc_co_u32 v55, vcc, 0, v55, vcc
	s_nop 0
	v_cmp_le_u32 vcc, v54, v183
	v_addc_co_u32 v55, vcc, 0, v55, vcc
	s_nop 0
	v_cmp_le_u32 vcc, v54, v182
	v_addc_co_u32 v55, vcc, 0, v55, vcc
	s_nop 0
	s_cmp_le_u32 s100, 8
	s_cbranch_scc1 .Lp12_pe_2
	v_cmp_le_u32 vcc, v54, v179
	v_addc_co_u32 v55, vcc, 0, v55, vcc
	s_nop 0
	v_cmp_le_u32 vcc, v54, v175
	v_addc_co_u32 v55, vcc, 0, v55, vcc
	s_nop 0
	v_cmp_le_u32 vcc, v54, v172
	v_addc_co_u32 v55, vcc, 0, v55, vcc
	s_nop 0
	v_cmp_le_u32 vcc, v54, v170
	v_addc_co_u32 v55, vcc, 0, v55, vcc
	s_nop 0
	v_cmp_le_u32 vcc, v54, v167
	v_addc_co_u32 v55, vcc, 0, v55, vcc
	s_nop 0
	v_cmp_le_u32 vcc, v54, v169
	v_addc_co_u32 v55, vcc, 0, v55, vcc
	s_nop 0
	v_cmp_le_u32 vcc, v54, v174
	v_addc_co_u32 v55, vcc, 0, v55, vcc
	s_nop 0
	v_cmp_le_u32 vcc, v54, v178
	v_addc_co_u32 v55, vcc, 0, v55, vcc
	s_nop 0
	s_cmp_le_u32 s100, 16
	s_cbranch_scc1 .Lp12_pe_2
	v_cmp_le_u32 vcc, v54, v181
	v_addc_co_u32 v55, vcc, 0, v55, vcc
	s_nop 0
	v_cmp_le_u32 vcc, v54, v180
	v_addc_co_u32 v55, vcc, 0, v55, vcc
	s_nop 0
	v_cmp_le_u32 vcc, v54, v177
	v_addc_co_u32 v55, vcc, 0, v55, vcc
	s_nop 0
	v_cmp_le_u32 vcc, v54, v176
	v_addc_co_u32 v55, vcc, 0, v55, vcc
	s_nop 0
	v_cmp_le_u32 vcc, v54, v173
	v_addc_co_u32 v55, vcc, 0, v55, vcc
	s_nop 0
	v_cmp_le_u32 vcc, v54, v171
	v_addc_co_u32 v55, vcc, 0, v55, vcc
	s_nop 0
	v_cmp_le_u32 vcc, v54, v168
	v_addc_co_u32 v55, vcc, 0, v55, vcc
	s_nop 0
	v_cmp_le_u32 vcc, v54, v166
	v_addc_co_u32 v55, vcc, 0, v55, vcc
	s_nop 0
	s_cmp_le_u32 s100, 24
	s_cbranch_scc1 .Lp12_pe_2
	v_cmp_le_u32 vcc, v54, v165
	v_addc_co_u32 v55, vcc, 0, v55, vcc
	s_nop 0
	v_cmp_le_u32 vcc, v54, v164
	v_addc_co_u32 v55, vcc, 0, v55, vcc
	s_nop 0
	v_cmp_le_u32 vcc, v54, v163
	v_addc_co_u32 v55, vcc, 0, v55, vcc
	s_nop 0
	v_cmp_le_u32 vcc, v54, v162
	v_addc_co_u32 v55, vcc, 0, v55, vcc
	s_nop 0
	v_cmp_le_u32 vcc, v54, v141
	v_addc_co_u32 v55, vcc, 0, v55, vcc
	s_nop 0
	v_cmp_le_u32 vcc, v54, v140
	v_addc_co_u32 v55, vcc, 0, v55, vcc
	s_nop 0
	v_cmp_le_u32 vcc, v54, v139
	v_addc_co_u32 v55, vcc, 0, v55, vcc
	s_nop 0
	v_cmp_le_u32 vcc, v54, v138
	v_addc_co_u32 v55, vcc, 0, v55, vcc
	s_nop 0
	s_cmp_le_u32 s100, 32
	s_cbranch_scc1 .Lp12_pe_2
	v_cmp_le_u32 vcc, v54, v137
	v_addc_co_u32 v55, vcc, 0, v55, vcc
	s_nop 0
	v_cmp_le_u32 vcc, v54, v136
	v_addc_co_u32 v55, vcc, 0, v55, vcc
	s_nop 0
	v_cmp_le_u32 vcc, v54, v135
	v_addc_co_u32 v55, vcc, 0, v55, vcc
	s_nop 0
	v_cmp_le_u32 vcc, v54, v134
	v_addc_co_u32 v55, vcc, 0, v55, vcc
	s_nop 0
	v_cmp_le_u32 vcc, v54, v133
	v_addc_co_u32 v55, vcc, 0, v55, vcc
	s_nop 0
	v_cmp_le_u32 vcc, v54, v131
	v_addc_co_u32 v55, vcc, 0, v55, vcc
	s_nop 0
	v_cmp_le_u32 vcc, v54, v132
	v_addc_co_u32 v55, vcc, 0, v55, vcc
	s_nop 0
	v_cmp_le_u32 vcc, v54, v130
	v_addc_co_u32 v55, vcc, 0, v55, vcc
	s_nop 0
	s_cmp_le_u32 s100, 40
	s_cbranch_scc1 .Lp12_pe_2
	v_cmp_le_u32 vcc, v54, v128
	v_addc_co_u32 v55, vcc, 0, v55, vcc
	s_nop 0
	v_cmp_le_u32 vcc, v54, v129
	v_addc_co_u32 v55, vcc, 0, v55, vcc
	s_nop 0
	v_cmp_le_u32 vcc, v54, v62
	v_addc_co_u32 v55, vcc, 0, v55, vcc
	s_nop 0
	v_cmp_le_u32 vcc, v54, v58
	v_addc_co_u32 v55, vcc, 0, v55, vcc
	s_nop 0
	v_cmp_le_u32 vcc, v54, v56
	v_addc_co_u32 v55, vcc, 0, v55, vcc
	s_nop 0
	v_cmp_le_u32 vcc, v54, v52
	v_addc_co_u32 v55, vcc, 0, v55, vcc
	s_nop 0
	v_cmp_le_u32 vcc, v54, v50
	v_addc_co_u32 v55, vcc, 0, v55, vcc
	s_nop 0
	v_cmp_le_u32 vcc, v54, v49
	v_addc_co_u32 v55, vcc, 0, v55, vcc
	s_nop 0
	s_cmp_le_u32 s100, 48
	s_cbranch_scc1 .Lp12_pe_2
	v_cmp_le_u32 vcc, v54, v48
	v_addc_co_u32 v55, vcc, 0, v55, vcc
	s_nop 0
	v_cmp_le_u32 vcc, v54, v51
	v_addc_co_u32 v55, vcc, 0, v55, vcc
	s_nop 0
	v_cmp_le_u32 vcc, v54, v47
	v_addc_co_u32 v55, vcc, 0, v55, vcc
	s_nop 0
	v_cmp_le_u32 vcc, v54, v46
	v_addc_co_u32 v55, vcc, 0, v55, vcc
	s_nop 0
	v_cmp_le_u32 vcc, v54, v45
	v_addc_co_u32 v55, vcc, 0, v55, vcc
	s_nop 0
	v_cmp_le_u32 vcc, v54, v44
	v_addc_co_u32 v55, vcc, 0, v55, vcc
	s_nop 0
	v_cmp_le_u32 vcc, v54, v43
	v_addc_co_u32 v55, vcc, 0, v55, vcc
	s_nop 0
	v_cmp_le_u32 vcc, v54, v42
	v_addc_co_u32 v55, vcc, 0, v55, vcc
	s_nop 0
	s_cmp_le_u32 s100, 56
	s_cbranch_scc1 .Lp12_pe_2
	v_cmp_le_u32 vcc, v54, v41
	v_addc_co_u32 v55, vcc, 0, v55, vcc
	s_nop 0
	v_cmp_le_u32 vcc, v54, v40
	v_addc_co_u32 v55, vcc, 0, v55, vcc
	s_nop 0
	v_cmp_le_u32 vcc, v54, v39
	v_addc_co_u32 v55, vcc, 0, v55, vcc
	s_nop 0
	v_cmp_le_u32 vcc, v54, v38
	v_addc_co_u32 v55, vcc, 0, v55, vcc
	s_nop 0
	v_cmp_le_u32 vcc, v54, v37
	v_addc_co_u32 v55, vcc, 0, v55, vcc
	s_nop 0
	v_cmp_le_u32 vcc, v54, v36
	v_addc_co_u32 v55, vcc, 0, v55, vcc
	s_nop 0
	v_cmp_le_u32 vcc, v54, v35
	v_addc_co_u32 v55, vcc, 0, v55, vcc
	s_nop 0
	v_cmp_le_u32 vcc, v54, v0
	v_addc_co_u32 v55, vcc, 0, v55, vcc
.Lp12_pe_2:
	s_nop 1
	v_add_u32_dpp v55, v55, v55 quad_perm:[1,0,3,2] row_mask:0xf bank_mask:0xf bound_ctrl:1
	s_nop 1
	v_add_u32_dpp v55, v55, v55 quad_perm:[2,3,0,1] row_mask:0xf bank_mask:0xf bound_ctrl:1
	s_nop 1
	v_add_u32_dpp v55, v55, v55 row_half_mirror row_mask:0xf bank_mask:0xf bound_ctrl:1
	s_nop 1
	v_add_u32_dpp v55, v55, v55 row_mirror row_mask:0xf bank_mask:0xf bound_ctrl:1
	s_nop 0
	v_readlane_b32 s0, v55, 0
	v_readlane_b32 s1, v55, 16
	s_add_i32 s0, s1, s0
	v_readlane_b32 s1, v55, 32
	s_add_i32 s0, s0, s1
	v_readlane_b32 s1, v55, 48
	s_add_i32 s0, s0, s1
	s_cmpk_gt_i32 s0, 0xff
	s_cselect_b64 vcc, -1, 0
	s_cmpk_eq_i32 s0, 0x100
	v_cndmask_b32_e32 v34, v34, v54, vcc
	s_cselect_b64 s[0:1], -1, 0
	v_subrev_co_u32_e32 v53, vcc, 1, v53
	s_or_b64 s[0:1], s[0:1], vcc
	s_andn2_b64 vcc, exec, s[0:1]
	s_cbranch_vccnz .LBB0_2871
	v_cmp_gt_u32_e32 vcc, v189, v34
	s_and_saveexec_b64 s[0:1], vcc
	s_nop 0
	v_mbcnt_lo_u32_b32 v53, vcc_lo, 0
	v_mbcnt_hi_u32_b32 v53, vcc_hi, v53
	v_lshl_add_u32 v53, v53, 2, s20
	ds_write_b32 v53, v2
	s_or_b64 exec, exec, s[0:1]
	s_bcnt1_i32_b64 s2, vcc
	v_cmp_gt_u32_e32 vcc, v188, v34
	s_and_saveexec_b64 s[0:1], vcc
	s_cbranch_execz .LBB0_2876
	s_lshl_b32 s3, s2, 2
	v_mbcnt_lo_u32_b32 v53, vcc_lo, 0
	s_add_i32 s3, s20, s3
	v_mbcnt_hi_u32_b32 v53, vcc_hi, v53
	v_lshl_add_u32 v53, v53, 2, s3
	ds_write_b32 v53, v4

; DI unsigned f2key(float f) { const unsigned u = __float_as_uint(f); return (u & 0x80000000u) ? ~u : (u | 0x80000000u); }
; template <int NV>
; DI void topk_row(const float* row, int s, LAS int* lst, int lane) {
;     ...
;     for (int jo = 0; jo < NV / 16; ++jo) { const float* rb = row + jo * 1024;
; #pragma unroll
;         for (int ji = 0; ji < 16; ++ji) { const int j = jo * 16 + ji; const unsigned u = f2key(rb[ji * 64 + lane]); key[j] = (j * 64 + lane <= s) ? u : 0u; } }
.LBB0_3128:
	v_lshlrev_b32_e32 v0, 2, v2
	v_lshl_add_u64 v[34:35], s[12:13], 0, v[0:1]
	flat_load_dword v38, v[34:35]
	flat_load_dword v39, v[34:35] offset:256
	flat_load_dword v40, v[34:35] offset:512
	flat_load_dword v41, v[34:35] offset:768
	flat_load_dword v45, v[34:35] offset:1024
	flat_load_dword v46, v[34:35] offset:1280
	flat_load_dword v47, v[34:35] offset:1536
	flat_load_dword v52, v[34:35] offset:1792
	flat_load_dword v53, v[34:35] offset:2048
	flat_load_dword v54, v[34:35] offset:2304
	flat_load_dword v55, v[34:35] offset:2560
	flat_load_dword v56, v[34:35] offset:2816
	flat_load_dword v57, v[34:35] offset:3072
	s_add_u32 s0, s12, 0x1000
	s_addc_u32 s1, s13, 0
	flat_load_dword v58, v[34:35] offset:3328
	flat_load_dword v48, v[34:35] offset:3584
	flat_load_dword v51, v[34:35] offset:3840
	v_lshl_add_u64 v[34:35], s[0:1], 0, v[0:1]
	v_lshlrev_b32_e32 v0, 2, v4
	v_lshl_add_u64 v[36:37], s[0:1], 0, v[0:1]
	flat_load_dword v50, v[34:35]
	flat_load_dword v49, v[36:37]
	s_movk_i32 s2, 0xff
	s_waitcnt vmcnt(0) lgkmcnt(0)
	v_not_b32_e32 v0, v38
	v_or_b32_e32 v34, 0x80000000, v38
	v_cmp_gt_i32_e32 vcc, 0, v38
	v_not_b32_e32 v35, v39
	v_or_b32_e32 v36, 0x80000000, v39
	v_cndmask_b32_e32 v44, v34, v0, vcc
	v_cmp_gt_i32_e32 vcc, 0, v39
	v_not_b32_e32 v37, v40
	v_or_b32_e32 v42, 0x80000000, v40
	v_cndmask_b32_e32 v43, v36, v35, vcc
	v_cmp_gt_i32_e32 vcc, 0, v40
	v_not_b32_e32 v59, v41
	v_or_b32_e32 v60, 0x80000000, v41
	v_cndmask_b32_e32 v42, v42, v37, vcc
	v_cmp_gt_i32_e32 vcc, 0, v41
	v_not_b32_e32 v61, v45
	v_or_b32_e32 v62, 0x80000000, v45
	v_cndmask_b32_e32 v41, v60, v59, vcc
	v_cmp_gt_i32_e32 vcc, 0, v45
	v_not_b32_e32 v63, v46
	v_or_b32_e32 v128, 0x80000000, v46
	v_cndmask_b32_e32 v0, v62, v61, vcc
	v_cmp_gt_i32_e32 vcc, 0, v46
	v_not_b32_e32 v129, v47
	v_or_b32_e32 v130, 0x80000000, v47
	v_cndmask_b32_e32 v34, v128, v63, vcc
	v_cmp_gt_i32_e32 vcc, 0, v47
	v_not_b32_e32 v131, v52
	v_or_b32_e32 v132, 0x80000000, v52
	v_cndmask_b32_e32 v35, v130, v129, vcc
	v_cmp_gt_i32_e32 vcc, 0, v52
	v_not_b32_e32 v133, v53
	v_or_b32_e32 v134, 0x80000000, v53
	v_cndmask_b32_e32 v36, v132, v131, vcc
	v_cmp_gt_i32_e32 vcc, 0, v53
	v_not_b32_e32 v135, v54
	v_or_b32_e32 v136, 0x80000000, v54
	v_cndmask_b32_e32 v45, v134, v133, vcc
	v_cmp_gt_i32_e32 vcc, 0, v54
	v_not_b32_e32 v137, v55
	v_or_b32_e32 v138, 0x80000000, v55
	v_cndmask_b32_e32 v46, v136, v135, vcc
	v_cmp_gt_i32_e32 vcc, 0, v55
	v_not_b32_e32 v139, v56
	v_not_b32_e32 v54, v57
	v_cndmask_b32_e32 v47, v138, v137, vcc
	v_cmp_lt_u32_e32 vcc, s2, v161
	v_or_b32_e32 v55, 0x80000000, v57
	s_nop 0
	v_cndmask_b32_e32 v40, 0, v0, vcc
	v_cmp_lt_u32_e32 vcc, s52, v161
	v_lshlrev_b32_e32 v0, 2, v6
	s_nop 0
	v_cndmask_b32_e32 v39, 0, v34, vcc
	v_cmp_lt_u32_e32 vcc, s53, v161
	s_nop 1
	v_cndmask_b32_e32 v38, 0, v35, vcc
	v_cmp_lt_u32_e32 vcc, s54, v161
	s_nop 1
	v_cndmask_b32_e32 v37, 0, v36, vcc
	v_cmp_lt_u32_e32 vcc, s55, v161
	s_nop 1
	v_cndmask_b32_e32 v36, 0, v45, vcc
	v_cmp_lt_u32_e32 vcc, s56, v161
	v_or_b32_e32 v45, 0x80000000, v56
	s_nop 0
	v_cndmask_b32_e32 v35, 0, v46, vcc
	v_cmp_lt_u32_e32 vcc, s57, v161
	s_nop 1
	v_cndmask_b32_e32 v34, 0, v47, vcc
	v_lshl_add_u64 v[46:47], s[0:1], 0, v[0:1]
	flat_load_dword v52, v[46:47]
	v_lshlrev_b32_e32 v0, 2, v8
	v_lshl_add_u64 v[46:47], s[0:1], 0, v[0:1]
	flat_load_dword v53, v[46:47]
	v_lshlrev_b32_e32 v0, 2, v10
	v_cmp_gt_i32_e32 vcc, 0, v56
	v_lshl_add_u64 v[46:47], s[0:1], 0, v[0:1]
	flat_load_dword v56, v[46:47]
	v_cndmask_b32_e32 v45, v45, v139, vcc
	v_cmp_lt_u32_e32 vcc, s59, v161
	v_lshlrev_b32_e32 v0, 2, v12
	v_lshl_add_u64 v[46:47], s[0:1], 0, v[0:1]
	v_cndmask_b32_e32 v45, 0, v45, vcc
	v_cmp_gt_i32_e32 vcc, 0, v57
	flat_load_dword v59, v[46:47]
	v_lshlrev_b32_e32 v0, 2, v14
	v_cndmask_b32_e32 v54, v55, v54, vcc
	v_cmp_lt_u32_e32 vcc, s60, v161
	v_not_b32_e32 v47, v58
	v_or_b32_e32 v57, 0x80000000, v58
	v_cndmask_b32_e32 v46, 0, v54, vcc
	v_lshl_add_u64 v[54:55], s[0:1], 0, v[0:1]
	flat_load_dword v128, v[54:55]
	v_lshlrev_b32_e32 v0, 2, v16
	v_lshl_add_u64 v[54:55], s[0:1], 0, v[0:1]
	flat_load_dword v129, v[54:55]
	v_lshlrev_b32_e32 v0, 2, v18
	v_lshl_add_u64 v[54:55], s[0:1], 0, v[0:1]
	flat_load_dword v130, v[54:55]
	v_lshlrev_b32_e32 v0, 2, v20
	v_lshl_add_u64 v[54:55], s[0:1], 0, v[0:1]
	flat_load_dword v131, v[54:55]
	v_lshlrev_b32_e32 v0, 2, v22
	v_lshl_add_u64 v[54:55], s[0:1], 0, v[0:1]
	flat_load_dword v132, v[54:55]
	v_lshlrev_b32_e32 v0, 2, v24
	v_lshl_add_u64 v[54:55], s[0:1], 0, v[0:1]
	flat_load_dword v133, v[54:55]
	v_lshlrev_b32_e32 v0, 2, v26
	v_lshl_add_u64 v[54:55], s[0:1], 0, v[0:1]
	flat_load_dword v134, v[54:55]
	v_lshlrev_b32_e32 v0, 2, v28
	v_lshl_add_u64 v[54:55], s[0:1], 0, v[0:1]
	flat_load_dword v135, v[54:55]
	v_lshlrev_b32_e32 v0, 2, v30
	v_lshl_add_u64 v[54:55], s[0:1], 0, v[0:1]
	flat_load_dword v136, v[54:55]
	v_lshlrev_b32_e32 v0, 2, v32
	v_lshl_add_u64 v[54:55], s[0:1], 0, v[0:1]
	flat_load_dword v137, v[54:55]
	v_cmp_gt_i32_e32 vcc, 0, v58
	v_or_b32_e32 v58, 0x80000000, v48
	s_waitcnt vmcnt(0) lgkmcnt(0)
; DI unsigned f2key(float f) { const unsigned u = __float_as_uint(f); return (u & 0x80000000u) ? ~u : (u | 0x80000000u); }
; template <int NV>
; DI void topk_row(const float* row, int s, LAS int* lst, int lane) {
;     ...
;     for (int jo = 0; jo < NV / 16; ++jo) { const float* rb = row + jo * 1024;
; #pragma unroll
;         for (int ji = 0; ji < 16; ++ji) { const int j = jo * 16 + ji; const unsigned u = f2key(rb[ji * 64 + lane]); key[j] = (j * 64 + lane <= s) ? u : 0u; } }
;     unsigned T = 0u;
; #pragma unroll 1
	v_not_b32_e32 v0, v52
	v_cndmask_b32_e32 v47, v57, v47, vcc
	v_cmp_lt_u32_e32 vcc, s61, v161
	v_not_b32_e32 v57, v48
	s_nop 0
	v_cndmask_b32_e32 v47, 0, v47, vcc
	v_cmp_gt_i32_e32 vcc, 0, v48
	s_nop 1
	v_cndmask_b32_e32 v48, v58, v57, vcc
	v_cmp_lt_u32_e32 vcc, s62, v161
	v_not_b32_e32 v57, v51
	v_or_b32_e32 v58, 0x80000000, v51
	v_cndmask_b32_e32 v48, 0, v48, vcc
	v_cmp_gt_i32_e32 vcc, 0, v51
	s_nop 1
	v_cndmask_b32_e32 v51, v58, v57, vcc
	v_cmp_lt_u32_e32 vcc, s63, v161
	v_not_b32_e32 v57, v50
	v_or_b32_e32 v58, 0x80000000, v50
	v_cndmask_b32_e32 v51, 0, v51, vcc
	v_cmp_gt_i32_e32 vcc, 0, v50
	s_nop 1
	v_cndmask_b32_e32 v50, v58, v57, vcc
	v_cmp_lt_u32_e32 vcc, s64, v161
	v_or_b32_e32 v58, 0x80000000, v49
	s_nop 0
	v_cndmask_b32_e32 v57, 0, v50, vcc
	v_not_b32_e32 v50, v49
	v_cmp_gt_i32_e32 vcc, 0, v49
	s_nop 1
	v_cndmask_b32_e32 v49, v58, v50, vcc
	v_cmp_lt_u32_e32 vcc, s65, v161
	s_nop 1
	v_cndmask_b32_e32 v63, 0, v49, vcc
	v_or_b32_e32 v49, 0x80000000, v52
	v_cmp_gt_i32_e32 vcc, 0, v52
	s_nop 1
	v_cndmask_b32_e32 v0, v49, v0, vcc
	v_cmp_lt_u32_e32 vcc, s66, v161
	v_or_b32_e32 v49, 0x80000000, v53
	s_nop 0
	v_cndmask_b32_e32 v62, 0, v0, vcc
	v_not_b32_e32 v0, v53
	v_cmp_gt_i32_e32 vcc, 0, v53
	s_nop 1
	v_cndmask_b32_e32 v0, v49, v0, vcc
	v_cmp_lt_u32_e32 vcc, s67, v161
	v_or_b32_e32 v49, 0x80000000, v56
	s_nop 0
	v_cndmask_b32_e32 v61, 0, v0, vcc
	v_not_b32_e32 v0, v56
	v_cmp_gt_i32_e32 vcc, 0, v56
	s_nop 1
	v_cndmask_b32_e32 v0, v49, v0, vcc
	v_cmp_lt_u32_e32 vcc, s68, v161
	v_or_b32_e32 v49, 0x80000000, v59
	s_nop 0
	v_cndmask_b32_e32 v60, 0, v0, vcc
	v_not_b32_e32 v0, v59
	v_cmp_gt_i32_e32 vcc, 0, v59
	s_nop 1
	v_cndmask_b32_e32 v0, v49, v0, vcc
	v_cmp_lt_u32_e32 vcc, s69, v161
	v_or_b32_e32 v49, 0x80000000, v128
	s_nop 0
	v_cndmask_b32_e32 v59, 0, v0, vcc
	v_not_b32_e32 v0, v128
	v_cmp_gt_i32_e32 vcc, 0, v128
	v_or_b32_e32 v128, 0x80000000, v136
	s_nop 0
	v_cndmask_b32_e32 v0, v49, v0, vcc
	v_cmp_lt_u32_e32 vcc, s70, v161
	v_or_b32_e32 v49, 0x80000000, v129
	s_nop 0
	v_cndmask_b32_e32 v58, 0, v0, vcc
	v_not_b32_e32 v0, v129
	v_cmp_gt_i32_e32 vcc, 0, v129
	v_or_b32_e32 v129, 0x80000000, v137
	s_nop 0
	v_cndmask_b32_e32 v0, v49, v0, vcc
	v_cmp_lt_u32_e32 vcc, s71, v161
	v_or_b32_e32 v49, 0x80000000, v130
	s_nop 0
	v_cndmask_b32_e32 v56, 0, v0, vcc
	v_not_b32_e32 v0, v130
	v_cmp_gt_i32_e32 vcc, 0, v130
	v_mov_b32_e32 v130, 31
	s_nop 0
	v_cndmask_b32_e32 v0, v49, v0, vcc
	v_cmp_lt_u32_e32 vcc, s72, v161
	v_or_b32_e32 v49, 0x80000000, v131
	s_nop 0
	v_cndmask_b32_e32 v55, 0, v0, vcc
	v_not_b32_e32 v0, v131
	v_cmp_gt_i32_e32 vcc, 0, v131
	s_nop 1
	v_cndmask_b32_e32 v0, v49, v0, vcc
	v_cmp_lt_u32_e32 vcc, s73, v161
	v_or_b32_e32 v49, 0x80000000, v132
	s_nop 0
	v_cndmask_b32_e32 v54, 0, v0, vcc
	v_not_b32_e32 v0, v132
	v_cmp_gt_i32_e32 vcc, 0, v132
	s_nop 1
	v_cndmask_b32_e32 v0, v49, v0, vcc
	v_cmp_lt_u32_e32 vcc, s74, v161
	v_or_b32_e32 v49, 0x80000000, v133
	s_nop 0
	v_cndmask_b32_e32 v53, 0, v0, vcc
	v_not_b32_e32 v0, v133
	v_cmp_gt_i32_e32 vcc, 0, v133
	s_nop 1
	v_cndmask_b32_e32 v0, v49, v0, vcc
	v_cmp_lt_u32_e32 vcc, s75, v161
	v_or_b32_e32 v49, 0x80000000, v134
	s_nop 0
	v_cndmask_b32_e32 v52, 0, v0, vcc
	v_not_b32_e32 v0, v134
	v_cmp_gt_i32_e32 vcc, 0, v134
	s_nop 1
	v_cndmask_b32_e32 v0, v49, v0, vcc
	v_cmp_lt_u32_e32 vcc, s76, v161
	v_or_b32_e32 v49, 0x80000000, v135
	s_nop 0
	v_cndmask_b32_e32 v50, 0, v0, vcc
	v_not_b32_e32 v0, v135
	v_cmp_gt_i32_e32 vcc, 0, v135
	s_nop 1
	v_cndmask_b32_e32 v0, v49, v0, vcc
	v_cmp_lt_u32_e32 vcc, s77, v161
	s_nop 1
	v_cndmask_b32_e32 v49, 0, v0, vcc
	v_not_b32_e32 v0, v136
	v_cmp_gt_i32_e32 vcc, 0, v136
	s_nop 1
	v_cndmask_b32_e32 v0, v128, v0, vcc
	v_cmp_lt_u32_e32 vcc, s78, v161
	v_not_b32_e32 v128, v137
	s_nop 0
	v_cndmask_b32_e32 v0, 0, v0, vcc
	v_cmp_gt_i32_e32 vcc, 0, v137
	s_nop 1
	v_cndmask_b32_e32 v128, v129, v128, vcc
	v_cmp_lt_u32_e32 vcc, s79, v161
	v_mov_b32_e32 v129, 0
	s_nop 0
	v_cndmask_b32_e32 v128, 0, v128, vcc
	v_readlane_b32 s100, v161, 0
	s_lshr_b32 s100, s100, 6
	s_add_u32 s100, s100, 1
; DI unsigned mbcnt64(unsigned long long m) { return __builtin_amdgcn_mbcnt_hi((unsigned)(m >> 32), __builtin_amdgcn_mbcnt_lo((unsigned)m, 0u)); }
; template <int NV>
; DI void topk_row(const float* row, int s, LAS int* lst, int lane) {
;     ...
;         const unsigned cand = T | (1u << bit); int c = 0;
; #pragma unroll
;         for (int j = 0; j < NV; ++j) asm volatile("v_cmp_le_u32 vcc, %2, %1\n\tv_addc_co_u32 %0, vcc, 0, %0, vcc" : "+v"(c) : "v"(key[j]), "s"(cand) : "vcc");
;         const int tot = wave_sum_i(c);
;         if (tot >= 256) T = cand;
;         if (tot == 256) break;
;     }
;     int bgt = 0;
; #pragma unroll
;     for (int j = 0; j < NV; ++j) { const bool sg = key[j] > T; const unsigned long long mg = __ballot(sg); if (sg) lst[bgt + (int)mbcnt64(mg)] = j * 64 + lane; bgt += __builtin_popcountll(mg); }
.LBB0_3129:
	v_lshlrev_b32_e64 v131, v130, 1
	v_mov_b32_e32 v132, 0
	v_or_b32_e32 v131, v131, v129
	v_cmp_le_u32 vcc, v131, v44
	v_addc_co_u32 v132, vcc, 0, v132, vcc
	s_nop 0
	v_cmp_le_u32 vcc, v131, v43
	v_addc_co_u32 v132, vcc, 0, v132, vcc
	s_nop 0
	v_cmp_le_u32 vcc, v131, v42
	v_addc_co_u32 v132, vcc, 0, v132, vcc
	s_nop 0
	v_cmp_le_u32 vcc, v131, v41
	v_addc_co_u32 v132, vcc, 0, v132, vcc
	s_nop 0
	v_cmp_le_u32 vcc, v131, v40
	v_addc_co_u32 v132, vcc, 0, v132, vcc
	s_nop 0
	v_cmp_le_u32 vcc, v131, v39
	v_addc_co_u32 v132, vcc, 0, v132, vcc
	s_nop 0
	v_cmp_le_u32 vcc, v131, v38
	v_addc_co_u32 v132, vcc, 0, v132, vcc
	s_nop 0
	v_cmp_le_u32 vcc, v131, v37
	v_addc_co_u32 v132, vcc, 0, v132, vcc
	s_nop 0
	s_cmp_le_u32 s100, 8
	s_cbranch_scc1 .Lp12_pe_3
	v_cmp_le_u32 vcc, v131, v36
	v_addc_co_u32 v132, vcc, 0, v132, vcc
	s_nop 0
	v_cmp_le_u32 vcc, v131, v35
	v_addc_co_u32 v132, vcc, 0, v132, vcc
	s_nop 0
	v_cmp_le_u32 vcc, v131, v34
	v_addc_co_u32 v132, vcc, 0, v132, vcc
	s_nop 0
	v_cmp_le_u32 vcc, v131, v45
	v_addc_co_u32 v132, vcc, 0, v132, vcc
	s_nop 0
	v_cmp_le_u32 vcc, v131, v46
	v_addc_co_u32 v132, vcc, 0, v132, vcc
	s_nop 0
	v_cmp_le_u32 vcc, v131, v47
	v_addc_co_u32 v132, vcc, 0, v132, vcc
	s_nop 0
	v_cmp_le_u32 vcc, v131, v48
	v_addc_co_u32 v132, vcc, 0, v132, vcc
	s_nop 0
	v_cmp_le_u32 vcc, v131, v51
	v_addc_co_u32 v132, vcc, 0, v132, vcc
	s_nop 0
	s_cmp_le_u32 s100, 16
	s_cbranch_scc1 .Lp12_pe_3
	v_cmp_le_u32 vcc, v131, v57
	v_addc_co_u32 v132, vcc, 0, v132, vcc
	s_nop 0
	v_cmp_le_u32 vcc, v131, v63
	v_addc_co_u32 v132, vcc, 0, v132, vcc
	s_nop 0
	v_cmp_le_u32 vcc, v131, v62
	v_addc_co_u32 v132, vcc, 0, v132, vcc
	s_nop 0
	v_cmp_le_u32 vcc, v131, v61
	v_addc_co_u32 v132, vcc, 0, v132, vcc
	s_nop 0
	v_cmp_le_u32 vcc, v131, v60
	v_addc_co_u32 v132, vcc, 0, v132, vcc
	s_nop 0
	v_cmp_le_u32 vcc, v131, v59
	v_addc_co_u32 v132, vcc, 0, v132, vcc
	s_nop 0
	v_cmp_le_u32 vcc, v131, v58
	v_addc_co_u32 v132, vcc, 0, v132, vcc
	s_nop 0
	v_cmp_le_u32 vcc, v131, v56
	v_addc_co_u32 v132, vcc, 0, v132, vcc
	s_nop 0
	s_cmp_le_u32 s100, 24
	s_cbranch_scc1 .Lp12_pe_3
	v_cmp_le_u32 vcc, v131, v55
	v_addc_co_u32 v132, vcc, 0, v132, vcc
	s_nop 0
	v_cmp_le_u32 vcc, v131, v54
	v_addc_co_u32 v132, vcc, 0, v132, vcc
	s_nop 0
	v_cmp_le_u32 vcc, v131, v53
	v_addc_co_u32 v132, vcc, 0, v132, vcc
	s_nop 0
	v_cmp_le_u32 vcc, v131, v52
	v_addc_co_u32 v132, vcc, 0, v132, vcc
	s_nop 0
	v_cmp_le_u32 vcc, v131, v50
	v_addc_co_u32 v132, vcc, 0, v132, vcc
	s_nop 0
	v_cmp_le_u32 vcc, v131, v49
	v_addc_co_u32 v132, vcc, 0, v132, vcc
	s_nop 0
	v_cmp_le_u32 vcc, v131, v0
	v_addc_co_u32 v132, vcc, 0, v132, vcc
	s_nop 0
	v_cmp_le_u32 vcc, v131, v128
	v_addc_co_u32 v132, vcc, 0, v132, vcc
.Lp12_pe_3:
	s_nop 1
	v_add_u32_dpp v132, v132, v132 quad_perm:[1,0,3,2] row_mask:0xf bank_mask:0xf bound_ctrl:1
	s_nop 1
	v_add_u32_dpp v132, v132, v132 quad_perm:[2,3,0,1] row_mask:0xf bank_mask:0xf bound_ctrl:1
	s_nop 1
	v_add_u32_dpp v132, v132, v132 row_half_mirror row_mask:0xf bank_mask:0xf bound_ctrl:1
	s_nop 1
	v_add_u32_dpp v132, v132, v132 row_mirror row_mask:0xf bank_mask:0xf bound_ctrl:1
	s_nop 0
	v_readlane_b32 s0, v132, 0
	v_readlane_b32 s1, v132, 16
	s_add_i32 s0, s1, s0
	v_readlane_b32 s1, v132, 32
	s_add_i32 s0, s0, s1
	v_readlane_b32 s1, v132, 48
	s_add_i32 s0, s0, s1
	s_cmpk_gt_i32 s0, 0xff
	s_cselect_b64 vcc, -1, 0
	s_cmpk_eq_i32 s0, 0x100
	v_cndmask_b32_e32 v129, v129, v131, vcc
	s_cselect_b64 s[0:1], -1, 0
	v_subrev_co_u32_e32 v130, vcc, 1, v130
	s_or_b64 s[0:1], s[0:1], vcc
	s_andn2_b64 vcc, exec, s[0:1]
	s_cbranch_vccnz .LBB0_3129
	v_cmp_gt_u32_e32 vcc, v44, v129
	s_and_saveexec_b64 s[0:1], vcc
	s_nop 0
	v_mbcnt_lo_u32_b32 v130, vcc_lo, 0
	v_mbcnt_hi_u32_b32 v130, vcc_hi, v130
	v_lshl_add_u32 v130, v130, 2, s20
	ds_write_b32 v130, v2
	s_or_b64 exec, exec, s[0:1]
	s_bcnt1_i32_b64 s2, vcc
	v_cmp_gt_u32_e32 vcc, v43, v129
	s_and_saveexec_b64 s[0:1], vcc
	s_cbranch_execz .LBB0_3134
	s_lshl_b32 s3, s2, 2
	v_mbcnt_lo_u32_b32 v130, vcc_lo, 0
	s_add_i32 s3, s20, s3
	v_mbcnt_hi_u32_b32 v130, vcc_hi, v130
	v_lshl_add_u32 v130, v130, 2, s3
	ds_write_b32 v130, v4
